# cache policy: streamed-once epilogue/hook operand loads (P3 gates, P4 residual x, fused P6 x1) marked nt so GEMM operand tiles stay in L2
# baseline (speedup 1.0000x reference)
; __device__ __forceinline__ size_t tm_block(int pm, int ct, int nct) { return ((size_t)pm * nct + ct) * 32768; }
; #define UNPK0(q_) ((f32x4){bf_lo((q_).x), bf_hi((q_).x), bf_lo((q_).y), bf_hi((q_).y)})
; #define UNPK1(q_) ((f32x4){bf_lo((q_).z), bf_hi((q_).z), bf_lo((q_).w), bf_hi((q_).w)})
;     static __device__ __forceinline__ float eneg(float g) { return __builtin_amdgcn_exp2f(-1.4426950408889634f * fminf(fmaxf(g, -30.f), 30.f)); }
;     __device__ __forceinline__ void mid(f32x4 (&acc)[2][2][4][2], const Unit& u, int wr, int wc, int fr, int fq) const {
;     ...
;         const PieceIn pa(scr, Z, tm_block(pm, ga_ct + cb, znct), wr, wc, fr, fq), pb(scr, Z, tm_block(pm, gb_ct + cb, znct), wr, wc, fr, fq);
;         const int col0 = cb * 64 + 8 * fq;
;         f32x4 ba[2][2], bb[2][2];
; #pragma unroll
;         for (int bj = 0; bj < 2; ++bj) { ba[bj][0] = *(const f32x4*)(bg + col0 + bj * 32); ba[bj][1] = *(const f32x4*)(bg + col0 + bj * 32 + 4); bb[bj][0] = *(const f32x4*)(bg + 1024 + col0 + bj * 32); bb[bj][1] = *(const f32x4*)(bg + 1024 + col0 + bj * 32 + 4); }
; #pragma unroll
;         for (int am = 0; am < 4; ++am) { const int ai = am >> 1;
;             u32x4 ra[4][2], rb[4][2];
; #pragma unroll
;             for (int m = 2 * (am & 1); m < 2 * (am & 1) + 2; ++m) { pa.fetch(ai, m, ra[m][0], ra[m][1]); pb.fetch(ai, m, rb[m][0], rb[m][1]); }
;             asm volatile("" ::: "memory");
; #pragma unroll
;             for (int m = 2 * (am & 1); m < 2 * (am & 1) + 2; ++m) {
;                 pa.stage(ra[m][0], ra[m][1]); const u32x4 ga0 = pa.get(0), ga1 = pa.get(1);
;                 asm volatile("" ::: "memory");
;                 pb.stage(rb[m][0], rb[m][1]); const u32x4 gb0 = pb.get(0), gb1 = pb.get(1);
;                 asm volatile("" ::: "memory");
; #pragma unroll
;                 for (int bj = 0; bj < 2; ++bj) { const u32x4 ga = bj ? ga1 : ga0, gb = bj ? gb1 : gb0;
;                     const f32x4 a0 = UNPK0(ga) + ba[bj][0], a1 = UNPK1(ga) + ba[bj][1], b0 = UNPK0(gb) + bb[bj][0], b1 = UNPK1(gb) + bb[bj][1];
; #pragma unroll
;                     for (int k = 0; k < 4; ++k) { acc[ai][bj][m][0][k] *= (1.0f + eneg(b0[k])) * __builtin_amdgcn_rcpf(1.0f + eneg(a0[k]));
.LBB0_381:
	s_cmp_lg_u32 s46, 0x40000
	s_cbranch_scc1 .LBB0_380
	v_mov_b32_e32 v3, s26
	v_mov_b32_e32 v136, s44
	v_add_u32_e32 v188, v223, v220
	v_add_u32_e32 v4, 36, v136
	v_ashrrev_i32_e32 v5, 31, v4
	v_mad_i64_i32 v[4:5], s[48:49], v3, s83, v[4:5]
	v_add_u32_e32 v134, 52, v136
	v_ashrrev_i32_e32 v135, 31, v134
	v_lshlrev_b64 v[4:5], 15, v[4:5]
	v_lshl_add_u64 v[186:187], v[208:209], 0, v[4:5]
	v_mad_i64_i32 v[4:5], s[48:49], v3, s83, v[134:135]
	global_load_dwordx4 v[190:193], v[186:187], off nt
	global_load_dwordx4 v[194:197], v[186:187], off offset:1024 nt
	v_lshlrev_b64 v[4:5], 15, v[4:5]
	v_lshl_add_u64 v[4:5], v[208:209], 0, v[4:5]
	global_load_dwordx4 v[228:231], v[4:5], off nt
	global_load_dwordx4 v[232:235], v[4:5], off offset:1024 nt
	v_lshl_or_b32 v134, v136, 6, v219
	v_ashrrev_i32_e32 v135, 31, v134
	v_lshlrev_b64 v[134:135], 2, v[134:135]
	v_lshl_add_u64 v[138:139], s[42:43], 0, v[134:135]
	v_add_co_u32_e32 v166, vcc, s84, v138
	v_lshl_add_u64 v[140:141], s[16:17], 0, v[134:135]
	global_load_dwordx4 v[150:153], v[138:139], off offset:16
	global_load_dwordx4 v[158:161], v[138:139], off
	global_load_dwordx4 v[162:165], v[140:141], off
	v_addc_co_u32_e32 v167, vcc, 0, v139, vcc
	global_load_dwordx4 v[154:157], v[166:167], off offset:16
	global_load_dwordx4 v[134:137], v[138:139], off offset:144
	global_load_dwordx4 v[142:145], v[138:139], off offset:128
	global_load_dwordx4 v[146:149], v[140:141], off offset:128
	s_nop 0
	global_load_dwordx4 v[138:141], v[166:167], off offset:144
	global_load_dwordx4 v[174:177], v[186:187], off offset:2048 nt
	global_load_dwordx4 v[178:181], v[186:187], off offset:3072 nt
	s_nop 0
	global_load_dwordx4 v[166:169], v[4:5], off offset:2048 nt
	global_load_dwordx4 v[170:173], v[4:5], off offset:3072 nt
	v_add_u32_e32 v3, v224, v222
	s_waitcnt vmcnt(0)
	v_mul_f32_e32 v134, 0xbfb8aa3b, v134
	v_mul_f32_e32 v135, 0xbfb8aa3b, v135
	v_mul_f32_e32 v136, 0xbfb8aa3b, v136
	v_mul_f32_e32 v137, 0xbfb8aa3b, v137
	v_mul_f32_e32 v138, 0xbfb8aa3b, v138
	v_mul_f32_e32 v139, 0xbfb8aa3b, v139
	v_mul_f32_e32 v140, 0xbfb8aa3b, v140
	v_mul_f32_e32 v141, 0xbfb8aa3b, v141
	v_mul_f32_e32 v142, 0xbfb8aa3b, v142
	v_mul_f32_e32 v143, 0xbfb8aa3b, v143
	v_mul_f32_e32 v144, 0xbfb8aa3b, v144
	v_mul_f32_e32 v145, 0xbfb8aa3b, v145
	v_mul_f32_e32 v146, 0xbfb8aa3b, v146
	v_mul_f32_e32 v147, 0xbfb8aa3b, v147
	v_mul_f32_e32 v148, 0xbfb8aa3b, v148
	v_mul_f32_e32 v149, 0xbfb8aa3b, v149
	v_mul_f32_e32 v150, 0xbfb8aa3b, v150
	v_mul_f32_e32 v151, 0xbfb8aa3b, v151
	v_mul_f32_e32 v152, 0xbfb8aa3b, v152
	v_mul_f32_e32 v153, 0xbfb8aa3b, v153
	v_mul_f32_e32 v154, 0xbfb8aa3b, v154
	v_mul_f32_e32 v155, 0xbfb8aa3b, v155
	v_mul_f32_e32 v156, 0xbfb8aa3b, v156
	v_mul_f32_e32 v157, 0xbfb8aa3b, v157
	v_mul_f32_e32 v158, 0xbfb8aa3b, v158
	v_mul_f32_e32 v159, 0xbfb8aa3b, v159
	v_mul_f32_e32 v160, 0xbfb8aa3b, v160
	v_mul_f32_e32 v161, 0xbfb8aa3b, v161
	v_mul_f32_e32 v162, 0xbfb8aa3b, v162
	v_mul_f32_e32 v163, 0xbfb8aa3b, v163
	v_mul_f32_e32 v164, 0xbfb8aa3b, v164
	v_mul_f32_e32 v165, 0xbfb8aa3b, v165
	v_lshlrev_b32_e32 v189, 16, v190
	v_and_b32_e32 v190, 0xffff0000, v190
	v_lshlrev_b32_e32 v227, 16, v191
	v_and_b32_e32 v237, 0xffff0000, v191
	v_lshlrev_b32_e32 v191, 16, v192
	v_fma_f32 v189, v189, s89, v158
	v_and_b32_e32 v192, 0xffff0000, v192
	v_lshlrev_b32_e32 v239, 16, v193
	v_and_b32_e32 v241, 0xffff0000, v193
	v_lshlrev_b32_e32 v193, 16, v228
	v_and_b32_e32 v228, 0xffff0000, v228
	v_lshlrev_b32_e32 v236, 16, v229
	v_and_b32_e32 v242, 0xffff0000, v229
	v_lshlrev_b32_e32 v229, 16, v230
	v_fma_f32 v191, v191, s89, v150
	v_fma_f32 v190, v190, s89, v159
	v_fma_f32 v192, v192, s89, v151
	v_fma_f32 v193, v193, s89, v162
	v_fma_f32 v229, v229, s89, v154
	v_fma_f32 v228, v228, s89, v163
	v_med3_f32 v189, v189, s85, v226
	v_med3_f32 v191, v191, s85, v226
	v_med3_f32 v190, v190, s85, v226
	v_exp_f32_e32 v189, v189
	v_med3_f32 v238, v192, s85, v226
	v_med3_f32 v192, v193, s85, v226
	v_med3_f32 v193, v229, s85, v226
	v_exp_f32_e32 v229, v191
	v_med3_f32 v191, v228, s85, v226
	v_exp_f32_e32 v228, v190
	v_add_f32_e32 v189, 1.0, v189
	v_exp_f32_e32 v190, v192
	v_exp_f32_e32 v192, v193
	v_add_f32_e32 v193, 1.0, v229
	v_add_f32_e32 v229, 1.0, v228
	v_rcp_f32_e32 v228, v189
	v_exp_f32_e32 v189, v238
	v_fma_f32 v227, v227, s89, v160
	v_and_b32_e32 v230, 0xffff0000, v230
	v_med3_f32 v227, v227, s85, v226
	v_lshlrev_b32_e32 v240, 16, v231
	v_and_b32_e32 v243, 0xffff0000, v231
	v_fma_f32 v231, v230, s89, v155
	v_add_f32_e32 v189, 1.0, v189
	v_exp_f32_e32 v227, v227
	v_rcp_f32_e32 v230, v193
	v_med3_f32 v193, v231, s85, v226
	v_rcp_f32_e32 v231, v189
	v_fma_f32 v189, v236, s89, v164
	v_med3_f32 v189, v189, s85, v226
	v_exp_f32_e32 v236, v189
	v_add_f32_e32 v189, 1.0, v227
	v_fma_f32 v227, v239, s89, v152
	v_med3_f32 v227, v227, s85, v226
	v_exp_f32_e32 v227, v227
	v_rcp_f32_e32 v238, v189
	v_fma_f32 v189, v240, s89, v156
	v_med3_f32 v189, v189, s85, v226
	v_fma_f32 v237, v237, s89, v161
	v_exp_f32_e32 v240, v189
	v_add_f32_e32 v189, 1.0, v227
	v_fma_f32 v227, v242, s89, v165
	v_med3_f32 v237, v237, s85, v226
	v_exp_f32_e32 v239, v237
	v_med3_f32 v227, v227, s85, v226
	v_exp_f32_e32 v237, v227
	v_fma_f32 v227, v241, s89, v153
	v_med3_f32 v227, v227, s85, v226
	v_rcp_f32_e32 v242, v189
	v_add_f32_e32 v189, 1.0, v239
	v_exp_f32_e32 v227, v227
	v_rcp_f32_e32 v239, v189
	v_fma_f32 v189, v243, s89, v157
	v_exp_f32_e32 v193, v193
	v_med3_f32 v189, v189, s85, v226
	v_exp_f32_e32 v241, v189
	v_add_f32_e32 v189, 1.0, v227
	v_exp_f32_e32 v191, v191
	v_rcp_f32_e32 v243, v189
	v_lshlrev_b32_e32 v189, 16, v194
	v_rcp_f32_e32 v229, v229
	v_fma_f32 v189, v189, s89, v142
; #define UNPK0(q_) ((f32x4){bf_lo((q_).x), bf_hi((q_).x), bf_lo((q_).y), bf_hi((q_).y)})
; #define UNPK1(q_) ((f32x4){bf_lo((q_).z), bf_hi((q_).z), bf_lo((q_).w), bf_hi((q_).w)})
;     static __device__ __forceinline__ float eneg(float g) { return __builtin_amdgcn_exp2f(-1.4426950408889634f * fminf(fmaxf(g, -30.f), 30.f)); }
;     __device__ __forceinline__ void mid(f32x4 (&acc)[2][2][4][2], const Unit& u, int wr, int wc, int fr, int fq) const {
;     ...
;                 for (int bj = 0; bj < 2; ++bj) { const u32x4 ga = bj ? ga1 : ga0, gb = bj ? gb1 : gb0;
;                     const f32x4 a0 = UNPK0(ga) + ba[bj][0], a1 = UNPK1(ga) + ba[bj][1], b0 = UNPK0(gb) + bb[bj][0], b1 = UNPK1(gb) + bb[bj][1];
; #pragma unroll
;                     for (int k = 0; k < 4; ++k) { acc[ai][bj][m][0][k] *= (1.0f + eneg(b0[k])) * __builtin_amdgcn_rcpf(1.0f + eneg(a0[k]));
;                                                   acc[ai][bj][m][1][k] *= (1.0f + eneg(b1[k])) * __builtin_amdgcn_rcpf(1.0f + eneg(a1[k])); } } }
	v_pk_add_f32 v[192:193], v[192:193], 1.0 op_sel_hi:[1,0]
	v_pk_mul_f32 v[192:193], v[230:231], v[192:193]
	v_med3_f32 v189, v189, s85, v226
	v_pk_add_f32 v[190:191], v[190:191], 1.0 op_sel_hi:[1,0]
	v_pk_mul_f32 v[126:127], v[126:127], v[192:193]
	v_lshlrev_b32_e32 v193, 16, v196
	v_exp_f32_e32 v189, v189
	v_pk_mul_f32 v[190:191], v[228:229], v[190:191]
	v_fma_f32 v193, v193, s89, v134
	v_pk_mul_f32 v[130:131], v[130:131], v[190:191]
	v_pk_add_f32 v[190:191], v[240:241], 1.0 op_sel_hi:[1,0]
	v_pk_mul_f32 v[190:191], v[242:243], v[190:191]
	v_med3_f32 v193, v193, s85, v226
	v_pk_mul_f32 v[128:129], v[128:129], v[190:191]
	v_and_b32_e32 v191, 0xffff0000, v194
	v_lshlrev_b32_e32 v194, 16, v234
	v_add_f32_e32 v189, 1.0, v189
	v_exp_f32_e32 v193, v193
	v_rcp_f32_e32 v192, v189
	v_fma_f32 v189, v194, s89, v138
	v_fma_f32 v191, v191, s89, v143
	v_pk_add_f32 v[236:237], v[236:237], 1.0 op_sel_hi:[1,0]
	v_pk_mul_f32 v[228:229], v[238:239], v[236:237]
	v_med3_f32 v189, v189, s85, v226
	v_med3_f32 v191, v191, s85, v226
	v_pk_mul_f32 v[132:133], v[132:133], v[228:229]
	v_lshlrev_b32_e32 v227, 16, v195
	v_and_b32_e32 v229, 0xffff0000, v195
	v_and_b32_e32 v195, 0xffff0000, v196
	v_lshlrev_b32_e32 v231, 16, v197
	v_and_b32_e32 v236, 0xffff0000, v197
	v_and_b32_e32 v197, 0xffff0000, v232
	v_exp_f32_e32 v194, v189
	v_add_f32_e32 v189, 1.0, v193
	v_exp_f32_e32 v193, v191
	v_rcp_f32_e32 v196, v189
	v_fma_f32 v189, v197, s89, v147
	v_fma_f32 v195, v195, s89, v135
	v_med3_f32 v189, v189, s85, v226
	v_med3_f32 v195, v195, s85, v226
	v_and_b32_e32 v230, 0xffff0000, v234
	v_exp_f32_e32 v191, v189
	v_add_f32_e32 v189, 1.0, v193
	v_exp_f32_e32 v197, v195
	v_rcp_f32_e32 v193, v189
	v_fma_f32 v189, v230, s89, v139
	v_fma_f32 v227, v227, s89, v144
	v_med3_f32 v189, v189, s85, v226
	v_med3_f32 v227, v227, s85, v226
	v_lshlrev_b32_e32 v228, 16, v233
	v_exp_f32_e32 v195, v189
	v_add_f32_e32 v189, 1.0, v197
	v_exp_f32_e32 v227, v227
	v_rcp_f32_e32 v197, v189
	v_fma_f32 v189, v228, s89, v148
	v_med3_f32 v189, v189, s85, v226
	v_exp_f32_e32 v228, v189
	v_add_f32_e32 v189, 1.0, v227
	v_fma_f32 v227, v231, s89, v136
	v_med3_f32 v227, v227, s85, v226
	v_lshlrev_b32_e32 v190, 16, v232
	v_lshlrev_b32_e32 v232, 16, v235
	v_exp_f32_e32 v227, v227
	v_fma_f32 v229, v229, s89, v145
	v_rcp_f32_e32 v230, v189
	v_fma_f32 v189, v232, s89, v140
	v_med3_f32 v229, v229, s85, v226
	v_and_b32_e32 v233, 0xffff0000, v233
	v_med3_f32 v189, v189, s85, v226
	v_exp_f32_e32 v231, v229
	v_fma_f32 v190, v190, s89, v146
	v_exp_f32_e32 v232, v189
	v_add_f32_e32 v189, 1.0, v227
	v_fma_f32 v227, v233, s89, v149
	v_med3_f32 v190, v190, s85, v226
	v_med3_f32 v227, v227, s85, v226
	v_exp_f32_e32 v190, v190
	v_exp_f32_e32 v229, v227
	v_rcp_f32_e32 v234, v189
	v_add_f32_e32 v189, 1.0, v231
	v_rcp_f32_e32 v231, v189
	v_pk_add_f32 v[228:229], v[228:229], 1.0 op_sel_hi:[1,0]
	v_pk_add_f32 v[190:191], v[190:191], 1.0 op_sel_hi:[1,0]
	v_and_b32_e32 v235, 0xffff0000, v235
	v_pk_mul_f32 v[190:191], v[192:193], v[190:191]
	v_pk_mul_f32 v[192:193], v[230:231], v[228:229]
	v_fma_f32 v189, v235, s89, v141
	v_pk_mul_f32 v[124:125], v[124:125], v[192:193]
	v_fma_f32 v192, v236, s89, v137
	v_med3_f32 v192, v192, s85, v226
	v_exp_f32_e32 v192, v192
	v_med3_f32 v189, v189, s85, v226
	v_exp_f32_e32 v233, v189
	v_add_f32_e32 v189, 1.0, v192
	v_rcp_f32_e32 v235, v189
	v_pk_mul_f32 v[122:123], v[122:123], v[190:191]
	v_pk_add_f32 v[190:191], v[232:233], 1.0 op_sel_hi:[1,0]
	v_lshlrev_b32_e32 v189, 16, v174
	v_pk_mul_f32 v[190:191], v[234:235], v[190:191]
	v_lshlrev_b32_e32 v227, 16, v169
	v_pk_mul_f32 v[120:121], v[120:121], v[190:191]
	v_and_b32_e32 v190, 0xffff0000, v174
	v_lshlrev_b32_e32 v174, 16, v176
	v_and_b32_e32 v228, 0xffff0000, v169
	v_fma_f32 v169, v174, s89, v150
	v_pk_add_f32 v[192:193], v[194:195], 1.0 op_sel_hi:[1,0]
	v_pk_mul_f32 v[192:193], v[196:197], v[192:193]
	v_med3_f32 v169, v169, s85, v226
	v_pk_mul_f32 v[118:119], v[118:119], v[192:193]
	v_lshlrev_b32_e32 v191, 16, v175
	v_and_b32_e32 v193, 0xffff0000, v175
	v_and_b32_e32 v175, 0xffff0000, v176
	v_lshlrev_b32_e32 v192, 16, v167
	v_and_b32_e32 v196, 0xffff0000, v167
	v_lshlrev_b32_e32 v167, 16, v168
	v_exp_f32_e32 v169, v169
	v_fma_f32 v167, v167, s89, v154
	v_fma_f32 v175, v175, s89, v151
	v_med3_f32 v167, v167, s85, v226
	v_med3_f32 v175, v175, s85, v226
	v_and_b32_e32 v197, 0xffff0000, v168
	v_fma_f32 v168, v189, s89, v158
	v_exp_f32_e32 v174, v167
	v_add_f32_e32 v167, 1.0, v169
	v_fma_f32 v169, v190, s89, v159
	v_exp_f32_e32 v189, v175
	v_fma_f32 v190, v191, s89, v160
	v_lshlrev_b32_e32 v194, 16, v177
	v_and_b32_e32 v195, 0xffff0000, v177
	v_lshlrev_b32_e32 v176, 16, v166
	v_and_b32_e32 v177, 0xffff0000, v166
	v_med3_f32 v190, v190, s85, v226
	v_fma_f32 v166, v176, s89, v162
	v_rcp_f32_e32 v176, v167
	v_fma_f32 v167, v177, s89, v163
	v_fma_f32 v177, v197, s89, v155
	v_exp_f32_e32 v191, v190
	v_med3_f32 v175, v177, s85, v226
	v_add_f32_e32 v177, 1.0, v189
	v_fma_f32 v189, v192, s89, v164
	v_med3_f32 v189, v189, s85, v226
	v_exp_f32_e32 v190, v189
	v_add_f32_e32 v189, 1.0, v191
	v_fma_f32 v191, v194, s89, v152
	v_med3_f32 v191, v191, s85, v226
	v_exp_f32_e32 v191, v191
	v_fma_f32 v193, v193, s89, v161
	v_rcp_f32_e32 v192, v189
	v_fma_f32 v189, v227, s89, v156
	v_med3_f32 v168, v168, s85, v226
	v_med3_f32 v169, v169, s85, v226
	v_med3_f32 v193, v193, s85, v226
	v_exp_f32_e32 v168, v168
	v_exp_f32_e32 v169, v169
	v_med3_f32 v189, v189, s85, v226
	v_exp_f32_e32 v193, v193
	v_exp_f32_e32 v194, v189
	v_add_f32_e32 v189, 1.0, v191
	v_fma_f32 v191, v196, s89, v165
	v_med3_f32 v166, v166, s85, v226
	v_med3_f32 v167, v167, s85, v226
	v_med3_f32 v191, v191, s85, v226
; #define UNPK0(q_) ((f32x4){bf_lo((q_).x), bf_hi((q_).x), bf_lo((q_).y), bf_hi((q_).y)})
; #define UNPK1(q_) ((f32x4){bf_lo((q_).z), bf_hi((q_).z), bf_lo((q_).w), bf_hi((q_).w)})
;     static __device__ __forceinline__ float eneg(float g) { return __builtin_amdgcn_exp2f(-1.4426950408889634f * fminf(fmaxf(g, -30.f), 30.f)); }
;     __device__ __forceinline__ void mid(f32x4 (&acc)[2][2][4][2], const Unit& u, int wr, int wc, int fr, int fq) const {
;     ...
;             for (int m = 2 * (am & 1); m < 2 * (am & 1) + 2; ++m) { pa.fetch(ai, m, ra[m][0], ra[m][1]); pb.fetch(ai, m, rb[m][0], rb[m][1]); }
;             asm volatile("" ::: "memory");
; #pragma unroll
;             for (int m = 2 * (am & 1); m < 2 * (am & 1) + 2; ++m) {
;                 pa.stage(ra[m][0], ra[m][1]); const u32x4 ga0 = pa.get(0), ga1 = pa.get(1);
;                 asm volatile("" ::: "memory");
;                 pb.stage(rb[m][0], rb[m][1]); const u32x4 gb0 = pb.get(0), gb1 = pb.get(1);
;                 asm volatile("" ::: "memory");
; #pragma unroll
;                 for (int bj = 0; bj < 2; ++bj) { const u32x4 ga = bj ? ga1 : ga0, gb = bj ? gb1 : gb0;
;                     const f32x4 a0 = UNPK0(ga) + ba[bj][0], a1 = UNPK1(ga) + ba[bj][1], b0 = UNPK0(gb) + bb[bj][0], b1 = UNPK1(gb) + bb[bj][1];
; #pragma unroll
;                     for (int k = 0; k < 4; ++k) { acc[ai][bj][m][0][k] *= (1.0f + eneg(b0[k])) * __builtin_amdgcn_rcpf(1.0f + eneg(a0[k]));
;                                                   acc[ai][bj][m][1][k] *= (1.0f + eneg(b1[k])) * __builtin_amdgcn_rcpf(1.0f + eneg(a1[k])); } } }
	v_exp_f32_e32 v166, v166
	v_add_f32_e32 v168, 1.0, v168
	v_exp_f32_e32 v167, v167
	v_add_f32_e32 v169, 1.0, v169
	v_exp_f32_e32 v191, v191
	v_rcp_f32_e32 v196, v189
	v_add_f32_e32 v189, 1.0, v193
	v_rcp_f32_e32 v168, v168
	v_rcp_f32_e32 v169, v169
	v_rcp_f32_e32 v193, v189
	v_pk_add_f32 v[190:191], v[190:191], 1.0 op_sel_hi:[1,0]
	v_pk_add_f32 v[166:167], v[166:167], 1.0 op_sel_hi:[1,0]
	v_pk_mul_f32 v[166:167], v[168:169], v[166:167]
	v_pk_mul_f32 v[168:169], v[192:193], v[190:191]
	v_exp_f32_e32 v175, v175
	v_pk_mul_f32 v[116:117], v[116:117], v[168:169]
	v_fma_f32 v169, v195, s89, v153
	v_med3_f32 v169, v169, s85, v226
	v_exp_f32_e32 v169, v169
	v_fma_f32 v168, v228, s89, v157
	v_med3_f32 v168, v168, s85, v226
	v_rcp_f32_e32 v177, v177
	v_exp_f32_e32 v195, v168
	v_pk_mul_f32 v[114:115], v[114:115], v[166:167]
	v_add_f32_e32 v166, 1.0, v169
	v_rcp_f32_e32 v197, v166
	v_pk_add_f32 v[168:169], v[174:175], 1.0 op_sel_hi:[1,0]
	v_pk_add_f32 v[166:167], v[194:195], 1.0 op_sel_hi:[1,0]
	v_pk_mul_f32 v[168:169], v[176:177], v[168:169]
	v_pk_mul_f32 v[166:167], v[196:197], v[166:167]
	v_pk_mul_f32 v[110:111], v[110:111], v[168:169]
	v_lshlrev_b32_e32 v169, 16, v180
	v_pk_mul_f32 v[112:113], v[112:113], v[166:167]
	v_lshlrev_b32_e32 v166, 16, v178
	v_fma_f32 v169, v169, s89, v134
	v_fma_f32 v166, v166, s89, v142
	v_med3_f32 v169, v169, s85, v226
	v_med3_f32 v166, v166, s85, v226
	v_exp_f32_e32 v169, v169
	v_and_b32_e32 v167, 0xffff0000, v178
	v_and_b32_e32 v176, 0xffff0000, v180
	v_lshlrev_b32_e32 v168, 16, v170
	v_and_b32_e32 v178, 0xffff0000, v170
	v_lshlrev_b32_e32 v180, 16, v171
	v_and_b32_e32 v189, 0xffff0000, v171
	v_lshlrev_b32_e32 v170, 16, v172
	v_and_b32_e32 v171, 0xffff0000, v172
	v_exp_f32_e32 v172, v166
	v_fma_f32 v168, v168, s89, v146
	v_add_f32_e32 v169, 1.0, v169
	v_med3_f32 v166, v168, s85, v226
	v_add_f32_e32 v168, 1.0, v172
	v_rcp_f32_e32 v172, v169
	v_fma_f32 v169, v178, s89, v147
	v_add_co_u32_e32 v178, vcc, s84, v186
	v_lshlrev_b32_e32 v174, 16, v179
	v_and_b32_e32 v175, 0xffff0000, v179
	v_addc_co_u32_e32 v179, vcc, 0, v187, vcc
	global_load_dwordx4 v[190:193], v[178:179], off nt
	global_load_dwordx4 v[194:197], v[178:179], off offset:1024 nt
	v_add_co_u32_e32 v236, vcc, s84, v4
	v_fma_f32 v167, v167, s89, v143
	s_nop 0
	v_addc_co_u32_e32 v237, vcc, 0, v5, vcc
	global_load_dwordx4 v[228:231], v[236:237], off nt
	global_load_dwordx4 v[232:235], v[236:237], off offset:1024 nt
	v_med3_f32 v167, v167, s85, v226
	v_lshlrev_b32_e32 v227, 16, v173
	v_and_b32_e32 v239, 0xffff0000, v173
	v_exp_f32_e32 v173, v167
	v_fma_f32 v174, v174, s89, v144
	v_lshlrev_b32_e32 v177, 16, v181
	v_med3_f32 v174, v174, s85, v226
	v_med3_f32 v167, v169, s85, v226
	v_add_f32_e32 v169, 1.0, v173
	v_fma_f32 v173, v176, s89, v135
	v_fma_f32 v176, v180, s89, v148
	v_exp_f32_e32 v180, v174
	v_fma_f32 v177, v177, s89, v136
	v_fma_f32 v175, v175, s89, v145
	v_med3_f32 v177, v177, s85, v226
	v_exp_f32_e32 v177, v177
	v_med3_f32 v175, v175, s85, v226
	v_med3_f32 v174, v176, s85, v226
	v_add_f32_e32 v176, 1.0, v180
	v_fma_f32 v180, v227, s89, v140
	v_exp_f32_e32 v227, v175
	v_fma_f32 v189, v189, s89, v149
	v_add_f32_e32 v177, 1.0, v177
	v_med3_f32 v175, v189, s85, v226
	v_exp_f32_e32 v166, v166
	v_exp_f32_e32 v167, v167
	v_exp_f32_e32 v174, v174
	v_exp_f32_e32 v175, v175
	v_rcp_f32_e32 v238, v177
	v_add_f32_e32 v177, 1.0, v227
	v_rcp_f32_e32 v168, v168
	v_rcp_f32_e32 v169, v169
	v_rcp_f32_e32 v176, v176
	v_rcp_f32_e32 v177, v177
	v_pk_add_f32 v[174:175], v[174:175], 1.0 op_sel_hi:[1,0]
	v_pk_add_f32 v[166:167], v[166:167], 1.0 op_sel_hi:[1,0]
	v_and_b32_e32 v181, 0xffff0000, v181
	v_pk_mul_f32 v[166:167], v[168:169], v[166:167]
	v_pk_mul_f32 v[168:169], v[176:177], v[174:175]
	v_pk_mul_f32 v[108:109], v[108:109], v[168:169]
	v_fma_f32 v169, v181, s89, v137
	v_med3_f32 v173, v173, s85, v226
	v_med3_f32 v169, v169, s85, v226
	v_exp_f32_e32 v173, v173
	v_exp_f32_e32 v169, v169
	v_fma_f32 v170, v170, s89, v138
	v_fma_f32 v171, v171, s89, v139
	v_fma_f32 v168, v239, s89, v141
	v_med3_f32 v170, v170, s85, v226
	v_med3_f32 v171, v171, s85, v226
	v_med3_f32 v180, v180, s85, v226
	v_med3_f32 v168, v168, s85, v226
	v_exp_f32_e32 v170, v170
	v_exp_f32_e32 v171, v171
	v_add_f32_e32 v173, 1.0, v173
	v_exp_f32_e32 v180, v180
	v_exp_f32_e32 v181, v168
	v_pk_mul_f32 v[106:107], v[106:107], v[166:167]
	v_add_f32_e32 v166, 1.0, v169
	v_rcp_f32_e32 v173, v173
	v_rcp_f32_e32 v239, v166
	v_pk_add_f32 v[166:167], v[180:181], 1.0 op_sel_hi:[1,0]
	v_pk_add_f32 v[168:169], v[170:171], 1.0 op_sel_hi:[1,0]
	v_pk_mul_f32 v[166:167], v[238:239], v[166:167]
	v_pk_mul_f32 v[168:169], v[172:173], v[168:169]
	v_pk_mul_f32 v[104:105], v[104:105], v[166:167]
	v_pk_mul_f32 v[102:103], v[102:103], v[168:169]
	global_load_dwordx4 v[174:177], v[178:179], off offset:2048 nt
	s_nop 0
	global_load_dwordx4 v[178:181], v[178:179], off offset:3072 nt
	s_nop 0
	global_load_dwordx4 v[166:169], v[236:237], off offset:2048 nt
	global_load_dwordx4 v[170:173], v[236:237], off offset:3072 nt
	s_waitcnt vmcnt(7)
	s_waitcnt vmcnt(6)
	s_waitcnt vmcnt(5)
	s_waitcnt vmcnt(4)
; #define UNPK0(q_) ((f32x4){bf_lo((q_).x), bf_hi((q_).x), bf_lo((q_).y), bf_hi((q_).y)})
; #define UNPK1(q_) ((f32x4){bf_lo((q_).z), bf_hi((q_).z), bf_lo((q_).w), bf_hi((q_).w)})
;     static __device__ __forceinline__ float eneg(float g) { return __builtin_amdgcn_exp2f(-1.4426950408889634f * fminf(fmaxf(g, -30.f), 30.f)); }
;     __device__ __forceinline__ void mid(f32x4 (&acc)[2][2][4][2], const Unit& u, int wr, int wc, int fr, int fq) const {
;     ...
;             for (int m = 2 * (am & 1); m < 2 * (am & 1) + 2; ++m) {
;                 pa.stage(ra[m][0], ra[m][1]); const u32x4 ga0 = pa.get(0), ga1 = pa.get(1);
;                 asm volatile("" ::: "memory");
;                 pb.stage(rb[m][0], rb[m][1]); const u32x4 gb0 = pb.get(0), gb1 = pb.get(1);
;                 asm volatile("" ::: "memory");
; #pragma unroll
;                 for (int bj = 0; bj < 2; ++bj) { const u32x4 ga = bj ? ga1 : ga0, gb = bj ? gb1 : gb0;
;                     const f32x4 a0 = UNPK0(ga) + ba[bj][0], a1 = UNPK1(ga) + ba[bj][1], b0 = UNPK0(gb) + bb[bj][0], b1 = UNPK1(gb) + bb[bj][1];
; #pragma unroll
;                     for (int k = 0; k < 4; ++k) { acc[ai][bj][m][0][k] *= (1.0f + eneg(b0[k])) * __builtin_amdgcn_rcpf(1.0f + eneg(a0[k]));
;                                                   acc[ai][bj][m][1][k] *= (1.0f + eneg(b1[k])) * __builtin_amdgcn_rcpf(1.0f + eneg(a1[k])); } } }
	v_lshlrev_b32_e32 v189, 16, v190
	v_fma_f32 v189, v189, s89, v158
	v_med3_f32 v189, v189, s85, v226
	v_lshlrev_b32_e32 v236, 16, v191
	v_and_b32_e32 v237, 0xffff0000, v191
	v_lshlrev_b32_e32 v191, 16, v192
	v_exp_f32_e32 v189, v189
	v_fma_f32 v191, v191, s89, v150
	v_med3_f32 v191, v191, s85, v226
	v_and_b32_e32 v227, 0xffff0000, v190
	v_lshlrev_b32_e32 v239, 16, v193
	v_and_b32_e32 v241, 0xffff0000, v193
	v_lshlrev_b32_e32 v190, 16, v228
	v_and_b32_e32 v193, 0xffff0000, v228
	v_lshlrev_b32_e32 v228, 16, v230
	v_add_f32_e32 v189, 1.0, v189
	v_exp_f32_e32 v191, v191
	v_and_b32_e32 v238, 0xffff0000, v192
	v_rcp_f32_e32 v192, v189
	v_fma_f32 v189, v228, s89, v154
	v_med3_f32 v189, v189, s85, v226
	v_exp_f32_e32 v228, v189
	v_add_f32_e32 v189, 1.0, v191
	v_fma_f32 v191, v227, s89, v159
	v_med3_f32 v191, v191, s85, v226
	v_lshlrev_b32_e32 v240, 16, v229
	v_and_b32_e32 v242, 0xffff0000, v229
	v_and_b32_e32 v229, 0xffff0000, v230
	v_rcp_f32_e32 v230, v189
	v_fma_f32 v189, v193, s89, v163
	v_exp_f32_e32 v193, v191
	v_fma_f32 v227, v238, s89, v151
	v_med3_f32 v189, v189, s85, v226
	v_med3_f32 v227, v227, s85, v226
	v_exp_f32_e32 v191, v189
	v_add_f32_e32 v189, 1.0, v193
	v_exp_f32_e32 v227, v227
	v_rcp_f32_e32 v193, v189
	v_fma_f32 v189, v229, s89, v155
	v_med3_f32 v189, v189, s85, v226
	v_exp_f32_e32 v229, v189
	v_add_f32_e32 v189, 1.0, v227
	v_fma_f32 v227, v236, s89, v160
	v_med3_f32 v227, v227, s85, v226
	v_exp_f32_e32 v227, v227
	v_lshlrev_b32_e32 v243, 16, v231
	v_and_b32_e32 v244, 0xffff0000, v231
	v_rcp_f32_e32 v231, v189
	v_fma_f32 v189, v240, s89, v164
	v_med3_f32 v189, v189, s85, v226
	v_exp_f32_e32 v236, v189
	v_add_f32_e32 v189, 1.0, v227
	v_fma_f32 v227, v239, s89, v152
	v_med3_f32 v227, v227, s85, v226
	v_exp_f32_e32 v227, v227
	v_fma_f32 v237, v237, s89, v161
	v_rcp_f32_e32 v238, v189
	v_fma_f32 v189, v243, s89, v156
	v_med3_f32 v237, v237, s85, v226
	v_med3_f32 v189, v189, s85, v226
	v_exp_f32_e32 v239, v237
	v_fma_f32 v190, v190, s89, v162
	v_exp_f32_e32 v240, v189
	v_add_f32_e32 v189, 1.0, v227
	v_fma_f32 v227, v242, s89, v165
	v_med3_f32 v190, v190, s85, v226
	v_med3_f32 v227, v227, s85, v226
	v_exp_f32_e32 v190, v190
	v_exp_f32_e32 v237, v227
	v_rcp_f32_e32 v242, v189
	v_add_f32_e32 v189, 1.0, v239
	v_rcp_f32_e32 v239, v189
	v_pk_add_f32 v[236:237], v[236:237], 1.0 op_sel_hi:[1,0]
	v_pk_add_f32 v[190:191], v[190:191], 1.0 op_sel_hi:[1,0]
	v_fma_f32 v189, v244, s89, v157
	v_pk_mul_f32 v[190:191], v[192:193], v[190:191]
	v_pk_mul_f32 v[192:193], v[238:239], v[236:237]
	v_pk_mul_f32 v[100:101], v[100:101], v[192:193]
	v_fma_f32 v192, v241, s89, v153
	v_med3_f32 v192, v192, s85, v226
	v_exp_f32_e32 v192, v192
	v_med3_f32 v189, v189, s85, v226
	v_exp_f32_e32 v241, v189
	v_pk_mul_f32 v[98:99], v[98:99], v[190:191]
	v_add_f32_e32 v189, 1.0, v192
	v_rcp_f32_e32 v243, v189
	v_lshlrev_b32_e32 v189, 16, v194
	v_fma_f32 v189, v189, s89, v142
	v_pk_add_f32 v[192:193], v[228:229], 1.0 op_sel_hi:[1,0]
	v_pk_mul_f32 v[192:193], v[230:231], v[192:193]
	v_med3_f32 v189, v189, s85, v226
	v_pk_mul_f32 v[94:95], v[94:95], v[192:193]
	v_lshlrev_b32_e32 v193, 16, v196
	v_exp_f32_e32 v189, v189
	v_fma_f32 v193, v193, s89, v134
	v_pk_add_f32 v[190:191], v[240:241], 1.0 op_sel_hi:[1,0]
	v_pk_mul_f32 v[190:191], v[242:243], v[190:191]
	v_med3_f32 v193, v193, s85, v226
	v_pk_mul_f32 v[96:97], v[96:97], v[190:191]
	v_and_b32_e32 v191, 0xffff0000, v194
	v_lshlrev_b32_e32 v194, 16, v234
	v_add_f32_e32 v189, 1.0, v189
	v_exp_f32_e32 v193, v193
	v_rcp_f32_e32 v192, v189
	v_fma_f32 v189, v194, s89, v138
	v_fma_f32 v191, v191, s89, v143
	v_med3_f32 v189, v189, s85, v226
	v_med3_f32 v191, v191, s85, v226
	v_lshlrev_b32_e32 v227, 16, v195
	v_and_b32_e32 v229, 0xffff0000, v195
	v_and_b32_e32 v195, 0xffff0000, v196
	v_lshlrev_b32_e32 v231, 16, v197
	v_and_b32_e32 v236, 0xffff0000, v197
	v_and_b32_e32 v197, 0xffff0000, v232
	v_exp_f32_e32 v194, v189
	v_add_f32_e32 v189, 1.0, v193
	v_exp_f32_e32 v193, v191
	v_rcp_f32_e32 v196, v189
	v_fma_f32 v189, v197, s89, v147
	v_fma_f32 v195, v195, s89, v135
	v_med3_f32 v189, v189, s85, v226
	v_med3_f32 v195, v195, s85, v226
	v_and_b32_e32 v230, 0xffff0000, v234
	v_exp_f32_e32 v191, v189
	v_add_f32_e32 v189, 1.0, v193
	v_exp_f32_e32 v197, v195
	v_rcp_f32_e32 v193, v189
	v_fma_f32 v189, v230, s89, v139
	v_fma_f32 v227, v227, s89, v144
	v_med3_f32 v189, v189, s85, v226
	v_med3_f32 v227, v227, s85, v226
	v_lshlrev_b32_e32 v228, 16, v233
	v_exp_f32_e32 v195, v189
	v_add_f32_e32 v189, 1.0, v197
	v_exp_f32_e32 v227, v227
	v_rcp_f32_e32 v197, v189
	v_fma_f32 v189, v228, s89, v148
	v_med3_f32 v189, v189, s85, v226
	v_exp_f32_e32 v228, v189
	v_add_f32_e32 v189, 1.0, v227
	v_fma_f32 v227, v231, s89, v136
	v_med3_f32 v227, v227, s85, v226
	v_lshlrev_b32_e32 v190, 16, v232
	v_lshlrev_b32_e32 v232, 16, v235
	v_exp_f32_e32 v227, v227
	v_fma_f32 v229, v229, s89, v145
	v_rcp_f32_e32 v230, v189
	v_fma_f32 v189, v232, s89, v140
	v_med3_f32 v229, v229, s85, v226
	v_and_b32_e32 v233, 0xffff0000, v233
	v_med3_f32 v189, v189, s85, v226
	v_exp_f32_e32 v231, v229
	v_fma_f32 v190, v190, s89, v146
	v_exp_f32_e32 v232, v189
	v_add_f32_e32 v189, 1.0, v227
	v_fma_f32 v227, v233, s89, v149
	v_med3_f32 v190, v190, s85, v226
	v_med3_f32 v227, v227, s85, v226
	v_exp_f32_e32 v190, v190
	v_exp_f32_e32 v229, v227
	v_rcp_f32_e32 v234, v189
	v_add_f32_e32 v189, 1.0, v231
	v_rcp_f32_e32 v231, v189
	v_pk_add_f32 v[228:229], v[228:229], 1.0 op_sel_hi:[1,0]
	v_pk_add_f32 v[190:191], v[190:191], 1.0 op_sel_hi:[1,0]
	v_and_b32_e32 v235, 0xffff0000, v235
	v_pk_mul_f32 v[190:191], v[192:193], v[190:191]
	v_pk_mul_f32 v[192:193], v[230:231], v[228:229]
	v_fma_f32 v189, v235, s89, v141
	v_pk_mul_f32 v[92:93], v[92:93], v[192:193]
	v_fma_f32 v192, v236, s89, v137
	v_med3_f32 v192, v192, s85, v226
	v_exp_f32_e32 v192, v192
	v_med3_f32 v189, v189, s85, v226
	v_exp_f32_e32 v233, v189
	v_add_f32_e32 v189, 1.0, v192
	v_rcp_f32_e32 v235, v189
	s_waitcnt vmcnt(3)
; #define UNPK0(q_) ((f32x4){bf_lo((q_).x), bf_hi((q_).x), bf_lo((q_).y), bf_hi((q_).y)})
; #define UNPK1(q_) ((f32x4){bf_lo((q_).z), bf_hi((q_).z), bf_lo((q_).w), bf_hi((q_).w)})
;     static __device__ __forceinline__ float eneg(float g) { return __builtin_amdgcn_exp2f(-1.4426950408889634f * fminf(fmaxf(g, -30.f), 30.f)); }
;     __device__ __forceinline__ void mid(f32x4 (&acc)[2][2][4][2], const Unit& u, int wr, int wc, int fr, int fq) const {
;     ...
;         for (int am = 0; am < 4; ++am) { const int ai = am >> 1;
;             u32x4 ra[4][2], rb[4][2];
; #pragma unroll
;             for (int m = 2 * (am & 1); m < 2 * (am & 1) + 2; ++m) { pa.fetch(ai, m, ra[m][0], ra[m][1]); pb.fetch(ai, m, rb[m][0], rb[m][1]); }
;             asm volatile("" ::: "memory");
; #pragma unroll
;             for (int m = 2 * (am & 1); m < 2 * (am & 1) + 2; ++m) {
;                 pa.stage(ra[m][0], ra[m][1]); const u32x4 ga0 = pa.get(0), ga1 = pa.get(1);
;                 asm volatile("" ::: "memory");
;                 pb.stage(rb[m][0], rb[m][1]); const u32x4 gb0 = pb.get(0), gb1 = pb.get(1);
;                 asm volatile("" ::: "memory");
; #pragma unroll
;                 for (int bj = 0; bj < 2; ++bj) { const u32x4 ga = bj ? ga1 : ga0, gb = bj ? gb1 : gb0;
;                     const f32x4 a0 = UNPK0(ga) + ba[bj][0], a1 = UNPK1(ga) + ba[bj][1], b0 = UNPK0(gb) + bb[bj][0], b1 = UNPK1(gb) + bb[bj][1];
; #pragma unroll
;                     for (int k = 0; k < 4; ++k) { acc[ai][bj][m][0][k] *= (1.0f + eneg(b0[k])) * __builtin_amdgcn_rcpf(1.0f + eneg(a0[k]));
;                                                   acc[ai][bj][m][1][k] *= (1.0f + eneg(b1[k])) * __builtin_amdgcn_rcpf(1.0f + eneg(a1[k])); } } }
	s_waitcnt vmcnt(2)
	s_waitcnt vmcnt(1)
	s_waitcnt vmcnt(0)
	v_pk_mul_f32 v[90:91], v[90:91], v[190:191]
	v_pk_add_f32 v[190:191], v[232:233], 1.0 op_sel_hi:[1,0]
	v_lshlrev_b32_e32 v189, 16, v174
	v_pk_mul_f32 v[190:191], v[234:235], v[190:191]
	v_lshlrev_b32_e32 v227, 16, v169
	v_pk_mul_f32 v[88:89], v[88:89], v[190:191]
	v_and_b32_e32 v190, 0xffff0000, v174
	v_lshlrev_b32_e32 v174, 16, v176
	v_and_b32_e32 v228, 0xffff0000, v169
	v_fma_f32 v169, v174, s89, v150
	v_pk_add_f32 v[192:193], v[194:195], 1.0 op_sel_hi:[1,0]
	v_pk_mul_f32 v[192:193], v[196:197], v[192:193]
	v_med3_f32 v169, v169, s85, v226
	v_pk_mul_f32 v[86:87], v[86:87], v[192:193]
	v_lshlrev_b32_e32 v191, 16, v175
	v_and_b32_e32 v193, 0xffff0000, v175
	v_and_b32_e32 v175, 0xffff0000, v176
	v_lshlrev_b32_e32 v192, 16, v167
	v_and_b32_e32 v196, 0xffff0000, v167
	v_lshlrev_b32_e32 v167, 16, v168
	v_exp_f32_e32 v169, v169
	v_fma_f32 v167, v167, s89, v154
	v_fma_f32 v175, v175, s89, v151
	v_med3_f32 v167, v167, s85, v226
	v_med3_f32 v175, v175, s85, v226
	v_and_b32_e32 v197, 0xffff0000, v168
	v_fma_f32 v168, v189, s89, v158
	v_exp_f32_e32 v174, v167
	v_add_f32_e32 v167, 1.0, v169
	v_fma_f32 v169, v190, s89, v159
	v_exp_f32_e32 v189, v175
	v_fma_f32 v190, v191, s89, v160
	v_lshlrev_b32_e32 v194, 16, v177
	v_and_b32_e32 v195, 0xffff0000, v177
	v_lshlrev_b32_e32 v176, 16, v166
	v_and_b32_e32 v177, 0xffff0000, v166
	v_med3_f32 v190, v190, s85, v226
	v_fma_f32 v166, v176, s89, v162
	v_rcp_f32_e32 v176, v167
	v_fma_f32 v167, v177, s89, v163
	v_fma_f32 v177, v197, s89, v155
	v_exp_f32_e32 v191, v190
	v_med3_f32 v175, v177, s85, v226
	v_add_f32_e32 v177, 1.0, v189
	v_fma_f32 v189, v192, s89, v164
	v_med3_f32 v189, v189, s85, v226
	v_exp_f32_e32 v190, v189
	v_add_f32_e32 v189, 1.0, v191
	v_fma_f32 v191, v194, s89, v152
	v_med3_f32 v191, v191, s85, v226
	v_exp_f32_e32 v191, v191
	v_fma_f32 v193, v193, s89, v161
	v_rcp_f32_e32 v192, v189
	v_fma_f32 v189, v227, s89, v156
	v_med3_f32 v168, v168, s85, v226
	v_med3_f32 v169, v169, s85, v226
	v_med3_f32 v193, v193, s85, v226
	v_exp_f32_e32 v168, v168
	v_exp_f32_e32 v169, v169
	v_med3_f32 v189, v189, s85, v226
	v_exp_f32_e32 v193, v193
	v_exp_f32_e32 v194, v189
	v_add_f32_e32 v189, 1.0, v191
	v_fma_f32 v191, v196, s89, v165
	v_med3_f32 v166, v166, s85, v226
	v_med3_f32 v167, v167, s85, v226
	v_med3_f32 v191, v191, s85, v226
	v_exp_f32_e32 v166, v166
	v_add_f32_e32 v168, 1.0, v168
	v_exp_f32_e32 v167, v167
	v_add_f32_e32 v169, 1.0, v169
	v_exp_f32_e32 v191, v191
	v_rcp_f32_e32 v196, v189
	v_add_f32_e32 v189, 1.0, v193
	v_rcp_f32_e32 v168, v168
	v_rcp_f32_e32 v169, v169
	v_rcp_f32_e32 v193, v189
	v_pk_add_f32 v[190:191], v[190:191], 1.0 op_sel_hi:[1,0]
	v_pk_add_f32 v[166:167], v[166:167], 1.0 op_sel_hi:[1,0]
	v_pk_mul_f32 v[166:167], v[168:169], v[166:167]
	v_pk_mul_f32 v[168:169], v[192:193], v[190:191]
	v_exp_f32_e32 v175, v175
	v_pk_mul_f32 v[84:85], v[84:85], v[168:169]
	v_fma_f32 v169, v195, s89, v153
	v_med3_f32 v169, v169, s85, v226
	v_exp_f32_e32 v169, v169
	v_fma_f32 v168, v228, s89, v157
	v_med3_f32 v168, v168, s85, v226
	v_rcp_f32_e32 v177, v177
	v_exp_f32_e32 v195, v168
	v_pk_mul_f32 v[82:83], v[82:83], v[166:167]
	v_add_f32_e32 v166, 1.0, v169
	v_rcp_f32_e32 v197, v166
	v_pk_add_f32 v[168:169], v[174:175], 1.0 op_sel_hi:[1,0]
	v_pk_add_f32 v[166:167], v[194:195], 1.0 op_sel_hi:[1,0]
	v_pk_mul_f32 v[168:169], v[176:177], v[168:169]
	v_pk_mul_f32 v[166:167], v[196:197], v[166:167]
	v_pk_mul_f32 v[78:79], v[78:79], v[168:169]
	v_lshlrev_b32_e32 v169, 16, v180
	v_pk_mul_f32 v[80:81], v[80:81], v[166:167]
	v_lshlrev_b32_e32 v166, 16, v178
	v_fma_f32 v169, v169, s89, v134
	v_fma_f32 v166, v166, s89, v142
	v_med3_f32 v169, v169, s85, v226
	v_med3_f32 v166, v166, s85, v226
	v_exp_f32_e32 v169, v169
	v_and_b32_e32 v167, 0xffff0000, v178
	v_and_b32_e32 v176, 0xffff0000, v180
	v_lshlrev_b32_e32 v168, 16, v170
	v_and_b32_e32 v178, 0xffff0000, v170
	v_lshlrev_b32_e32 v180, 16, v171
	v_and_b32_e32 v189, 0xffff0000, v171
	v_lshlrev_b32_e32 v170, 16, v172
	v_and_b32_e32 v171, 0xffff0000, v172
	v_exp_f32_e32 v172, v166
	v_fma_f32 v168, v168, s89, v146
	v_add_f32_e32 v169, 1.0, v169
	v_med3_f32 v166, v168, s85, v226
	v_add_f32_e32 v168, 1.0, v172
	v_rcp_f32_e32 v172, v169
	v_fma_f32 v169, v178, s89, v147
	v_add_co_u32_e32 v178, vcc, s79, v186
	v_lshlrev_b32_e32 v174, 16, v179
	v_and_b32_e32 v175, 0xffff0000, v179
	v_addc_co_u32_e32 v179, vcc, 0, v187, vcc
	v_add_co_u32_e32 v186, vcc, s86, v186
	v_fma_f32 v167, v167, s89, v143
	s_nop 0
	v_addc_co_u32_e32 v187, vcc, 0, v187, vcc
	global_load_dwordx4 v[190:193], v[186:187], off offset:-4096 nt
	global_load_dwordx4 v[194:197], v[178:179], off offset:1024 nt
	v_add_co_u32_e32 v236, vcc, s79, v4
	s_nop 0
	s_nop 0
	v_addc_co_u32_e32 v237, vcc, 0, v5, vcc
	v_add_co_u32_e32 v4, vcc, s86, v4
	v_med3_f32 v167, v167, s85, v226
	s_nop 0
	v_addc_co_u32_e32 v5, vcc, 0, v5, vcc
	global_load_dwordx4 v[228:231], v[4:5], off offset:-4096 nt
	global_load_dwordx4 v[232:235], v[236:237], off offset:1024 nt
	v_lshlrev_b32_e32 v227, 16, v173
	v_and_b32_e32 v239, 0xffff0000, v173
	v_exp_f32_e32 v173, v167
	v_fma_f32 v174, v174, s89, v144
	v_lshlrev_b32_e32 v177, 16, v181
	v_med3_f32 v174, v174, s85, v226
	v_med3_f32 v167, v169, s85, v226
	v_add_f32_e32 v169, 1.0, v173
	v_fma_f32 v173, v176, s89, v135
	v_fma_f32 v176, v180, s89, v148
	v_exp_f32_e32 v180, v174
	v_fma_f32 v177, v177, s89, v136
	v_fma_f32 v175, v175, s89, v145
	v_med3_f32 v177, v177, s85, v226
	v_exp_f32_e32 v177, v177
	v_med3_f32 v175, v175, s85, v226
	v_med3_f32 v174, v176, s85, v226
	v_add_f32_e32 v176, 1.0, v180
	v_fma_f32 v180, v227, s89, v140
; #define UNPK0(q_) ((f32x4){bf_lo((q_).x), bf_hi((q_).x), bf_lo((q_).y), bf_hi((q_).y)})
; #define UNPK1(q_) ((f32x4){bf_lo((q_).z), bf_hi((q_).z), bf_lo((q_).w), bf_hi((q_).w)})
;     static __device__ __forceinline__ float eneg(float g) { return __builtin_amdgcn_exp2f(-1.4426950408889634f * fminf(fmaxf(g, -30.f), 30.f)); }
;     __device__ __forceinline__ void mid(f32x4 (&acc)[2][2][4][2], const Unit& u, int wr, int wc, int fr, int fq) const {
;     ...
;         for (int am = 0; am < 4; ++am) { const int ai = am >> 1;
;             u32x4 ra[4][2], rb[4][2];
; #pragma unroll
;             for (int m = 2 * (am & 1); m < 2 * (am & 1) + 2; ++m) { pa.fetch(ai, m, ra[m][0], ra[m][1]); pb.fetch(ai, m, rb[m][0], rb[m][1]); }
;             asm volatile("" ::: "memory");
; #pragma unroll
;             for (int m = 2 * (am & 1); m < 2 * (am & 1) + 2; ++m) {
;                 pa.stage(ra[m][0], ra[m][1]); const u32x4 ga0 = pa.get(0), ga1 = pa.get(1);
;                 asm volatile("" ::: "memory");
;                 pb.stage(rb[m][0], rb[m][1]); const u32x4 gb0 = pb.get(0), gb1 = pb.get(1);
;                 asm volatile("" ::: "memory");
; #pragma unroll
;                 for (int bj = 0; bj < 2; ++bj) { const u32x4 ga = bj ? ga1 : ga0, gb = bj ? gb1 : gb0;
;                     const f32x4 a0 = UNPK0(ga) + ba[bj][0], a1 = UNPK1(ga) + ba[bj][1], b0 = UNPK0(gb) + bb[bj][0], b1 = UNPK1(gb) + bb[bj][1];
; #pragma unroll
;                     for (int k = 0; k < 4; ++k) { acc[ai][bj][m][0][k] *= (1.0f + eneg(b0[k])) * __builtin_amdgcn_rcpf(1.0f + eneg(a0[k]));
;                                                   acc[ai][bj][m][1][k] *= (1.0f + eneg(b1[k])) * __builtin_amdgcn_rcpf(1.0f + eneg(a1[k])); } } }
	v_exp_f32_e32 v227, v175
	v_fma_f32 v189, v189, s89, v149
	v_add_f32_e32 v177, 1.0, v177
	v_med3_f32 v175, v189, s85, v226
	v_exp_f32_e32 v166, v166
	v_exp_f32_e32 v167, v167
	v_exp_f32_e32 v174, v174
	v_exp_f32_e32 v175, v175
	v_rcp_f32_e32 v238, v177
	v_add_f32_e32 v177, 1.0, v227
	v_rcp_f32_e32 v168, v168
	v_rcp_f32_e32 v169, v169
	v_rcp_f32_e32 v176, v176
	v_rcp_f32_e32 v177, v177
	v_pk_add_f32 v[174:175], v[174:175], 1.0 op_sel_hi:[1,0]
	v_pk_add_f32 v[166:167], v[166:167], 1.0 op_sel_hi:[1,0]
	v_and_b32_e32 v181, 0xffff0000, v181
	v_pk_mul_f32 v[166:167], v[168:169], v[166:167]
	v_pk_mul_f32 v[168:169], v[176:177], v[174:175]
	v_pk_mul_f32 v[76:77], v[76:77], v[168:169]
	v_fma_f32 v169, v181, s89, v137
	v_med3_f32 v173, v173, s85, v226
	v_med3_f32 v169, v169, s85, v226
	v_exp_f32_e32 v173, v173
	v_exp_f32_e32 v169, v169
	v_fma_f32 v170, v170, s89, v138
	v_fma_f32 v171, v171, s89, v139
	v_fma_f32 v168, v239, s89, v141
	v_med3_f32 v170, v170, s85, v226
	v_med3_f32 v171, v171, s85, v226
	v_med3_f32 v180, v180, s85, v226
	v_med3_f32 v168, v168, s85, v226
	v_exp_f32_e32 v170, v170
	v_exp_f32_e32 v171, v171
	v_add_f32_e32 v173, 1.0, v173
	v_exp_f32_e32 v180, v180
	v_exp_f32_e32 v181, v168
	v_pk_mul_f32 v[74:75], v[74:75], v[166:167]
	v_add_f32_e32 v166, 1.0, v169
	v_rcp_f32_e32 v173, v173
	v_rcp_f32_e32 v239, v166
	v_pk_add_f32 v[166:167], v[180:181], 1.0 op_sel_hi:[1,0]
	v_pk_add_f32 v[168:169], v[170:171], 1.0 op_sel_hi:[1,0]
	v_pk_mul_f32 v[166:167], v[238:239], v[166:167]
	v_pk_mul_f32 v[168:169], v[172:173], v[168:169]
	v_pk_mul_f32 v[72:73], v[72:73], v[166:167]
	v_pk_mul_f32 v[70:71], v[70:71], v[168:169]
	global_load_dwordx4 v[174:177], v[178:179], off offset:2048 nt
	s_nop 0
	global_load_dwordx4 v[178:181], v[178:179], off offset:3072 nt
	s_nop 0
	global_load_dwordx4 v[166:169], v[236:237], off offset:2048 nt
	global_load_dwordx4 v[170:173], v[236:237], off offset:3072 nt
	s_waitcnt vmcnt(7)
	s_waitcnt vmcnt(6)
	s_waitcnt vmcnt(5)
	s_waitcnt vmcnt(4)
	v_lshlrev_b32_e32 v189, 16, v190
	v_fma_f32 v189, v189, s89, v158
	v_med3_f32 v189, v189, s85, v226
	v_lshlrev_b32_e32 v236, 16, v191
	v_and_b32_e32 v237, 0xffff0000, v191
	v_lshlrev_b32_e32 v191, 16, v192
	v_exp_f32_e32 v189, v189
	v_fma_f32 v191, v191, s89, v150
	v_med3_f32 v191, v191, s85, v226
	v_and_b32_e32 v227, 0xffff0000, v190
	v_lshlrev_b32_e32 v239, 16, v193
	v_and_b32_e32 v241, 0xffff0000, v193
	v_lshlrev_b32_e32 v190, 16, v228
	v_and_b32_e32 v193, 0xffff0000, v228
	v_lshlrev_b32_e32 v228, 16, v230
	v_add_f32_e32 v189, 1.0, v189
	v_exp_f32_e32 v191, v191
	v_and_b32_e32 v238, 0xffff0000, v192
	v_rcp_f32_e32 v192, v189
	v_fma_f32 v189, v228, s89, v154
	v_med3_f32 v189, v189, s85, v226
	v_exp_f32_e32 v228, v189
	v_add_f32_e32 v189, 1.0, v191
	v_fma_f32 v191, v227, s89, v159
	v_med3_f32 v191, v191, s85, v226
	v_lshlrev_b32_e32 v240, 16, v229
	v_and_b32_e32 v242, 0xffff0000, v229
	v_and_b32_e32 v229, 0xffff0000, v230
	v_rcp_f32_e32 v230, v189
	v_fma_f32 v189, v193, s89, v163
	v_exp_f32_e32 v193, v191
	v_fma_f32 v227, v238, s89, v151
	v_med3_f32 v189, v189, s85, v226
	v_med3_f32 v227, v227, s85, v226
	v_exp_f32_e32 v191, v189
	v_add_f32_e32 v189, 1.0, v193
	v_exp_f32_e32 v227, v227
	v_rcp_f32_e32 v193, v189
	v_fma_f32 v189, v229, s89, v155
	v_med3_f32 v189, v189, s85, v226
	v_exp_f32_e32 v229, v189
	v_add_f32_e32 v189, 1.0, v227
	v_fma_f32 v227, v236, s89, v160
	v_med3_f32 v227, v227, s85, v226
	v_exp_f32_e32 v227, v227
	v_lshlrev_b32_e32 v243, 16, v231
	v_and_b32_e32 v244, 0xffff0000, v231
	v_rcp_f32_e32 v231, v189
	v_fma_f32 v189, v240, s89, v164
	v_med3_f32 v189, v189, s85, v226
	v_exp_f32_e32 v236, v189
	v_add_f32_e32 v189, 1.0, v227
	v_fma_f32 v227, v239, s89, v152
	v_med3_f32 v227, v227, s85, v226
	v_exp_f32_e32 v227, v227
	v_fma_f32 v237, v237, s89, v161
	v_rcp_f32_e32 v238, v189
	v_fma_f32 v189, v243, s89, v156
	v_med3_f32 v237, v237, s85, v226
	v_med3_f32 v189, v189, s85, v226
	v_exp_f32_e32 v239, v237
	v_fma_f32 v190, v190, s89, v162
	v_exp_f32_e32 v240, v189
	v_add_f32_e32 v189, 1.0, v227
	v_fma_f32 v227, v242, s89, v165
	v_med3_f32 v190, v190, s85, v226
	v_med3_f32 v227, v227, s85, v226
	v_exp_f32_e32 v190, v190
	v_exp_f32_e32 v237, v227
	v_rcp_f32_e32 v242, v189
	v_add_f32_e32 v189, 1.0, v239
	v_rcp_f32_e32 v239, v189
	v_pk_add_f32 v[236:237], v[236:237], 1.0 op_sel_hi:[1,0]
	v_pk_add_f32 v[190:191], v[190:191], 1.0 op_sel_hi:[1,0]
	v_fma_f32 v189, v244, s89, v157
	v_pk_mul_f32 v[190:191], v[192:193], v[190:191]
	v_pk_mul_f32 v[192:193], v[238:239], v[236:237]
	v_pk_mul_f32 v[68:69], v[68:69], v[192:193]
	v_fma_f32 v192, v241, s89, v153
	v_med3_f32 v192, v192, s85, v226
	v_exp_f32_e32 v192, v192
	v_med3_f32 v189, v189, s85, v226
	v_exp_f32_e32 v241, v189
	v_pk_mul_f32 v[66:67], v[66:67], v[190:191]
	v_add_f32_e32 v189, 1.0, v192
	v_rcp_f32_e32 v243, v189
	v_lshlrev_b32_e32 v189, 16, v194
	v_fma_f32 v189, v189, s89, v142
	v_pk_add_f32 v[192:193], v[228:229], 1.0 op_sel_hi:[1,0]
	v_pk_mul_f32 v[192:193], v[230:231], v[192:193]
	v_med3_f32 v189, v189, s85, v226
	v_pk_mul_f32 v[62:63], v[62:63], v[192:193]
	v_lshlrev_b32_e32 v193, 16, v196
	v_exp_f32_e32 v189, v189
	v_fma_f32 v193, v193, s89, v134
	v_pk_add_f32 v[190:191], v[240:241], 1.0 op_sel_hi:[1,0]
	v_pk_mul_f32 v[190:191], v[242:243], v[190:191]
	v_med3_f32 v193, v193, s85, v226
	v_pk_mul_f32 v[64:65], v[64:65], v[190:191]
	v_and_b32_e32 v191, 0xffff0000, v194
	v_lshlrev_b32_e32 v194, 16, v234
	v_add_f32_e32 v189, 1.0, v189
	v_exp_f32_e32 v193, v193
	v_rcp_f32_e32 v192, v189
	v_fma_f32 v189, v194, s89, v138
	v_fma_f32 v191, v191, s89, v143
	v_med3_f32 v189, v189, s85, v226
	v_med3_f32 v191, v191, s85, v226
; #define UNPK0(q_) ((f32x4){bf_lo((q_).x), bf_hi((q_).x), bf_lo((q_).y), bf_hi((q_).y)})
; #define UNPK1(q_) ((f32x4){bf_lo((q_).z), bf_hi((q_).z), bf_lo((q_).w), bf_hi((q_).w)})
;     static __device__ __forceinline__ float eneg(float g) { return __builtin_amdgcn_exp2f(-1.4426950408889634f * fminf(fmaxf(g, -30.f), 30.f)); }
;     __device__ __forceinline__ void mid(f32x4 (&acc)[2][2][4][2], const Unit& u, int wr, int wc, int fr, int fq) const {
;     ...
;             for (int m = 2 * (am & 1); m < 2 * (am & 1) + 2; ++m) {
;                 pa.stage(ra[m][0], ra[m][1]); const u32x4 ga0 = pa.get(0), ga1 = pa.get(1);
;                 asm volatile("" ::: "memory");
;                 pb.stage(rb[m][0], rb[m][1]); const u32x4 gb0 = pb.get(0), gb1 = pb.get(1);
;                 asm volatile("" ::: "memory");
; #pragma unroll
;                 for (int bj = 0; bj < 2; ++bj) { const u32x4 ga = bj ? ga1 : ga0, gb = bj ? gb1 : gb0;
;                     const f32x4 a0 = UNPK0(ga) + ba[bj][0], a1 = UNPK1(ga) + ba[bj][1], b0 = UNPK0(gb) + bb[bj][0], b1 = UNPK1(gb) + bb[bj][1];
; #pragma unroll
;                     for (int k = 0; k < 4; ++k) { acc[ai][bj][m][0][k] *= (1.0f + eneg(b0[k])) * __builtin_amdgcn_rcpf(1.0f + eneg(a0[k]));
;                                                   acc[ai][bj][m][1][k] *= (1.0f + eneg(b1[k])) * __builtin_amdgcn_rcpf(1.0f + eneg(a1[k])); } } }
	v_lshlrev_b32_e32 v227, 16, v195
	v_and_b32_e32 v229, 0xffff0000, v195
	v_and_b32_e32 v195, 0xffff0000, v196
	v_lshlrev_b32_e32 v231, 16, v197
	v_and_b32_e32 v236, 0xffff0000, v197
	v_and_b32_e32 v197, 0xffff0000, v232
	v_exp_f32_e32 v194, v189
	v_add_f32_e32 v189, 1.0, v193
	v_exp_f32_e32 v193, v191
	v_rcp_f32_e32 v196, v189
	v_fma_f32 v189, v197, s89, v147
	v_fma_f32 v195, v195, s89, v135
	v_med3_f32 v189, v189, s85, v226
	v_med3_f32 v195, v195, s85, v226
	v_and_b32_e32 v230, 0xffff0000, v234
	v_exp_f32_e32 v191, v189
	v_add_f32_e32 v189, 1.0, v193
	v_exp_f32_e32 v197, v195
	v_rcp_f32_e32 v193, v189
	v_fma_f32 v189, v230, s89, v139
	v_fma_f32 v227, v227, s89, v144
	v_med3_f32 v189, v189, s85, v226
	v_med3_f32 v227, v227, s85, v226
	v_lshlrev_b32_e32 v228, 16, v233
	v_exp_f32_e32 v195, v189
	v_add_f32_e32 v189, 1.0, v197
	v_exp_f32_e32 v227, v227
	v_rcp_f32_e32 v197, v189
	v_fma_f32 v189, v228, s89, v148
	v_med3_f32 v189, v189, s85, v226
	v_exp_f32_e32 v228, v189
	v_add_f32_e32 v189, 1.0, v227
	v_fma_f32 v227, v231, s89, v136
	v_med3_f32 v227, v227, s85, v226
	v_lshlrev_b32_e32 v190, 16, v232
	v_lshlrev_b32_e32 v232, 16, v235
	v_exp_f32_e32 v227, v227
	v_fma_f32 v229, v229, s89, v145
	v_rcp_f32_e32 v230, v189
	v_fma_f32 v189, v232, s89, v140
	v_med3_f32 v229, v229, s85, v226
	v_and_b32_e32 v233, 0xffff0000, v233
	v_med3_f32 v189, v189, s85, v226
	v_exp_f32_e32 v231, v229
	v_fma_f32 v190, v190, s89, v146
	v_exp_f32_e32 v232, v189
	v_add_f32_e32 v189, 1.0, v227
	v_fma_f32 v227, v233, s89, v149
	v_med3_f32 v190, v190, s85, v226
	v_med3_f32 v227, v227, s85, v226
	v_exp_f32_e32 v190, v190
	v_exp_f32_e32 v229, v227
	v_rcp_f32_e32 v234, v189
	v_add_f32_e32 v189, 1.0, v231
	v_rcp_f32_e32 v231, v189
	v_pk_add_f32 v[228:229], v[228:229], 1.0 op_sel_hi:[1,0]
	v_pk_add_f32 v[190:191], v[190:191], 1.0 op_sel_hi:[1,0]
	v_and_b32_e32 v235, 0xffff0000, v235
	v_pk_mul_f32 v[190:191], v[192:193], v[190:191]
	v_pk_mul_f32 v[192:193], v[230:231], v[228:229]
	v_fma_f32 v189, v235, s89, v141
	v_pk_mul_f32 v[60:61], v[60:61], v[192:193]
	v_fma_f32 v192, v236, s89, v137
	v_med3_f32 v192, v192, s85, v226
	v_exp_f32_e32 v192, v192
	v_med3_f32 v189, v189, s85, v226
	v_exp_f32_e32 v233, v189
	v_add_f32_e32 v189, 1.0, v192
	v_rcp_f32_e32 v235, v189
	s_waitcnt vmcnt(3)
	s_waitcnt vmcnt(2)
	s_waitcnt vmcnt(1)
	s_waitcnt vmcnt(0)
	v_pk_mul_f32 v[58:59], v[58:59], v[190:191]
	v_pk_add_f32 v[190:191], v[232:233], 1.0 op_sel_hi:[1,0]
	v_lshlrev_b32_e32 v189, 16, v174
	v_pk_mul_f32 v[190:191], v[234:235], v[190:191]
	v_lshlrev_b32_e32 v227, 16, v169
	v_pk_mul_f32 v[56:57], v[56:57], v[190:191]
	v_and_b32_e32 v190, 0xffff0000, v174
	v_lshlrev_b32_e32 v174, 16, v176
	v_and_b32_e32 v228, 0xffff0000, v169
	v_fma_f32 v169, v174, s89, v150
	v_pk_add_f32 v[192:193], v[194:195], 1.0 op_sel_hi:[1,0]
	v_pk_mul_f32 v[192:193], v[196:197], v[192:193]
	v_med3_f32 v169, v169, s85, v226
	v_pk_mul_f32 v[54:55], v[54:55], v[192:193]
	v_lshlrev_b32_e32 v191, 16, v175
	v_and_b32_e32 v193, 0xffff0000, v175
	v_and_b32_e32 v175, 0xffff0000, v176
	v_lshlrev_b32_e32 v192, 16, v167
	v_and_b32_e32 v196, 0xffff0000, v167
	v_lshlrev_b32_e32 v167, 16, v168
	v_exp_f32_e32 v169, v169
	v_fma_f32 v167, v167, s89, v154
	v_fma_f32 v175, v175, s89, v151
	v_med3_f32 v167, v167, s85, v226
	v_med3_f32 v175, v175, s85, v226
	v_and_b32_e32 v197, 0xffff0000, v168
	v_fma_f32 v168, v189, s89, v158
	v_exp_f32_e32 v174, v167
	v_add_f32_e32 v167, 1.0, v169
	v_fma_f32 v169, v190, s89, v159
	v_exp_f32_e32 v189, v175
	v_fma_f32 v190, v191, s89, v160
	v_lshlrev_b32_e32 v194, 16, v177
	v_and_b32_e32 v195, 0xffff0000, v177
	v_lshlrev_b32_e32 v176, 16, v166
	v_and_b32_e32 v177, 0xffff0000, v166
	v_med3_f32 v190, v190, s85, v226
	v_fma_f32 v166, v176, s89, v162
	v_rcp_f32_e32 v176, v167
	v_fma_f32 v167, v177, s89, v163
	v_fma_f32 v177, v197, s89, v155
	v_exp_f32_e32 v191, v190
	v_med3_f32 v175, v177, s85, v226
	v_add_f32_e32 v177, 1.0, v189
	v_fma_f32 v189, v192, s89, v164
	v_med3_f32 v189, v189, s85, v226
	v_exp_f32_e32 v190, v189
	v_add_f32_e32 v189, 1.0, v191
	v_fma_f32 v191, v194, s89, v152
	v_med3_f32 v191, v191, s85, v226
	v_exp_f32_e32 v191, v191
	v_fma_f32 v193, v193, s89, v161
	v_rcp_f32_e32 v192, v189
	v_fma_f32 v189, v227, s89, v156
	v_med3_f32 v168, v168, s85, v226
	v_med3_f32 v169, v169, s85, v226
	v_med3_f32 v193, v193, s85, v226
	v_exp_f32_e32 v168, v168
	v_exp_f32_e32 v169, v169
	v_med3_f32 v189, v189, s85, v226
	v_exp_f32_e32 v193, v193
	v_exp_f32_e32 v194, v189
	v_add_f32_e32 v189, 1.0, v191
	v_fma_f32 v191, v196, s89, v165
	v_med3_f32 v166, v166, s85, v226
	v_med3_f32 v167, v167, s85, v226
	v_med3_f32 v191, v191, s85, v226
	v_exp_f32_e32 v166, v166
	v_add_f32_e32 v168, 1.0, v168
	v_exp_f32_e32 v167, v167
	v_add_f32_e32 v169, 1.0, v169
	v_exp_f32_e32 v191, v191
	v_rcp_f32_e32 v196, v189
	v_add_f32_e32 v189, 1.0, v193
	v_rcp_f32_e32 v168, v168
	v_rcp_f32_e32 v169, v169
	v_rcp_f32_e32 v193, v189
	v_pk_add_f32 v[190:191], v[190:191], 1.0 op_sel_hi:[1,0]
	v_pk_add_f32 v[166:167], v[166:167], 1.0 op_sel_hi:[1,0]
	v_pk_mul_f32 v[166:167], v[168:169], v[166:167]
	v_pk_mul_f32 v[168:169], v[192:193], v[190:191]
	v_pk_mul_f32 v[50:51], v[50:51], v[166:167]
	v_pk_mul_f32 v[52:53], v[52:53], v[168:169]
	v_fma_f32 v169, v195, s89, v153
	v_med3_f32 v169, v169, s85, v226
	v_exp_f32_e32 v169, v169
	v_fma_f32 v168, v228, s89, v157
	v_med3_f32 v168, v168, s85, v226
	v_exp_f32_e32 v195, v168
	v_add_f32_e32 v166, 1.0, v169
	v_rcp_f32_e32 v197, v166
	v_exp_f32_e32 v175, v175
	v_pk_add_f32 v[166:167], v[194:195], 1.0 op_sel_hi:[1,0]
	v_rcp_f32_e32 v177, v177
	v_pk_mul_f32 v[166:167], v[196:197], v[166:167]
; #define UNPK0(q_) ((f32x4){bf_lo((q_).x), bf_hi((q_).x), bf_lo((q_).y), bf_hi((q_).y)})
; #define UNPK1(q_) ((f32x4){bf_lo((q_).z), bf_hi((q_).z), bf_lo((q_).w), bf_hi((q_).w)})
;     static __device__ __forceinline__ float eneg(float g) { return __builtin_amdgcn_exp2f(-1.4426950408889634f * fminf(fmaxf(g, -30.f), 30.f)); }
;     __device__ __forceinline__ void mid(f32x4 (&acc)[2][2][4][2], const Unit& u, int wr, int wc, int fr, int fq) const {
;     ...
;         for (int am = 0; am < 4; ++am) { const int ai = am >> 1;
;             u32x4 ra[4][2], rb[4][2];
; #pragma unroll
;             for (int m = 2 * (am & 1); m < 2 * (am & 1) + 2; ++m) { pa.fetch(ai, m, ra[m][0], ra[m][1]); pb.fetch(ai, m, rb[m][0], rb[m][1]); }
;             asm volatile("" ::: "memory");
; #pragma unroll
;             for (int m = 2 * (am & 1); m < 2 * (am & 1) + 2; ++m) {
;                 pa.stage(ra[m][0], ra[m][1]); const u32x4 ga0 = pa.get(0), ga1 = pa.get(1);
;                 asm volatile("" ::: "memory");
;                 pb.stage(rb[m][0], rb[m][1]); const u32x4 gb0 = pb.get(0), gb1 = pb.get(1);
;                 asm volatile("" ::: "memory");
; #pragma unroll
;                 for (int bj = 0; bj < 2; ++bj) { const u32x4 ga = bj ? ga1 : ga0, gb = bj ? gb1 : gb0;
;                     const f32x4 a0 = UNPK0(ga) + ba[bj][0], a1 = UNPK1(ga) + ba[bj][1], b0 = UNPK0(gb) + bb[bj][0], b1 = UNPK1(gb) + bb[bj][1];
; #pragma unroll
;                     for (int k = 0; k < 4; ++k) { acc[ai][bj][m][0][k] *= (1.0f + eneg(b0[k])) * __builtin_amdgcn_rcpf(1.0f + eneg(a0[k]));
;                                                   acc[ai][bj][m][1][k] *= (1.0f + eneg(b1[k])) * __builtin_amdgcn_rcpf(1.0f + eneg(a1[k])); } } }
	global_load_dwordx4 v[190:193], v[186:187], off nt
	global_load_dwordx4 v[194:197], v[186:187], off offset:1024 nt
	global_load_dwordx4 v[228:231], v[4:5], off nt
	global_load_dwordx4 v[232:235], v[4:5], off offset:1024 nt
	v_pk_add_f32 v[168:169], v[174:175], 1.0 op_sel_hi:[1,0]
	v_pk_mul_f32 v[48:49], v[48:49], v[166:167]
	v_pk_mul_f32 v[168:169], v[176:177], v[168:169]
	v_lshlrev_b32_e32 v166, 16, v178
	v_pk_mul_f32 v[46:47], v[46:47], v[168:169]
	v_lshlrev_b32_e32 v169, 16, v180
	v_fma_f32 v169, v169, s89, v134
	v_and_b32_e32 v167, 0xffff0000, v178
	v_fma_f32 v166, v166, s89, v142
	v_med3_f32 v169, v169, s85, v226
	v_fma_f32 v167, v167, s89, v143
	v_med3_f32 v166, v166, s85, v226
	v_exp_f32_e32 v169, v169
	v_lshlrev_b32_e32 v174, 16, v179
	v_and_b32_e32 v175, 0xffff0000, v179
	v_and_b32_e32 v176, 0xffff0000, v180
	v_lshlrev_b32_e32 v177, 16, v181
	v_and_b32_e32 v179, 0xffff0000, v181
	v_lshlrev_b32_e32 v168, 16, v170
	v_and_b32_e32 v178, 0xffff0000, v170
	v_lshlrev_b32_e32 v180, 16, v171
	v_and_b32_e32 v181, 0xffff0000, v171
	v_lshlrev_b32_e32 v170, 16, v172
	v_and_b32_e32 v171, 0xffff0000, v172
	v_exp_f32_e32 v172, v166
	v_med3_f32 v167, v167, s85, v226
	v_lshlrev_b32_e32 v189, 16, v173
	v_and_b32_e32 v227, 0xffff0000, v173
	v_exp_f32_e32 v173, v167
	v_fma_f32 v177, v177, s89, v136
	v_fma_f32 v174, v174, s89, v144
	v_fma_f32 v175, v175, s89, v145
	v_fma_f32 v168, v168, s89, v146
	v_add_f32_e32 v169, 1.0, v169
	v_med3_f32 v177, v177, s85, v226
	v_med3_f32 v166, v168, s85, v226
	v_add_f32_e32 v168, 1.0, v172
	v_rcp_f32_e32 v172, v169
	v_fma_f32 v169, v178, s89, v147
	v_med3_f32 v174, v174, s85, v226
	v_exp_f32_e32 v177, v177
	v_med3_f32 v175, v175, s85, v226
	v_med3_f32 v167, v169, s85, v226
	v_add_f32_e32 v169, 1.0, v173
	v_fma_f32 v173, v176, s89, v135
	v_fma_f32 v176, v180, s89, v148
	v_exp_f32_e32 v178, v174
	v_fma_f32 v180, v181, s89, v149
	v_exp_f32_e32 v181, v175
	v_med3_f32 v174, v176, s85, v226
	v_add_f32_e32 v177, 1.0, v177
	v_med3_f32 v175, v180, s85, v226
	v_exp_f32_e32 v166, v166
	v_exp_f32_e32 v167, v167
	v_exp_f32_e32 v174, v174
	v_add_f32_e32 v176, 1.0, v178
	v_exp_f32_e32 v175, v175
	v_rcp_f32_e32 v180, v177
	v_add_f32_e32 v177, 1.0, v181
	v_rcp_f32_e32 v168, v168
	v_rcp_f32_e32 v169, v169
	v_rcp_f32_e32 v176, v176
	v_rcp_f32_e32 v177, v177
	v_pk_add_f32 v[174:175], v[174:175], 1.0 op_sel_hi:[1,0]
	v_pk_add_f32 v[166:167], v[166:167], 1.0 op_sel_hi:[1,0]
	v_pk_mul_f32 v[166:167], v[168:169], v[166:167]
	v_pk_mul_f32 v[168:169], v[176:177], v[174:175]
	v_med3_f32 v173, v173, s85, v226
	v_pk_mul_f32 v[44:45], v[44:45], v[168:169]
	v_fma_f32 v169, v179, s89, v137
	v_med3_f32 v169, v169, s85, v226
	v_exp_f32_e32 v173, v173
	v_exp_f32_e32 v169, v169
	v_fma_f32 v170, v170, s89, v138
	v_fma_f32 v171, v171, s89, v139
	v_fma_f32 v178, v189, s89, v140
	v_fma_f32 v168, v227, s89, v141
	v_med3_f32 v170, v170, s85, v226
	v_med3_f32 v171, v171, s85, v226
	v_med3_f32 v178, v178, s85, v226
	v_med3_f32 v168, v168, s85, v226
	v_exp_f32_e32 v170, v170
	v_exp_f32_e32 v171, v171
	v_add_f32_e32 v173, 1.0, v173
	v_exp_f32_e32 v178, v178
	v_exp_f32_e32 v179, v168
	v_pk_mul_f32 v[42:43], v[42:43], v[166:167]
	v_add_f32_e32 v166, 1.0, v169
	v_rcp_f32_e32 v173, v173
	v_rcp_f32_e32 v181, v166
	v_pk_add_f32 v[166:167], v[178:179], 1.0 op_sel_hi:[1,0]
	v_pk_add_f32 v[168:169], v[170:171], 1.0 op_sel_hi:[1,0]
	v_pk_mul_f32 v[166:167], v[180:181], v[166:167]
	v_pk_mul_f32 v[168:169], v[172:173], v[168:169]
	v_pk_mul_f32 v[40:41], v[40:41], v[166:167]
	v_pk_mul_f32 v[38:39], v[38:39], v[168:169]
	global_load_dwordx4 v[174:177], v[186:187], off offset:2048 nt
	global_load_dwordx4 v[178:181], v[186:187], off offset:3072 nt
	global_load_dwordx4 v[166:169], v[4:5], off offset:2048 nt
	global_load_dwordx4 v[170:173], v[4:5], off offset:3072 nt
	s_waitcnt vmcnt(7)
	s_waitcnt vmcnt(6)
	s_waitcnt vmcnt(5)
	s_waitcnt vmcnt(4)
	v_lshlrev_b32_e32 v187, 16, v192
	v_lshlrev_b32_e32 v4, 16, v190
	v_fma_f32 v187, v187, s89, v150
	v_fma_f32 v4, v4, s89, v158
	v_med3_f32 v187, v187, s85, v226
	v_med3_f32 v4, v4, s85, v226
	v_exp_f32_e32 v187, v187
	v_and_b32_e32 v5, 0xffff0000, v190
	v_lshlrev_b32_e32 v189, 16, v191
	v_and_b32_e32 v227, 0xffff0000, v191
	v_and_b32_e32 v191, 0xffff0000, v192
	v_exp_f32_e32 v192, v4
	v_fma_f32 v5, v5, s89, v159
	v_lshlrev_b32_e32 v186, 16, v228
	v_lshlrev_b32_e32 v236, 16, v193
	v_and_b32_e32 v237, 0xffff0000, v193
	v_and_b32_e32 v193, 0xffff0000, v228
	v_fma_f32 v186, v186, s89, v162
	v_add_f32_e32 v187, 1.0, v187
	v_med3_f32 v5, v5, s85, v226
	v_med3_f32 v4, v186, s85, v226
	v_add_f32_e32 v186, 1.0, v192
	v_rcp_f32_e32 v192, v187
	v_fma_f32 v187, v193, s89, v163
	v_exp_f32_e32 v193, v5
	v_fma_f32 v189, v189, s89, v160
	v_fma_f32 v191, v191, s89, v151
	v_med3_f32 v189, v189, s85, v226
	v_lshlrev_b32_e32 v190, 16, v230
	v_and_b32_e32 v230, 0xffff0000, v230
	v_med3_f32 v191, v191, s85, v226
	v_exp_f32_e32 v189, v189
	v_lshlrev_b32_e32 v238, 16, v231
	v_and_b32_e32 v239, 0xffff0000, v231
	v_med3_f32 v5, v187, s85, v226
	v_add_f32_e32 v187, 1.0, v193
	v_fma_f32 v193, v230, s89, v155
	v_exp_f32_e32 v230, v191
	v_fma_f32 v231, v236, s89, v152
	v_fma_f32 v227, v227, s89, v161
	v_med3_f32 v231, v231, s85, v226
	v_add_f32_e32 v189, 1.0, v189
	v_exp_f32_e32 v231, v231
	v_med3_f32 v227, v227, s85, v226
	v_lshlrev_b32_e32 v228, 16, v229
	v_and_b32_e32 v229, 0xffff0000, v229
	v_med3_f32 v191, v193, s85, v226
	v_add_f32_e32 v193, 1.0, v230
	v_rcp_f32_e32 v230, v189
	v_fma_f32 v189, v238, s89, v156
	v_exp_f32_e32 v227, v227
	v_fma_f32 v228, v228, s89, v164
	v_fma_f32 v229, v229, s89, v165
	v_med3_f32 v189, v189, s85, v226
	v_med3_f32 v228, v228, s85, v226
; #define UNPK0(q_) ((f32x4){bf_lo((q_).x), bf_hi((q_).x), bf_lo((q_).y), bf_hi((q_).y)})
; #define UNPK1(q_) ((f32x4){bf_lo((q_).z), bf_hi((q_).z), bf_lo((q_).w), bf_hi((q_).w)})
;     static __device__ __forceinline__ float eneg(float g) { return __builtin_amdgcn_exp2f(-1.4426950408889634f * fminf(fmaxf(g, -30.f), 30.f)); }
;     __device__ __forceinline__ void mid(f32x4 (&acc)[2][2][4][2], const Unit& u, int wr, int wc, int fr, int fq) const {
;     ...
;             for (int m = 2 * (am & 1); m < 2 * (am & 1) + 2; ++m) {
;                 pa.stage(ra[m][0], ra[m][1]); const u32x4 ga0 = pa.get(0), ga1 = pa.get(1);
;                 asm volatile("" ::: "memory");
;                 pb.stage(rb[m][0], rb[m][1]); const u32x4 gb0 = pb.get(0), gb1 = pb.get(1);
;                 asm volatile("" ::: "memory");
; #pragma unroll
;                 for (int bj = 0; bj < 2; ++bj) { const u32x4 ga = bj ? ga1 : ga0, gb = bj ? gb1 : gb0;
;                     const f32x4 a0 = UNPK0(ga) + ba[bj][0], a1 = UNPK1(ga) + ba[bj][1], b0 = UNPK0(gb) + bb[bj][0], b1 = UNPK1(gb) + bb[bj][1];
; #pragma unroll
;                     for (int k = 0; k < 4; ++k) { acc[ai][bj][m][0][k] *= (1.0f + eneg(b0[k])) * __builtin_amdgcn_rcpf(1.0f + eneg(a0[k]));
;                                                   acc[ai][bj][m][1][k] *= (1.0f + eneg(b1[k])) * __builtin_amdgcn_rcpf(1.0f + eneg(a1[k])); } } }
	v_exp_f32_e32 v236, v189
	v_add_f32_e32 v189, 1.0, v231
	v_med3_f32 v229, v229, s85, v226
	v_exp_f32_e32 v4, v4
	v_exp_f32_e32 v5, v5
	v_exp_f32_e32 v228, v228
	v_exp_f32_e32 v229, v229
	v_rcp_f32_e32 v238, v189
	v_add_f32_e32 v189, 1.0, v227
	v_rcp_f32_e32 v186, v186
	v_rcp_f32_e32 v187, v187
	v_rcp_f32_e32 v231, v189
	v_pk_add_f32 v[228:229], v[228:229], 1.0 op_sel_hi:[1,0]
	v_pk_add_f32 v[4:5], v[4:5], 1.0 op_sel_hi:[1,0]
	v_fma_f32 v190, v190, s89, v154
	v_pk_mul_f32 v[4:5], v[186:187], v[4:5]
	v_pk_mul_f32 v[186:187], v[230:231], v[228:229]
	v_pk_mul_f32 v[36:37], v[36:37], v[186:187]
	v_fma_f32 v187, v237, s89, v153
	v_med3_f32 v187, v187, s85, v226
	v_exp_f32_e32 v187, v187
	v_fma_f32 v186, v239, s89, v157
	v_med3_f32 v190, v190, s85, v226
	v_exp_f32_e32 v190, v190
	v_exp_f32_e32 v191, v191
	v_med3_f32 v186, v186, s85, v226
	v_rcp_f32_e32 v193, v193
	v_exp_f32_e32 v237, v186
	v_pk_mul_f32 v[34:35], v[34:35], v[4:5]
	v_add_f32_e32 v4, 1.0, v187
	v_rcp_f32_e32 v239, v4
	v_pk_add_f32 v[186:187], v[190:191], 1.0 op_sel_hi:[1,0]
	v_pk_add_f32 v[4:5], v[236:237], 1.0 op_sel_hi:[1,0]
	v_pk_mul_f32 v[186:187], v[192:193], v[186:187]
	v_pk_mul_f32 v[4:5], v[238:239], v[4:5]
	v_pk_mul_f32 v[30:31], v[30:31], v[186:187]
	v_lshlrev_b32_e32 v187, 16, v196
	v_pk_mul_f32 v[32:33], v[32:33], v[4:5]
	v_lshlrev_b32_e32 v4, 16, v194
	v_fma_f32 v187, v187, s89, v134
	v_fma_f32 v4, v4, s89, v142
	v_med3_f32 v187, v187, s85, v226
	v_med3_f32 v4, v4, s85, v226
	v_exp_f32_e32 v187, v187
	v_and_b32_e32 v5, 0xffff0000, v194
	v_exp_f32_e32 v192, v4
	v_fma_f32 v5, v5, s89, v143
	v_lshlrev_b32_e32 v186, 16, v232
	v_lshlrev_b32_e32 v189, 16, v195
	v_and_b32_e32 v193, 0xffff0000, v232
	v_fma_f32 v186, v186, s89, v146
	v_add_f32_e32 v187, 1.0, v187
	v_med3_f32 v5, v5, s85, v226
	v_and_b32_e32 v191, 0xffff0000, v196
	v_med3_f32 v4, v186, s85, v226
	v_add_f32_e32 v186, 1.0, v192
	v_rcp_f32_e32 v192, v187
	v_fma_f32 v187, v193, s89, v147
	v_exp_f32_e32 v193, v5
	v_fma_f32 v189, v189, s89, v144
	v_fma_f32 v191, v191, s89, v135
	v_med3_f32 v189, v189, s85, v226
	v_lshlrev_b32_e32 v227, 16, v197
	v_and_b32_e32 v196, 0xffff0000, v234
	v_med3_f32 v191, v191, s85, v226
	v_exp_f32_e32 v189, v189
	v_med3_f32 v5, v187, s85, v226
	v_add_f32_e32 v187, 1.0, v193
	v_fma_f32 v193, v196, s89, v139
	v_exp_f32_e32 v196, v191
	v_fma_f32 v227, v227, s89, v136
	v_med3_f32 v227, v227, s85, v226
	v_and_b32_e32 v195, 0xffff0000, v195
	v_lshlrev_b32_e32 v228, 16, v235
	v_add_f32_e32 v189, 1.0, v189
	v_exp_f32_e32 v227, v227
	v_med3_f32 v191, v193, s85, v226
	v_add_f32_e32 v193, 1.0, v196
	v_rcp_f32_e32 v196, v189
	v_fma_f32 v189, v228, s89, v140
	v_fma_f32 v195, v195, s89, v145
	v_med3_f32 v189, v189, s85, v226
	v_med3_f32 v195, v195, s85, v226
	v_and_b32_e32 v229, 0xffff0000, v197
	v_lshlrev_b32_e32 v194, 16, v233
	v_and_b32_e32 v197, 0xffff0000, v233
	v_exp_f32_e32 v228, v189
	v_add_f32_e32 v189, 1.0, v227
	v_exp_f32_e32 v227, v195
	v_fma_f32 v194, v194, s89, v148
	v_fma_f32 v197, v197, s89, v149
	v_med3_f32 v194, v194, s85, v226
	v_med3_f32 v195, v197, s85, v226
	v_exp_f32_e32 v4, v4
	v_exp_f32_e32 v5, v5
	v_exp_f32_e32 v194, v194
	v_exp_f32_e32 v195, v195
	v_rcp_f32_e32 v230, v189
	v_add_f32_e32 v189, 1.0, v227
	v_rcp_f32_e32 v186, v186
	v_rcp_f32_e32 v187, v187
	v_rcp_f32_e32 v197, v189
	v_pk_add_f32 v[194:195], v[194:195], 1.0 op_sel_hi:[1,0]
	v_pk_add_f32 v[4:5], v[4:5], 1.0 op_sel_hi:[1,0]
	v_lshlrev_b32_e32 v190, 16, v234
	v_pk_mul_f32 v[4:5], v[186:187], v[4:5]
	v_pk_mul_f32 v[186:187], v[196:197], v[194:195]
	s_waitcnt vmcnt(3)
	s_waitcnt vmcnt(2)
	v_fma_f32 v190, v190, s89, v138
	v_pk_mul_f32 v[28:29], v[28:29], v[186:187]
	v_fma_f32 v187, v229, s89, v137
	v_med3_f32 v190, v190, s85, v226
	v_med3_f32 v187, v187, s85, v226
	v_and_b32_e32 v231, 0xffff0000, v235
	v_exp_f32_e32 v190, v190
	v_exp_f32_e32 v191, v191
	v_exp_f32_e32 v187, v187
	v_rcp_f32_e32 v193, v193
	v_fma_f32 v186, v231, s89, v141
	s_waitcnt vmcnt(1)
	s_waitcnt vmcnt(0)
; #define UNPK0(q_) ((f32x4){bf_lo((q_).x), bf_hi((q_).x), bf_lo((q_).y), bf_hi((q_).y)})
; #define UNPK1(q_) ((f32x4){bf_lo((q_).z), bf_hi((q_).z), bf_lo((q_).w), bf_hi((q_).w)})
;     static __device__ __forceinline__ float eneg(float g) { return __builtin_amdgcn_exp2f(-1.4426950408889634f * fminf(fmaxf(g, -30.f), 30.f)); }
;     __device__ __forceinline__ void mid(f32x4 (&acc)[2][2][4][2], const Unit& u, int wr, int wc, int fr, int fq) const {
;     ...
;             for (int m = 2 * (am & 1); m < 2 * (am & 1) + 2; ++m) {
;                 pa.stage(ra[m][0], ra[m][1]); const u32x4 ga0 = pa.get(0), ga1 = pa.get(1);
;                 asm volatile("" ::: "memory");
;                 pb.stage(rb[m][0], rb[m][1]); const u32x4 gb0 = pb.get(0), gb1 = pb.get(1);
;                 asm volatile("" ::: "memory");
; #pragma unroll
;                 for (int bj = 0; bj < 2; ++bj) { const u32x4 ga = bj ? ga1 : ga0, gb = bj ? gb1 : gb0;
;                     const f32x4 a0 = UNPK0(ga) + ba[bj][0], a1 = UNPK1(ga) + ba[bj][1], b0 = UNPK0(gb) + bb[bj][0], b1 = UNPK1(gb) + bb[bj][1];
; #pragma unroll
;                     for (int k = 0; k < 4; ++k) { acc[ai][bj][m][0][k] *= (1.0f + eneg(b0[k])) * __builtin_amdgcn_rcpf(1.0f + eneg(a0[k]));
;                                                   acc[ai][bj][m][1][k] *= (1.0f + eneg(b1[k])) * __builtin_amdgcn_rcpf(1.0f + eneg(a1[k])); } } }
	v_lshlrev_b32_e32 v3, 16, v174
	v_fma_f32 v3, v3, s89, v158
	v_med3_f32 v186, v186, s85, v226
	v_exp_f32_e32 v229, v186
	v_pk_mul_f32 v[26:27], v[26:27], v[4:5]
	v_add_f32_e32 v4, 1.0, v187
	v_pk_add_f32 v[186:187], v[190:191], 1.0 op_sel_hi:[1,0]
	v_med3_f32 v3, v3, s85, v226
	v_rcp_f32_e32 v231, v4
	v_pk_mul_f32 v[186:187], v[192:193], v[186:187]
	v_exp_f32_e32 v3, v3
	v_pk_mul_f32 v[22:23], v[22:23], v[186:187]
	v_lshlrev_b32_e32 v186, 16, v176
	v_fma_f32 v150, v186, s89, v150
	v_pk_add_f32 v[4:5], v[228:229], 1.0 op_sel_hi:[1,0]
	v_pk_mul_f32 v[4:5], v[230:231], v[4:5]
	v_lshlrev_b32_e32 v189, 16, v168
	v_add_f32_e32 v3, 1.0, v3
	v_med3_f32 v150, v150, s85, v226
	v_pk_mul_f32 v[24:25], v[24:25], v[4:5]
	v_and_b32_e32 v5, 0xffff0000, v174
	v_rcp_f32_e32 v158, v3
	v_fma_f32 v3, v189, s89, v154
	v_exp_f32_e32 v154, v150
	v_fma_f32 v5, v5, s89, v159
	v_med3_f32 v3, v3, s85, v226
	v_med3_f32 v5, v5, s85, v226
	v_lshlrev_b32_e32 v4, 16, v166
	v_and_b32_e32 v166, 0xffff0000, v166
	v_exp_f32_e32 v150, v3
	v_add_f32_e32 v3, 1.0, v154
	v_exp_f32_e32 v159, v5
	v_and_b32_e32 v176, 0xffff0000, v176
	v_rcp_f32_e32 v154, v3
	v_fma_f32 v3, v166, s89, v163
	v_fma_f32 v151, v176, s89, v151
	v_med3_f32 v3, v3, s85, v226
	v_and_b32_e32 v168, 0xffff0000, v168
	v_exp_f32_e32 v5, v3
	v_add_f32_e32 v3, 1.0, v159
	v_med3_f32 v151, v151, s85, v226
	v_lshlrev_b32_e32 v174, 16, v175
	v_rcp_f32_e32 v159, v3
	v_fma_f32 v3, v168, s89, v155
	v_exp_f32_e32 v155, v151
	v_fma_f32 v160, v174, s89, v160
	v_med3_f32 v3, v3, s85, v226
	v_med3_f32 v160, v160, s85, v226
	v_lshlrev_b32_e32 v188, 16, v167
	v_fma_f32 v4, v4, s89, v162
	v_exp_f32_e32 v151, v3
	v_add_f32_e32 v3, 1.0, v155
	v_exp_f32_e32 v162, v160
	v_lshlrev_b32_e32 v187, 16, v177
	v_rcp_f32_e32 v155, v3
	v_fma_f32 v3, v188, s89, v164
	v_fma_f32 v152, v187, s89, v152
	v_med3_f32 v3, v3, s85, v226
	v_and_b32_e32 v175, 0xffff0000, v175
	v_lshlrev_b32_e32 v190, 16, v169
	v_exp_f32_e32 v160, v3
	v_add_f32_e32 v3, 1.0, v162
	v_med3_f32 v152, v152, s85, v226
	v_rcp_f32_e32 v162, v3
	v_fma_f32 v3, v190, s89, v156
	v_exp_f32_e32 v156, v152
	v_fma_f32 v161, v175, s89, v161
	v_med3_f32 v161, v161, s85, v226
	v_and_b32_e32 v167, 0xffff0000, v167
	v_med3_f32 v3, v3, s85, v226
	v_exp_f32_e32 v163, v161
	v_and_b32_e32 v177, 0xffff0000, v177
	v_exp_f32_e32 v152, v3
	v_add_f32_e32 v3, 1.0, v156
	v_fma_f32 v156, v167, s89, v165
	v_fma_f32 v153, v177, s89, v153
	v_med3_f32 v156, v156, s85, v226
	v_and_b32_e32 v169, 0xffff0000, v169
	v_exp_f32_e32 v161, v156
	v_rcp_f32_e32 v156, v3
	v_add_f32_e32 v3, 1.0, v163
	v_med3_f32 v153, v153, s85, v226
	v_rcp_f32_e32 v163, v3
	v_fma_f32 v3, v169, s89, v157
	v_exp_f32_e32 v157, v153
	v_med3_f32 v4, v4, s85, v226
	v_med3_f32 v3, v3, s85, v226
	v_exp_f32_e32 v4, v4
	v_exp_f32_e32 v153, v3
	v_add_f32_e32 v3, 1.0, v157
	v_rcp_f32_e32 v157, v3
	v_lshlrev_b32_e32 v3, 16, v178
	v_fma_f32 v3, v3, s89, v142
	v_pk_add_f32 v[4:5], v[4:5], 1.0 op_sel_hi:[1,0]
	v_med3_f32 v3, v3, s85, v226
	v_pk_mul_f32 v[4:5], v[158:159], v[4:5]
	v_exp_f32_e32 v3, v3
	v_pk_mul_f32 v[18:19], v[18:19], v[4:5]
	v_pk_add_f32 v[4:5], v[152:153], 1.0 op_sel_hi:[1,0]
	v_lshlrev_b32_e32 v152, 16, v180
	v_pk_add_f32 v[160:161], v[160:161], 1.0 op_sel_hi:[1,0]
	v_fma_f32 v134, v152, s89, v134
	v_pk_mul_f32 v[158:159], v[162:163], v[160:161]
	v_pk_mul_f32 v[20:21], v[20:21], v[158:159]
	v_pk_mul_f32 v[4:5], v[156:157], v[4:5]
	v_lshlrev_b32_e32 v159, 16, v172
	v_add_f32_e32 v3, 1.0, v3
	v_med3_f32 v134, v134, s85, v226
	v_pk_mul_f32 v[16:17], v[16:17], v[4:5]
	v_and_b32_e32 v5, 0xffff0000, v178
	v_rcp_f32_e32 v142, v3
	v_fma_f32 v3, v159, s89, v138
	v_exp_f32_e32 v138, v134
	v_fma_f32 v5, v5, s89, v143
	v_med3_f32 v3, v3, s85, v226
	v_med3_f32 v5, v5, s85, v226
	v_and_b32_e32 v156, 0xffff0000, v170
	v_exp_f32_e32 v134, v3
	v_add_f32_e32 v3, 1.0, v138
	v_exp_f32_e32 v143, v5
	v_and_b32_e32 v153, 0xffff0000, v180
	v_rcp_f32_e32 v138, v3
	v_fma_f32 v3, v156, s89, v147
	v_fma_f32 v135, v153, s89, v135
	v_pk_add_f32 v[150:151], v[150:151], 1.0 op_sel_hi:[1,0]
	v_med3_f32 v3, v3, s85, v226
	v_pk_mul_f32 v[150:151], v[154:155], v[150:151]
	v_and_b32_e32 v160, 0xffff0000, v172
	v_exp_f32_e32 v5, v3
	v_add_f32_e32 v3, 1.0, v143
	v_med3_f32 v135, v135, s85, v226
	v_pk_mul_f32 v[14:15], v[14:15], v[150:151]
	v_lshlrev_b32_e32 v150, 16, v179
	v_rcp_f32_e32 v143, v3
	v_fma_f32 v3, v160, s89, v139
	v_exp_f32_e32 v139, v135
	v_fma_f32 v144, v150, s89, v144
	v_lshlrev_b32_e32 v4, 16, v170
	v_med3_f32 v3, v3, s85, v226
	v_med3_f32 v144, v144, s85, v226
	v_lshlrev_b32_e32 v157, 16, v171
	v_fma_f32 v4, v4, s89, v146
	v_exp_f32_e32 v135, v3
	v_add_f32_e32 v3, 1.0, v139
	v_exp_f32_e32 v146, v144
	v_lshlrev_b32_e32 v154, 16, v181
	v_rcp_f32_e32 v139, v3
	v_fma_f32 v3, v157, s89, v148
	v_fma_f32 v136, v154, s89, v136
	v_med3_f32 v3, v3, s85, v226
	v_and_b32_e32 v151, 0xffff0000, v179
	v_lshlrev_b32_e32 v161, 16, v173
	v_exp_f32_e32 v144, v3
	v_add_f32_e32 v3, 1.0, v146
	v_med3_f32 v136, v136, s85, v226
	v_rcp_f32_e32 v146, v3
	v_fma_f32 v3, v161, s89, v140
	v_exp_f32_e32 v140, v136
	v_fma_f32 v145, v151, s89, v145
	v_med3_f32 v145, v145, s85, v226
	v_and_b32_e32 v158, 0xffff0000, v171
	v_med3_f32 v3, v3, s85, v226
	v_exp_f32_e32 v147, v145
	v_and_b32_e32 v155, 0xffff0000, v181
	v_exp_f32_e32 v136, v3
	v_add_f32_e32 v3, 1.0, v140
	v_fma_f32 v140, v158, s89, v149
	v_fma_f32 v137, v155, s89, v137
	v_med3_f32 v140, v140, s85, v226
	v_and_b32_e32 v162, 0xffff0000, v173
	v_exp_f32_e32 v145, v140
	v_rcp_f32_e32 v140, v3
	v_add_f32_e32 v3, 1.0, v147
	v_med3_f32 v137, v137, s85, v226
	v_rcp_f32_e32 v147, v3
	v_fma_f32 v3, v162, s89, v141
	v_exp_f32_e32 v141, v137
	v_med3_f32 v4, v4, s85, v226
	v_exp_f32_e32 v4, v4
	v_med3_f32 v3, v3, s85, v226
	v_exp_f32_e32 v137, v3
	v_add_f32_e32 v3, 1.0, v141
	v_rcp_f32_e32 v141, v3
	v_pk_add_f32 v[4:5], v[4:5], 1.0 op_sel_hi:[1,0]
	v_pk_add_f32 v[144:145], v[144:145], 1.0 op_sel_hi:[1,0]
	v_pk_mul_f32 v[4:5], v[142:143], v[4:5]
	v_pk_add_f32 v[134:135], v[134:135], 1.0 op_sel_hi:[1,0]
	v_pk_mul_f32 v[10:11], v[10:11], v[4:5]
	v_pk_add_f32 v[4:5], v[136:137], 1.0 op_sel_hi:[1,0]
	v_pk_mul_f32 v[142:143], v[146:147], v[144:145]
	v_pk_mul_f32 v[134:135], v[138:139], v[134:135]
	v_pk_mul_f32 v[4:5], v[140:141], v[4:5]
	v_pk_mul_f32 v[12:13], v[12:13], v[142:143]
	v_pk_mul_f32 v[8:9], v[8:9], v[4:5]
	v_pk_mul_f32 v[6:7], v[6:7], v[134:135]
	s_branch .LBB0_380

; __device__ __forceinline__ size_t tm_block(int pm, int ct, int nct) { return ((size_t)pm * nct + ct) * 32768; }
; __device__ __forceinline__ u32x4 pack8(const f32x4& v0, const f32x4& v1) { u32x4 w; w.x = cvt_pk_bf16(v0[0], v0[1]); w.y = cvt_pk_bf16(v0[2], v0[3]); w.z = cvt_pk_bf16(v1[0], v1[1]); w.w = cvt_pk_bf16(v1[2], v1[3]); return w; }
; #define UNPK0(q_) ((f32x4){bf_lo((q_).x), bf_hi((q_).x), bf_lo((q_).y), bf_hi((q_).y)})
; #define UNPK1(q_) ((f32x4){bf_lo((q_).z), bf_hi((q_).z), bf_lo((q_).w), bf_hi((q_).w)})
;     static __device__ __forceinline__ float eneg(float g) { return __builtin_amdgcn_exp2f(-1.4426950408889634f * fminf(fmaxf(g, -30.f), 30.f)); }
;     __device__ __forceinline__ void operator()(const f32x4 (&acc)[2][2][4][2], const Unit& u, int wr, int wc, int fr, int fq) const {
;         const int cb = u.pn * 4 + wc, col0 = cb * 64 + 8 * fq;
;         const PieceOut po(scr, O, tm_block(u.pm, cb, 16), wr, wc, fr, fq);
;         const PieceIn pb(scr, Z, tm_block(u.pm, gb_ct + cb, znct), wr, wc, fr, fq);
;         f32x4 bb[2][2];
; #pragma unroll
;         for (int bj = 0; bj < 2; ++bj) { bb[bj][0] = *(const f32x4*)(bg + 1024 + col0 + bj * 32); bb[bj][1] = *(const f32x4*)(bg + 1024 + col0 + bj * 32 + 4); }
;         u32x4 rb[2][4][2];
; #pragma unroll
;         for (int ai = 0; ai < 2; ++ai)
; #pragma unroll
;             for (int m = 0; m < 4; ++m) pb.fetch(ai, m, rb[ai][m][0], rb[ai][m][1]);
;         asm volatile("" ::: "memory");
; #pragma unroll
;         for (int ai = 0; ai < 2; ++ai)
; #pragma unroll
;             for (int m = 0; m < 4; ++m) {
;                 pb.stage(rb[ai][m][0], rb[ai][m][1]); const u32x4 gb0 = pb.get(0), gb1 = pb.get(1);
;                 asm volatile("" ::: "memory");
; #pragma unroll
;                 for (int bj = 0; bj < 2; ++bj) { const u32x4 gb = bj ? gb1 : gb0;
;                     const f32x4 b0 = UNPK0(gb) + bb[bj][0], b1 = UNPK1(gb) + bb[bj][1];
;                     f32x4 v0 = acc[ai][bj][m][0], v1 = acc[ai][bj][m][1];
; #pragma unroll
;                     for (int k = 0; k < 4; ++k) { v0[k] *= __builtin_amdgcn_rcpf(1.0f + eneg(b0[k])); v1[k] *= __builtin_amdgcn_rcpf(1.0f + eneg(b1[k])); }
;                     po.put(bj, pack8(v0, v1)); }
;                 po.flush<false>(ai, m);
.LBB0_385:
	s_ashr_i32 s27, s26, 31
	s_lshl_b64 s[0:1], s[26:27], 19
	s_add_u32 s19, s3, s0
	s_addc_u32 s21, s76, s1
	s_add_i32 s0, s44, 52
	s_mul_hi_i32 s1, s26, 0x44
	s_mulk_i32 s26, 0x44
	s_ashr_i32 s27, s0, 31
	s_add_u32 s0, s26, s0
	s_addc_u32 s1, s1, s27
	s_lshl_b64 s[0:1], s[0:1], 15
	v_lshl_add_u64 v[4:5], v[208:209], 0, s[0:1]
	global_load_dwordx4 v[228:231], v[4:5], off nt
	global_load_dwordx4 v[232:235], v[4:5], off offset:1024 nt
	v_lshl_or_b32 v134, s44, 6, v219
	v_ashrrev_i32_e32 v135, 31, v134
	v_lshlrev_b64 v[134:135], 2, v[134:135]
	v_lshl_add_u64 v[136:137], s[16:17], 0, v[134:135]
	v_lshl_add_u64 v[134:135], s[42:43], 0, v[134:135]
	v_add_co_u32_e32 v134, vcc, s84, v134
	global_load_dwordx4 v[146:149], v[136:137], off
	s_nop 0
	v_addc_co_u32_e32 v135, vcc, 0, v135, vcc
	global_load_dwordx4 v[142:145], v[134:135], off offset:16
	global_load_dwordx4 v[138:141], v[136:137], off offset:128
	s_nop 0
	global_load_dwordx4 v[134:137], v[134:135], off offset:144
	s_nop 0
	global_load_dwordx4 v[236:239], v[4:5], off offset:2048 nt
	global_load_dwordx4 v[240:243], v[4:5], off offset:3072 nt
	v_add_co_u32_e32 v150, vcc, s84, v4
	v_add_u32_e32 v3, v224, v222
	s_nop 0
	v_addc_co_u32_e32 v151, vcc, 0, v5, vcc
	v_add_co_u32_e32 v152, vcc, s79, v4
	v_add_u32_e32 v227, v223, v220
	s_nop 0
	v_addc_co_u32_e32 v153, vcc, 0, v5, vcc
	v_add_co_u32_e32 v4, vcc, s86, v4
	s_ashr_i32 s45, s44, 31
	s_nop 0
	v_addc_co_u32_e32 v5, vcc, 0, v5, vcc
	global_load_dwordx4 v[190:193], v[150:151], off nt
	global_load_dwordx4 v[194:197], v[150:151], off offset:1024 nt
	global_load_dwordx4 v[182:185], v[150:151], off offset:2048 nt
	global_load_dwordx4 v[186:189], v[150:151], off offset:3072 nt
	global_load_dwordx4 v[174:177], v[152:153], off offset:1024 nt
	global_load_dwordx4 v[166:169], v[152:153], off offset:2048 nt
	global_load_dwordx4 v[178:181], v[4:5], off offset:-4096 nt
	global_load_dwordx4 v[170:173], v[152:153], off offset:3072 nt
	global_load_dwordx4 v[158:161], v[4:5], off
	global_load_dwordx4 v[162:165], v[4:5], off offset:1024
	s_nop 0
	global_load_dwordx4 v[150:153], v[4:5], off offset:2048
	global_load_dwordx4 v[154:157], v[4:5], off offset:3072
	s_lshl_b64 s[0:1], s[44:45], 15
	s_add_u32 s0, s19, s0
	s_addc_u32 s1, s21, s1
	s_add_u32 s0, s0, s12
	s_addc_u32 s1, s1, s13
	s_waitcnt vmcnt(0)
	v_mul_f32_e32 v134, 0xbfb8aa3b, v134
	v_mul_f32_e32 v135, 0xbfb8aa3b, v135
	v_mul_f32_e32 v136, 0xbfb8aa3b, v136
	v_mul_f32_e32 v137, 0xbfb8aa3b, v137
	v_mul_f32_e32 v138, 0xbfb8aa3b, v138
	v_mul_f32_e32 v139, 0xbfb8aa3b, v139
	v_mul_f32_e32 v140, 0xbfb8aa3b, v140
	v_mul_f32_e32 v141, 0xbfb8aa3b, v141
	v_mul_f32_e32 v142, 0xbfb8aa3b, v142
	v_mul_f32_e32 v143, 0xbfb8aa3b, v143
	v_mul_f32_e32 v144, 0xbfb8aa3b, v144
	v_mul_f32_e32 v145, 0xbfb8aa3b, v145
	v_mul_f32_e32 v146, 0xbfb8aa3b, v146
	v_mul_f32_e32 v147, 0xbfb8aa3b, v147
	v_mul_f32_e32 v148, 0xbfb8aa3b, v148
	v_mul_f32_e32 v149, 0xbfb8aa3b, v149
	v_lshlrev_b32_e32 v4, 16, v228
	v_lshlrev_b32_e32 v244, 16, v230
	v_fma_f32 v4, v4, s89, v146
	v_med3_f32 v4, v4, s85, v226
	v_fma_f32 v244, v244, s89, v142
	v_med3_f32 v244, v244, s85, v226
	v_exp_f32_e32 v4, v4
	v_exp_f32_e32 v244, v244
	v_and_b32_e32 v5, 0xffff0000, v228
	v_lshlrev_b32_e32 v228, 16, v229
	v_fma_f32 v228, v228, s89, v148
	v_and_b32_e32 v230, 0xffff0000, v230
	v_fma_f32 v5, v5, s89, v147
	v_fma_f32 v230, v230, s89, v143
	v_med3_f32 v228, v228, s85, v226
	v_add_f32_e32 v4, 1.0, v4
	v_add_f32_e32 v244, 1.0, v244
	v_exp_f32_e32 v228, v228
	v_rcp_f32_e32 v4, v4
	v_rcp_f32_e32 v244, v244
	v_med3_f32 v5, v5, s85, v226
	v_med3_f32 v230, v230, s85, v226
	v_exp_f32_e32 v5, v5
	v_exp_f32_e32 v230, v230
	v_and_b32_e32 v229, 0xffff0000, v229
	v_lshlrev_b32_e32 v245, 16, v231
	v_and_b32_e32 v231, 0xffff0000, v231
	v_fma_f32 v245, v245, s89, v144
	v_mul_f32_e32 v4, v130, v4
	v_mul_f32_e32 v130, v126, v244
	v_add_f32_e32 v126, 1.0, v228
	v_fma_f32 v228, v229, s89, v149
	v_fma_f32 v229, v231, s89, v145
	v_med3_f32 v245, v245, s85, v226
	v_add_f32_e32 v5, 1.0, v5
	v_add_f32_e32 v230, 1.0, v230
	v_med3_f32 v228, v228, s85, v226
	v_exp_f32_e32 v245, v245
	v_rcp_f32_e32 v5, v5
	v_rcp_f32_e32 v230, v230
	v_exp_f32_e32 v228, v228
	v_med3_f32 v229, v229, s85, v226
	v_exp_f32_e32 v229, v229
	v_mul_f32_e32 v5, v131, v5
	v_mul_f32_e32 v131, v127, v230
	v_add_f32_e32 v127, 1.0, v245
	v_add_f32_e32 v228, 1.0, v228
	v_rcp_f32_e32 v126, v126
	v_rcp_f32_e32 v127, v127
	v_rcp_f32_e32 v228, v228
	v_add_f32_e32 v229, 1.0, v229
	v_rcp_f32_e32 v229, v229
	v_mul_f32_e32 v132, v132, v126
	v_mul_f32_e32 v230, v128, v127
	v_mul_f32_e32 v127, v133, v228
	v_cvt_pk_bf16_f32 v126, v4, v5
	v_and_b32_e32 v5, 0xffff0000, v232
	v_mul_f32_e32 v129, v129, v229
	v_cvt_pk_bf16_f32 v127, v132, v127
	v_cvt_pk_bf16_f32 v128, v130, v131
	v_fma_f32 v5, v5, s89, v139
	v_cvt_pk_bf16_f32 v129, v230, v129
	ds_write_b128 v227, v[126:129]
	v_lshlrev_b32_e32 v4, 16, v232
	v_lshlrev_b32_e32 v128, 16, v234
	v_fma_f32 v4, v4, s89, v138
	v_fma_f32 v128, v128, s89, v134
	v_med3_f32 v5, v5, s85, v226
	v_exp_f32_e32 v5, v5
	v_med3_f32 v4, v4, s85, v226
	v_med3_f32 v128, v128, s85, v226
	v_exp_f32_e32 v4, v4
	v_exp_f32_e32 v128, v128
	v_and_b32_e32 v129, 0xffff0000, v234
	v_add_f32_e32 v5, 1.0, v5
	v_fma_f32 v129, v129, s89, v135
	v_rcp_f32_e32 v5, v5
	v_add_f32_e32 v4, 1.0, v4
	v_add_f32_e32 v128, 1.0, v128
	v_med3_f32 v129, v129, s85, v226
	v_rcp_f32_e32 v4, v4
	v_rcp_f32_e32 v128, v128
	v_exp_f32_e32 v129, v129
	v_lshlrev_b32_e32 v126, 16, v233
	v_lshlrev_b32_e32 v130, 16, v235
	v_mul_f32_e32 v5, v123, v5
	v_fma_f32 v123, v126, s89, v140
	v_fma_f32 v126, v130, s89, v136
	v_mul_f32_e32 v4, v122, v4
	v_mul_f32_e32 v122, v118, v128
	v_add_f32_e32 v118, 1.0, v129
	v_med3_f32 v123, v123, s85, v226
	v_med3_f32 v126, v126, s85, v226
	v_rcp_f32_e32 v118, v118
	v_exp_f32_e32 v123, v123
	v_exp_f32_e32 v126, v126
	v_and_b32_e32 v127, 0xffff0000, v233
	v_and_b32_e32 v131, 0xffff0000, v235
	v_mul_f32_e32 v128, v119, v118
	v_add_f32_e32 v118, 1.0, v123
	v_add_f32_e32 v119, 1.0, v126
	v_fma_f32 v123, v127, s89, v141
	v_fma_f32 v126, v131, s89, v137
	v_med3_f32 v123, v123, s85, v226
	v_med3_f32 v126, v126, s85, v226
	v_exp_f32_e32 v123, v123
	v_exp_f32_e32 v126, v126
	v_rcp_f32_e32 v119, v119
	v_rcp_f32_e32 v118, v118
	v_add_f32_e32 v123, 1.0, v123
	v_add_f32_e32 v126, 1.0, v126
	v_rcp_f32_e32 v123, v123
	v_rcp_f32_e32 v126, v126
	v_mul_f32_e32 v127, v120, v119
	v_mul_f32_e32 v124, v124, v118
	v_mul_f32_e32 v119, v125, v123
	v_mul_f32_e32 v121, v121, v126
	v_cvt_pk_bf16_f32 v118, v4, v5
	v_cvt_pk_bf16_f32 v119, v124, v119
	v_cvt_pk_bf16_f32 v120, v122, v128
	v_cvt_pk_bf16_f32 v121, v127, v121
	ds_write_b128 v227, v[118:121] offset:64
	ds_read_b128 v[118:121], v3
	ds_read_b128 v[122:125], v3 offset:1152
	v_lshl_add_u64 v[4:5], s[0:1], 0, v[206:207]
	s_waitcnt lgkmcnt(1)
; __device__ __forceinline__ u32x4 pack8(const f32x4& v0, const f32x4& v1) { u32x4 w; w.x = cvt_pk_bf16(v0[0], v0[1]); w.y = cvt_pk_bf16(v0[2], v0[3]); w.z = cvt_pk_bf16(v1[0], v1[1]); w.w = cvt_pk_bf16(v1[2], v1[3]); return w; }
; #define UNPK0(q_) ((f32x4){bf_lo((q_).x), bf_hi((q_).x), bf_lo((q_).y), bf_hi((q_).y)})
; #define UNPK1(q_) ((f32x4){bf_lo((q_).z), bf_hi((q_).z), bf_lo((q_).w), bf_hi((q_).w)})
;     static __device__ __forceinline__ float eneg(float g) { return __builtin_amdgcn_exp2f(-1.4426950408889634f * fminf(fmaxf(g, -30.f), 30.f)); }
;     __device__ __forceinline__ void operator()(const f32x4 (&acc)[2][2][4][2], const Unit& u, int wr, int wc, int fr, int fq) const {
;     ...
; #pragma unroll
;         for (int ai = 0; ai < 2; ++ai)
; #pragma unroll
;             for (int m = 0; m < 4; ++m) {
;                 pb.stage(rb[ai][m][0], rb[ai][m][1]); const u32x4 gb0 = pb.get(0), gb1 = pb.get(1);
;                 asm volatile("" ::: "memory");
; #pragma unroll
;                 for (int bj = 0; bj < 2; ++bj) { const u32x4 gb = bj ? gb1 : gb0;
;                     const f32x4 b0 = UNPK0(gb) + bb[bj][0], b1 = UNPK1(gb) + bb[bj][1];
;                     f32x4 v0 = acc[ai][bj][m][0], v1 = acc[ai][bj][m][1];
; #pragma unroll
;                     for (int k = 0; k < 4; ++k) { v0[k] *= __builtin_amdgcn_rcpf(1.0f + eneg(b0[k])); v1[k] *= __builtin_amdgcn_rcpf(1.0f + eneg(b1[k])); }
;                     po.put(bj, pack8(v0, v1)); }
;                 po.flush<false>(ai, m);
;                 asm volatile("" ::: "memory"); }
	global_store_dwordx4 v[4:5], v[118:121], off
	s_waitcnt lgkmcnt(0)
	global_store_dwordx4 v[4:5], v[122:125], off offset:1024
	v_mov_b64_e32 v[118:119], v[236:237]
	v_mov_b64_e32 v[120:121], v[238:239]
	v_mov_b64_e32 v[122:123], v[240:241]
	v_mov_b64_e32 v[124:125], v[242:243]
	s_waitcnt lgkmcnt(0)
	v_lshlrev_b32_e32 v126, 16, v118
	v_and_b32_e32 v118, 0xffff0000, v118
	v_lshlrev_b32_e32 v128, 16, v120
	v_fma_f32 v126, v126, s89, v146
	v_fma_f32 v128, v128, s89, v142
	v_fma_f32 v118, v118, s89, v147
	v_med3_f32 v126, v126, s85, v226
	v_med3_f32 v128, v128, s85, v226
	v_med3_f32 v118, v118, s85, v226
	v_exp_f32_e32 v126, v126
	v_exp_f32_e32 v128, v128
	v_exp_f32_e32 v118, v118
	v_and_b32_e32 v120, 0xffff0000, v120
	v_fma_f32 v120, v120, s89, v143
	v_add_f32_e32 v126, 1.0, v126
	v_add_f32_e32 v128, 1.0, v128
	v_add_f32_e32 v118, 1.0, v118
	v_med3_f32 v120, v120, s85, v226
	v_rcp_f32_e32 v126, v126
	v_rcp_f32_e32 v128, v128
	v_rcp_f32_e32 v118, v118
	v_exp_f32_e32 v120, v120
	v_lshlrev_b32_e32 v127, 16, v119
	v_lshlrev_b32_e32 v129, 16, v121
	v_mul_f32_e32 v114, v114, v126
	v_mul_f32_e32 v126, v110, v128
	v_mul_f32_e32 v110, v115, v118
	v_add_f32_e32 v115, 1.0, v120
	v_fma_f32 v118, v127, s89, v148
	v_fma_f32 v120, v129, s89, v144
	v_med3_f32 v118, v118, s85, v226
	v_med3_f32 v120, v120, s85, v226
	v_rcp_f32_e32 v115, v115
	v_exp_f32_e32 v118, v118
	v_exp_f32_e32 v120, v120
	v_and_b32_e32 v119, 0xffff0000, v119
	v_and_b32_e32 v121, 0xffff0000, v121
	v_mul_f32_e32 v115, v111, v115
	v_add_f32_e32 v111, 1.0, v118
	v_add_f32_e32 v118, 1.0, v120
	v_fma_f32 v119, v119, s89, v149
	v_fma_f32 v120, v121, s89, v145
	v_med3_f32 v119, v119, s85, v226
	v_med3_f32 v120, v120, s85, v226
	v_exp_f32_e32 v119, v119
	v_exp_f32_e32 v120, v120
	v_rcp_f32_e32 v111, v111
	v_rcp_f32_e32 v118, v118
	v_add_f32_e32 v119, 1.0, v119
	v_add_f32_e32 v120, 1.0, v120
	v_rcp_f32_e32 v119, v119
	v_rcp_f32_e32 v120, v120
	v_mul_f32_e32 v111, v116, v111
	v_mul_f32_e32 v116, v112, v118
	v_mul_f32_e32 v112, v117, v119
	v_mul_f32_e32 v113, v113, v120
	v_cvt_pk_bf16_f32 v110, v114, v110
	v_cvt_pk_bf16_f32 v111, v111, v112
	v_cvt_pk_bf16_f32 v112, v126, v115
	v_cvt_pk_bf16_f32 v113, v116, v113
	ds_write_b128 v227, v[110:113]
	s_waitcnt lgkmcnt(1)
	v_lshlrev_b32_e32 v110, 16, v122
	v_and_b32_e32 v111, 0xffff0000, v122
	v_lshlrev_b32_e32 v114, 16, v124
	v_fma_f32 v110, v110, s89, v138
	v_fma_f32 v114, v114, s89, v134
	v_fma_f32 v111, v111, s89, v139
	v_med3_f32 v110, v110, s85, v226
	v_med3_f32 v114, v114, s85, v226
	v_med3_f32 v111, v111, s85, v226
	v_exp_f32_e32 v110, v110
	v_exp_f32_e32 v114, v114
	v_exp_f32_e32 v111, v111
	v_and_b32_e32 v115, 0xffff0000, v124
	v_add_f32_e32 v110, 1.0, v110
	v_add_f32_e32 v114, 1.0, v114
	v_add_f32_e32 v111, 1.0, v111
	v_fma_f32 v115, v115, s89, v135
	v_rcp_f32_e32 v110, v110
	v_rcp_f32_e32 v114, v114
	v_rcp_f32_e32 v111, v111
	v_med3_f32 v115, v115, s85, v226
	v_exp_f32_e32 v115, v115
	v_lshlrev_b32_e32 v112, 16, v123
	v_lshlrev_b32_e32 v116, 16, v125
	v_mul_f32_e32 v106, v106, v110
	v_mul_f32_e32 v110, v102, v114
	v_mul_f32_e32 v102, v107, v111
	v_fma_f32 v111, v112, s89, v140
	v_fma_f32 v112, v116, s89, v136
	v_add_f32_e32 v107, 1.0, v115
	v_med3_f32 v111, v111, s85, v226
	v_med3_f32 v112, v112, s85, v226
	v_rcp_f32_e32 v107, v107
	v_exp_f32_e32 v111, v111
	v_exp_f32_e32 v112, v112
	v_and_b32_e32 v113, 0xffff0000, v123
	v_and_b32_e32 v117, 0xffff0000, v125
	v_mul_f32_e32 v107, v103, v107
	v_add_f32_e32 v103, 1.0, v111
	v_add_f32_e32 v111, 1.0, v112
	v_fma_f32 v112, v113, s89, v141
	v_fma_f32 v113, v117, s89, v137
	v_med3_f32 v112, v112, s85, v226
	v_med3_f32 v113, v113, s85, v226
	v_exp_f32_e32 v112, v112
	v_exp_f32_e32 v113, v113
	v_rcp_f32_e32 v103, v103
	v_rcp_f32_e32 v111, v111
	v_add_f32_e32 v112, 1.0, v112
	v_add_f32_e32 v113, 1.0, v113
	v_rcp_f32_e32 v112, v112
	v_rcp_f32_e32 v113, v113
	v_mul_f32_e32 v103, v108, v103
	v_mul_f32_e32 v108, v104, v111
	v_mul_f32_e32 v104, v109, v112
	v_mul_f32_e32 v105, v105, v113
	v_cvt_pk_bf16_f32 v102, v106, v102
	v_cvt_pk_bf16_f32 v103, v103, v104
	v_cvt_pk_bf16_f32 v104, v110, v107
	v_cvt_pk_bf16_f32 v105, v108, v105
	ds_write_b128 v227, v[102:105] offset:64
	ds_read_b128 v[102:105], v3
	ds_read_b128 v[106:109], v3 offset:1152
	s_waitcnt lgkmcnt(1)
	global_store_dwordx4 v[4:5], v[102:105], off offset:2048
	s_waitcnt lgkmcnt(0)
	global_store_dwordx4 v[4:5], v[106:109], off offset:3072
	v_mov_b64_e32 v[102:103], v[190:191]
	v_mov_b64_e32 v[104:105], v[192:193]
	v_mov_b64_e32 v[106:107], v[194:195]
	v_mov_b64_e32 v[108:109], v[196:197]
	s_waitcnt lgkmcnt(0)
	v_lshlrev_b32_e32 v110, 16, v102
	v_and_b32_e32 v102, 0xffff0000, v102
	v_lshlrev_b32_e32 v112, 16, v104
	v_fma_f32 v110, v110, s89, v146
	v_fma_f32 v112, v112, s89, v142
	v_fma_f32 v102, v102, s89, v147
	v_med3_f32 v110, v110, s85, v226
	v_med3_f32 v112, v112, s85, v226
	v_med3_f32 v102, v102, s85, v226
	v_exp_f32_e32 v110, v110
	v_exp_f32_e32 v112, v112
	v_exp_f32_e32 v102, v102
	v_and_b32_e32 v104, 0xffff0000, v104
	v_fma_f32 v104, v104, s89, v143
	v_add_f32_e32 v110, 1.0, v110
	v_add_f32_e32 v112, 1.0, v112
	v_add_f32_e32 v102, 1.0, v102
	v_med3_f32 v104, v104, s85, v226
	v_rcp_f32_e32 v110, v110
	v_rcp_f32_e32 v112, v112
	v_rcp_f32_e32 v102, v102
	v_exp_f32_e32 v104, v104
	v_lshlrev_b32_e32 v111, 16, v103
	v_lshlrev_b32_e32 v113, 16, v105
	v_mul_f32_e32 v98, v98, v110
	v_mul_f32_e32 v110, v94, v112
	v_mul_f32_e32 v94, v99, v102
	v_add_f32_e32 v99, 1.0, v104
	v_fma_f32 v102, v111, s89, v148
	v_fma_f32 v104, v113, s89, v144
	v_med3_f32 v102, v102, s85, v226
	v_med3_f32 v104, v104, s85, v226
	v_rcp_f32_e32 v99, v99
	v_exp_f32_e32 v102, v102
	v_exp_f32_e32 v104, v104
	v_and_b32_e32 v103, 0xffff0000, v103
	v_and_b32_e32 v105, 0xffff0000, v105
	v_mul_f32_e32 v99, v95, v99
	v_add_f32_e32 v95, 1.0, v102
	v_add_f32_e32 v102, 1.0, v104
	v_fma_f32 v103, v103, s89, v149
	v_fma_f32 v104, v105, s89, v145
	v_med3_f32 v103, v103, s85, v226
	v_med3_f32 v104, v104, s85, v226
	v_exp_f32_e32 v103, v103
	v_exp_f32_e32 v104, v104
	v_rcp_f32_e32 v95, v95
	v_rcp_f32_e32 v102, v102
	v_add_f32_e32 v103, 1.0, v103
	v_add_f32_e32 v104, 1.0, v104
	v_rcp_f32_e32 v103, v103
	v_rcp_f32_e32 v104, v104
	v_mul_f32_e32 v95, v100, v95
	v_mul_f32_e32 v100, v96, v102
	v_mul_f32_e32 v96, v101, v103
	v_mul_f32_e32 v97, v97, v104
	v_cvt_pk_bf16_f32 v94, v98, v94
	v_cvt_pk_bf16_f32 v95, v95, v96
	v_cvt_pk_bf16_f32 v96, v110, v99
	v_cvt_pk_bf16_f32 v97, v100, v97
	ds_write_b128 v227, v[94:97]
	s_waitcnt lgkmcnt(1)
; __device__ __forceinline__ u32x4 pack8(const f32x4& v0, const f32x4& v1) { u32x4 w; w.x = cvt_pk_bf16(v0[0], v0[1]); w.y = cvt_pk_bf16(v0[2], v0[3]); w.z = cvt_pk_bf16(v1[0], v1[1]); w.w = cvt_pk_bf16(v1[2], v1[3]); return w; }
; #define UNPK0(q_) ((f32x4){bf_lo((q_).x), bf_hi((q_).x), bf_lo((q_).y), bf_hi((q_).y)})
; #define UNPK1(q_) ((f32x4){bf_lo((q_).z), bf_hi((q_).z), bf_lo((q_).w), bf_hi((q_).w)})
;     static __device__ __forceinline__ float eneg(float g) { return __builtin_amdgcn_exp2f(-1.4426950408889634f * fminf(fmaxf(g, -30.f), 30.f)); }
;     __device__ __forceinline__ void operator()(const f32x4 (&acc)[2][2][4][2], const Unit& u, int wr, int wc, int fr, int fq) const {
;     ...
; #pragma unroll
;         for (int ai = 0; ai < 2; ++ai)
; #pragma unroll
;             for (int m = 0; m < 4; ++m) {
;                 pb.stage(rb[ai][m][0], rb[ai][m][1]); const u32x4 gb0 = pb.get(0), gb1 = pb.get(1);
;                 asm volatile("" ::: "memory");
; #pragma unroll
;                 for (int bj = 0; bj < 2; ++bj) { const u32x4 gb = bj ? gb1 : gb0;
;                     const f32x4 b0 = UNPK0(gb) + bb[bj][0], b1 = UNPK1(gb) + bb[bj][1];
;                     f32x4 v0 = acc[ai][bj][m][0], v1 = acc[ai][bj][m][1];
; #pragma unroll
;                     for (int k = 0; k < 4; ++k) { v0[k] *= __builtin_amdgcn_rcpf(1.0f + eneg(b0[k])); v1[k] *= __builtin_amdgcn_rcpf(1.0f + eneg(b1[k])); }
;                     po.put(bj, pack8(v0, v1)); }
;                 po.flush<false>(ai, m);
;                 asm volatile("" ::: "memory"); }
	v_lshlrev_b32_e32 v94, 16, v106
	v_and_b32_e32 v95, 0xffff0000, v106
	v_lshlrev_b32_e32 v98, 16, v108
	v_fma_f32 v94, v94, s89, v138
	v_fma_f32 v98, v98, s89, v134
	v_fma_f32 v95, v95, s89, v139
	v_med3_f32 v94, v94, s85, v226
	v_med3_f32 v98, v98, s85, v226
	v_med3_f32 v95, v95, s85, v226
	v_exp_f32_e32 v94, v94
	v_exp_f32_e32 v98, v98
	v_exp_f32_e32 v95, v95
	v_and_b32_e32 v99, 0xffff0000, v108
	v_add_f32_e32 v94, 1.0, v94
	v_add_f32_e32 v98, 1.0, v98
	v_add_f32_e32 v95, 1.0, v95
	v_fma_f32 v99, v99, s89, v135
	v_rcp_f32_e32 v94, v94
	v_rcp_f32_e32 v98, v98
	v_rcp_f32_e32 v95, v95
	v_med3_f32 v99, v99, s85, v226
	v_exp_f32_e32 v99, v99
	v_lshlrev_b32_e32 v96, 16, v107
	v_lshlrev_b32_e32 v100, 16, v109
	v_mul_f32_e32 v90, v90, v94
	v_mul_f32_e32 v94, v86, v98
	v_mul_f32_e32 v86, v91, v95
	v_fma_f32 v95, v96, s89, v140
	v_fma_f32 v96, v100, s89, v136
	v_add_f32_e32 v91, 1.0, v99
	v_med3_f32 v95, v95, s85, v226
	v_med3_f32 v96, v96, s85, v226
	v_rcp_f32_e32 v91, v91
	v_exp_f32_e32 v95, v95
	v_exp_f32_e32 v96, v96
	v_and_b32_e32 v97, 0xffff0000, v107
	v_and_b32_e32 v101, 0xffff0000, v109
	v_mul_f32_e32 v91, v87, v91
	v_add_f32_e32 v87, 1.0, v95
	v_add_f32_e32 v95, 1.0, v96
	v_fma_f32 v96, v97, s89, v141
	v_fma_f32 v97, v101, s89, v137
	v_med3_f32 v96, v96, s85, v226
	v_med3_f32 v97, v97, s85, v226
	v_exp_f32_e32 v96, v96
	v_exp_f32_e32 v97, v97
	v_rcp_f32_e32 v87, v87
	v_rcp_f32_e32 v95, v95
	v_add_f32_e32 v96, 1.0, v96
	v_add_f32_e32 v97, 1.0, v97
	v_rcp_f32_e32 v96, v96
	v_rcp_f32_e32 v97, v97
	v_mul_f32_e32 v87, v92, v87
	v_mul_f32_e32 v92, v88, v95
	v_mul_f32_e32 v88, v93, v96
	v_mul_f32_e32 v89, v89, v97
	v_cvt_pk_bf16_f32 v86, v90, v86
	v_cvt_pk_bf16_f32 v87, v87, v88
	v_cvt_pk_bf16_f32 v88, v94, v91
	v_cvt_pk_bf16_f32 v89, v92, v89
	ds_write_b128 v227, v[86:89] offset:64
	ds_read_b128 v[86:89], v3
	ds_read_b128 v[90:93], v3 offset:1152
	v_add_co_u32_e32 v94, vcc, s84, v4
	s_nop 1
	v_addc_co_u32_e32 v95, vcc, 0, v5, vcc
	s_waitcnt lgkmcnt(1)
	global_store_dwordx4 v[94:95], v[86:89], off
	s_waitcnt lgkmcnt(0)
	global_store_dwordx4 v[94:95], v[90:93], off offset:1024
	v_mov_b64_e32 v[86:87], v[182:183]
	v_mov_b64_e32 v[88:89], v[184:185]
	v_mov_b64_e32 v[90:91], v[186:187]
	v_mov_b64_e32 v[92:93], v[188:189]
	s_waitcnt lgkmcnt(0)
	v_lshlrev_b32_e32 v96, 16, v86
	v_and_b32_e32 v86, 0xffff0000, v86
	v_lshlrev_b32_e32 v98, 16, v88
	v_fma_f32 v96, v96, s89, v146
	v_fma_f32 v98, v98, s89, v142
	v_fma_f32 v86, v86, s89, v147
	v_med3_f32 v96, v96, s85, v226
	v_med3_f32 v98, v98, s85, v226
	v_med3_f32 v86, v86, s85, v226
	v_exp_f32_e32 v96, v96
	v_exp_f32_e32 v98, v98
	v_exp_f32_e32 v86, v86
	v_and_b32_e32 v88, 0xffff0000, v88
	v_fma_f32 v88, v88, s89, v143
	v_add_f32_e32 v96, 1.0, v96
	v_add_f32_e32 v98, 1.0, v98
	v_add_f32_e32 v86, 1.0, v86
	v_med3_f32 v88, v88, s85, v226
	v_rcp_f32_e32 v96, v96
	v_rcp_f32_e32 v98, v98
	v_rcp_f32_e32 v86, v86
	v_exp_f32_e32 v88, v88
	v_lshlrev_b32_e32 v97, 16, v87
	v_lshlrev_b32_e32 v99, 16, v89
	v_mul_f32_e32 v82, v82, v96
	v_mul_f32_e32 v96, v78, v98
	v_mul_f32_e32 v78, v83, v86
	v_add_f32_e32 v83, 1.0, v88
	v_fma_f32 v86, v97, s89, v148
	v_fma_f32 v88, v99, s89, v144
	v_med3_f32 v86, v86, s85, v226
	v_med3_f32 v88, v88, s85, v226
	v_rcp_f32_e32 v83, v83
	v_exp_f32_e32 v86, v86
	v_exp_f32_e32 v88, v88
	v_and_b32_e32 v87, 0xffff0000, v87
	v_and_b32_e32 v89, 0xffff0000, v89
	v_mul_f32_e32 v83, v79, v83
	v_add_f32_e32 v79, 1.0, v86
	v_add_f32_e32 v86, 1.0, v88
	v_fma_f32 v87, v87, s89, v149
	v_fma_f32 v88, v89, s89, v145
	v_med3_f32 v87, v87, s85, v226
	v_med3_f32 v88, v88, s85, v226
	v_exp_f32_e32 v87, v87
	v_exp_f32_e32 v88, v88
	v_rcp_f32_e32 v79, v79
	v_rcp_f32_e32 v86, v86
	v_add_f32_e32 v87, 1.0, v87
	v_add_f32_e32 v88, 1.0, v88
	v_rcp_f32_e32 v87, v87
	v_rcp_f32_e32 v88, v88
	v_mul_f32_e32 v79, v84, v79
	v_mul_f32_e32 v84, v80, v86
	v_mul_f32_e32 v80, v85, v87
	v_mul_f32_e32 v81, v81, v88
	v_cvt_pk_bf16_f32 v78, v82, v78
	v_cvt_pk_bf16_f32 v79, v79, v80
	v_cvt_pk_bf16_f32 v80, v96, v83
	v_cvt_pk_bf16_f32 v81, v84, v81
	ds_write_b128 v227, v[78:81]
	s_waitcnt lgkmcnt(1)
	v_lshlrev_b32_e32 v78, 16, v90
	v_and_b32_e32 v79, 0xffff0000, v90
	v_lshlrev_b32_e32 v82, 16, v92
	v_fma_f32 v78, v78, s89, v138
	v_fma_f32 v82, v82, s89, v134
	v_fma_f32 v79, v79, s89, v139
	v_med3_f32 v78, v78, s85, v226
	v_med3_f32 v82, v82, s85, v226
	v_med3_f32 v79, v79, s85, v226
	v_exp_f32_e32 v78, v78
	v_exp_f32_e32 v82, v82
	v_exp_f32_e32 v79, v79
	v_and_b32_e32 v83, 0xffff0000, v92
	v_add_f32_e32 v78, 1.0, v78
	v_add_f32_e32 v82, 1.0, v82
	v_add_f32_e32 v79, 1.0, v79
	v_fma_f32 v83, v83, s89, v135
	v_rcp_f32_e32 v78, v78
	v_rcp_f32_e32 v82, v82
	v_rcp_f32_e32 v79, v79
	v_med3_f32 v83, v83, s85, v226
	v_exp_f32_e32 v83, v83
	v_lshlrev_b32_e32 v80, 16, v91
	v_lshlrev_b32_e32 v84, 16, v93
	v_mul_f32_e32 v74, v74, v78
	v_mul_f32_e32 v78, v70, v82
	v_mul_f32_e32 v70, v75, v79
	v_fma_f32 v79, v80, s89, v140
	v_fma_f32 v80, v84, s89, v136
	v_add_f32_e32 v75, 1.0, v83
	v_med3_f32 v79, v79, s85, v226
	v_med3_f32 v80, v80, s85, v226
	v_rcp_f32_e32 v75, v75
	v_exp_f32_e32 v79, v79
	v_exp_f32_e32 v80, v80
	v_and_b32_e32 v81, 0xffff0000, v91
	v_and_b32_e32 v85, 0xffff0000, v93
	v_mul_f32_e32 v75, v71, v75
	v_add_f32_e32 v71, 1.0, v79
	v_add_f32_e32 v79, 1.0, v80
	v_fma_f32 v80, v81, s89, v141
	v_fma_f32 v81, v85, s89, v137
	v_med3_f32 v80, v80, s85, v226
	v_med3_f32 v81, v81, s85, v226
	v_exp_f32_e32 v80, v80
	v_exp_f32_e32 v81, v81
	v_rcp_f32_e32 v71, v71
	v_rcp_f32_e32 v79, v79
	v_add_f32_e32 v80, 1.0, v80
	v_add_f32_e32 v81, 1.0, v81
	v_rcp_f32_e32 v80, v80
	v_rcp_f32_e32 v81, v81
	v_mul_f32_e32 v71, v76, v71
	v_mul_f32_e32 v76, v72, v79
	v_mul_f32_e32 v72, v77, v80
	v_mul_f32_e32 v73, v73, v81
	v_cvt_pk_bf16_f32 v70, v74, v70
	v_cvt_pk_bf16_f32 v71, v71, v72
	v_cvt_pk_bf16_f32 v72, v78, v75
	v_cvt_pk_bf16_f32 v73, v76, v73
	ds_write_b128 v227, v[70:73] offset:64
	ds_read_b128 v[70:73], v3
	ds_read_b128 v[74:77], v3 offset:1152
	s_waitcnt lgkmcnt(1)
; __device__ __forceinline__ u32x4 pack8(const f32x4& v0, const f32x4& v1) { u32x4 w; w.x = cvt_pk_bf16(v0[0], v0[1]); w.y = cvt_pk_bf16(v0[2], v0[3]); w.z = cvt_pk_bf16(v1[0], v1[1]); w.w = cvt_pk_bf16(v1[2], v1[3]); return w; }
; #define UNPK0(q_) ((f32x4){bf_lo((q_).x), bf_hi((q_).x), bf_lo((q_).y), bf_hi((q_).y)})
; #define UNPK1(q_) ((f32x4){bf_lo((q_).z), bf_hi((q_).z), bf_lo((q_).w), bf_hi((q_).w)})
;     static __device__ __forceinline__ float eneg(float g) { return __builtin_amdgcn_exp2f(-1.4426950408889634f * fminf(fmaxf(g, -30.f), 30.f)); }
;     __device__ __forceinline__ void operator()(const f32x4 (&acc)[2][2][4][2], const Unit& u, int wr, int wc, int fr, int fq) const {
;     ...
; #pragma unroll
;         for (int ai = 0; ai < 2; ++ai)
; #pragma unroll
;             for (int m = 0; m < 4; ++m) {
;                 pb.stage(rb[ai][m][0], rb[ai][m][1]); const u32x4 gb0 = pb.get(0), gb1 = pb.get(1);
;                 asm volatile("" ::: "memory");
; #pragma unroll
;                 for (int bj = 0; bj < 2; ++bj) { const u32x4 gb = bj ? gb1 : gb0;
;                     const f32x4 b0 = UNPK0(gb) + bb[bj][0], b1 = UNPK1(gb) + bb[bj][1];
;                     f32x4 v0 = acc[ai][bj][m][0], v1 = acc[ai][bj][m][1];
; #pragma unroll
;                     for (int k = 0; k < 4; ++k) { v0[k] *= __builtin_amdgcn_rcpf(1.0f + eneg(b0[k])); v1[k] *= __builtin_amdgcn_rcpf(1.0f + eneg(b1[k])); }
;                     po.put(bj, pack8(v0, v1)); }
;                 po.flush<false>(ai, m);
;                 asm volatile("" ::: "memory"); }
	global_store_dwordx4 v[94:95], v[70:73], off offset:2048
	s_waitcnt lgkmcnt(0)
	global_store_dwordx4 v[94:95], v[74:77], off offset:3072
	v_mov_b64_e32 v[70:71], v[178:179]
	v_mov_b64_e32 v[72:73], v[180:181]
	v_mov_b64_e32 v[74:75], v[174:175]
	v_mov_b64_e32 v[76:77], v[176:177]
	s_waitcnt lgkmcnt(0)
	v_lshlrev_b32_e32 v78, 16, v70
	v_and_b32_e32 v70, 0xffff0000, v70
	v_lshlrev_b32_e32 v80, 16, v72
	v_fma_f32 v78, v78, s89, v146
	v_fma_f32 v80, v80, s89, v142
	v_fma_f32 v70, v70, s89, v147
	v_med3_f32 v78, v78, s85, v226
	v_med3_f32 v80, v80, s85, v226
	v_med3_f32 v70, v70, s85, v226
	v_exp_f32_e32 v78, v78
	v_exp_f32_e32 v80, v80
	v_exp_f32_e32 v70, v70
	v_and_b32_e32 v72, 0xffff0000, v72
	v_fma_f32 v72, v72, s89, v143
	v_add_f32_e32 v78, 1.0, v78
	v_add_f32_e32 v80, 1.0, v80
	v_add_f32_e32 v70, 1.0, v70
	v_med3_f32 v72, v72, s85, v226
	v_rcp_f32_e32 v78, v78
	v_rcp_f32_e32 v80, v80
	v_rcp_f32_e32 v70, v70
	v_exp_f32_e32 v72, v72
	v_lshlrev_b32_e32 v79, 16, v71
	v_lshlrev_b32_e32 v81, 16, v73
	v_mul_f32_e32 v66, v66, v78
	v_mul_f32_e32 v78, v62, v80
	v_mul_f32_e32 v62, v67, v70
	v_add_f32_e32 v67, 1.0, v72
	v_fma_f32 v70, v79, s89, v148
	v_fma_f32 v72, v81, s89, v144
	v_med3_f32 v70, v70, s85, v226
	v_med3_f32 v72, v72, s85, v226
	v_rcp_f32_e32 v67, v67
	v_exp_f32_e32 v70, v70
	v_exp_f32_e32 v72, v72
	v_and_b32_e32 v71, 0xffff0000, v71
	v_and_b32_e32 v73, 0xffff0000, v73
	v_mul_f32_e32 v67, v63, v67
	v_add_f32_e32 v63, 1.0, v70
	v_add_f32_e32 v70, 1.0, v72
	v_fma_f32 v71, v71, s89, v149
	v_fma_f32 v72, v73, s89, v145
	v_med3_f32 v71, v71, s85, v226
	v_med3_f32 v72, v72, s85, v226
	v_exp_f32_e32 v71, v71
	v_exp_f32_e32 v72, v72
	v_rcp_f32_e32 v63, v63
	v_rcp_f32_e32 v70, v70
	v_add_f32_e32 v71, 1.0, v71
	v_add_f32_e32 v72, 1.0, v72
	v_rcp_f32_e32 v71, v71
	v_rcp_f32_e32 v72, v72
	v_mul_f32_e32 v63, v68, v63
	v_mul_f32_e32 v68, v64, v70
	v_mul_f32_e32 v64, v69, v71
	v_mul_f32_e32 v65, v65, v72
	v_cvt_pk_bf16_f32 v62, v66, v62
	v_cvt_pk_bf16_f32 v63, v63, v64
	v_cvt_pk_bf16_f32 v64, v78, v67
	v_cvt_pk_bf16_f32 v65, v68, v65
	ds_write_b128 v227, v[62:65]
	s_waitcnt lgkmcnt(1)
	v_lshlrev_b32_e32 v62, 16, v74
	v_and_b32_e32 v63, 0xffff0000, v74
	v_lshlrev_b32_e32 v66, 16, v76
	v_fma_f32 v62, v62, s89, v138
	v_fma_f32 v66, v66, s89, v134
	v_fma_f32 v63, v63, s89, v139
	v_med3_f32 v62, v62, s85, v226
	v_med3_f32 v66, v66, s85, v226
	v_med3_f32 v63, v63, s85, v226
	v_exp_f32_e32 v62, v62
	v_exp_f32_e32 v66, v66
	v_exp_f32_e32 v63, v63
	v_and_b32_e32 v67, 0xffff0000, v76
	v_add_f32_e32 v62, 1.0, v62
	v_add_f32_e32 v66, 1.0, v66
	v_add_f32_e32 v63, 1.0, v63
	v_fma_f32 v67, v67, s89, v135
	v_rcp_f32_e32 v62, v62
	v_rcp_f32_e32 v66, v66
	v_rcp_f32_e32 v63, v63
	v_med3_f32 v67, v67, s85, v226
	v_exp_f32_e32 v67, v67
	v_lshlrev_b32_e32 v64, 16, v75
	v_lshlrev_b32_e32 v68, 16, v77
	v_mul_f32_e32 v58, v58, v62
	v_mul_f32_e32 v62, v54, v66
	v_mul_f32_e32 v54, v59, v63
	v_fma_f32 v63, v64, s89, v140
	v_fma_f32 v64, v68, s89, v136
	v_add_f32_e32 v59, 1.0, v67
	v_med3_f32 v63, v63, s85, v226
	v_med3_f32 v64, v64, s85, v226
	v_rcp_f32_e32 v59, v59
	v_exp_f32_e32 v63, v63
	v_exp_f32_e32 v64, v64
	v_and_b32_e32 v65, 0xffff0000, v75
	v_and_b32_e32 v69, 0xffff0000, v77
	v_mul_f32_e32 v59, v55, v59
	v_add_f32_e32 v55, 1.0, v63
	v_add_f32_e32 v63, 1.0, v64
	v_fma_f32 v64, v65, s89, v141
	v_fma_f32 v65, v69, s89, v137
	v_med3_f32 v64, v64, s85, v226
	v_med3_f32 v65, v65, s85, v226
	v_exp_f32_e32 v64, v64
	v_exp_f32_e32 v65, v65
	v_rcp_f32_e32 v55, v55
	v_rcp_f32_e32 v63, v63
	v_add_f32_e32 v64, 1.0, v64
	v_add_f32_e32 v65, 1.0, v65
	v_rcp_f32_e32 v64, v64
	v_rcp_f32_e32 v65, v65
	v_mul_f32_e32 v55, v60, v55
	v_mul_f32_e32 v60, v56, v63
	v_mul_f32_e32 v56, v61, v64
	v_mul_f32_e32 v57, v57, v65
	v_cvt_pk_bf16_f32 v54, v58, v54
	v_cvt_pk_bf16_f32 v55, v55, v56
	v_cvt_pk_bf16_f32 v56, v62, v59
	v_cvt_pk_bf16_f32 v57, v60, v57
	ds_write_b128 v227, v[54:57] offset:64
	ds_read_b128 v[54:57], v3
	ds_read_b128 v[58:61], v3 offset:1152
	v_add_co_u32_e32 v62, vcc, s79, v4
	s_nop 1
	v_addc_co_u32_e32 v63, vcc, 0, v5, vcc
	v_add_co_u32_e32 v4, vcc, s86, v4
	s_nop 1
	v_addc_co_u32_e32 v5, vcc, 0, v5, vcc
	s_waitcnt lgkmcnt(1)
	global_store_dwordx4 v[4:5], v[54:57], off offset:-4096
	s_waitcnt lgkmcnt(0)
	global_store_dwordx4 v[62:63], v[58:61], off offset:1024
	v_mov_b64_e32 v[54:55], v[166:167]
	v_mov_b64_e32 v[56:57], v[168:169]
	v_mov_b64_e32 v[58:59], v[170:171]
	v_mov_b64_e32 v[60:61], v[172:173]
	s_andn2_b64 vcc, exec, s[4:5]
	s_mov_b64 s[4:5], -1
	s_waitcnt lgkmcnt(0)
	v_lshlrev_b32_e32 v64, 16, v54
	v_and_b32_e32 v54, 0xffff0000, v54
	v_lshlrev_b32_e32 v66, 16, v56
	v_fma_f32 v64, v64, s89, v146
	v_fma_f32 v66, v66, s89, v142
	v_fma_f32 v54, v54, s89, v147
	v_med3_f32 v64, v64, s85, v226
	v_med3_f32 v66, v66, s85, v226
	v_med3_f32 v54, v54, s85, v226
	v_exp_f32_e32 v64, v64
	v_exp_f32_e32 v66, v66
	v_exp_f32_e32 v54, v54
	v_and_b32_e32 v56, 0xffff0000, v56
	v_fma_f32 v56, v56, s89, v143
	v_add_f32_e32 v64, 1.0, v64
	v_add_f32_e32 v66, 1.0, v66
	v_add_f32_e32 v54, 1.0, v54
	v_med3_f32 v56, v56, s85, v226
	v_rcp_f32_e32 v64, v64
	v_rcp_f32_e32 v66, v66
	v_rcp_f32_e32 v54, v54
	v_exp_f32_e32 v56, v56
	v_lshlrev_b32_e32 v65, 16, v55
	v_lshlrev_b32_e32 v67, 16, v57
	v_mul_f32_e32 v50, v50, v64
	v_mul_f32_e32 v64, v46, v66
	v_mul_f32_e32 v46, v51, v54
	v_add_f32_e32 v51, 1.0, v56
	v_fma_f32 v54, v65, s89, v148
	v_fma_f32 v56, v67, s89, v144
	v_med3_f32 v54, v54, s85, v226
	v_med3_f32 v56, v56, s85, v226
	v_rcp_f32_e32 v51, v51
	v_exp_f32_e32 v54, v54
	v_exp_f32_e32 v56, v56
	v_and_b32_e32 v55, 0xffff0000, v55
	v_and_b32_e32 v57, 0xffff0000, v57
	v_mul_f32_e32 v51, v47, v51
	v_add_f32_e32 v47, 1.0, v54
	v_add_f32_e32 v54, 1.0, v56
	v_fma_f32 v55, v55, s89, v149
	v_fma_f32 v56, v57, s89, v145
	v_med3_f32 v55, v55, s85, v226
	v_med3_f32 v56, v56, s85, v226
	v_exp_f32_e32 v55, v55
	v_exp_f32_e32 v56, v56
	v_rcp_f32_e32 v47, v47
	v_rcp_f32_e32 v54, v54
	v_add_f32_e32 v55, 1.0, v55
	v_add_f32_e32 v56, 1.0, v56
	v_rcp_f32_e32 v55, v55
	v_rcp_f32_e32 v56, v56
	v_mul_f32_e32 v47, v52, v47
	v_mul_f32_e32 v52, v48, v54
	v_mul_f32_e32 v48, v53, v55
	v_mul_f32_e32 v49, v49, v56
	v_cvt_pk_bf16_f32 v46, v50, v46
	v_cvt_pk_bf16_f32 v47, v47, v48
	v_cvt_pk_bf16_f32 v48, v64, v51
	v_cvt_pk_bf16_f32 v49, v52, v49
	ds_write_b128 v227, v[46:49]
	s_waitcnt lgkmcnt(1)
; __device__ __forceinline__ u32x4 pack8(const f32x4& v0, const f32x4& v1) { u32x4 w; w.x = cvt_pk_bf16(v0[0], v0[1]); w.y = cvt_pk_bf16(v0[2], v0[3]); w.z = cvt_pk_bf16(v1[0], v1[1]); w.w = cvt_pk_bf16(v1[2], v1[3]); return w; }
; #define UNPK0(q_) ((f32x4){bf_lo((q_).x), bf_hi((q_).x), bf_lo((q_).y), bf_hi((q_).y)})
; #define UNPK1(q_) ((f32x4){bf_lo((q_).z), bf_hi((q_).z), bf_lo((q_).w), bf_hi((q_).w)})
;     static __device__ __forceinline__ float eneg(float g) { return __builtin_amdgcn_exp2f(-1.4426950408889634f * fminf(fmaxf(g, -30.f), 30.f)); }
;     __device__ __forceinline__ void operator()(const f32x4 (&acc)[2][2][4][2], const Unit& u, int wr, int wc, int fr, int fq) const {
;     ...
; #pragma unroll
;         for (int ai = 0; ai < 2; ++ai)
; #pragma unroll
;             for (int m = 0; m < 4; ++m) {
;                 pb.stage(rb[ai][m][0], rb[ai][m][1]); const u32x4 gb0 = pb.get(0), gb1 = pb.get(1);
;                 asm volatile("" ::: "memory");
; #pragma unroll
;                 for (int bj = 0; bj < 2; ++bj) { const u32x4 gb = bj ? gb1 : gb0;
;                     const f32x4 b0 = UNPK0(gb) + bb[bj][0], b1 = UNPK1(gb) + bb[bj][1];
;                     f32x4 v0 = acc[ai][bj][m][0], v1 = acc[ai][bj][m][1];
; #pragma unroll
;                     for (int k = 0; k < 4; ++k) { v0[k] *= __builtin_amdgcn_rcpf(1.0f + eneg(b0[k])); v1[k] *= __builtin_amdgcn_rcpf(1.0f + eneg(b1[k])); }
;                     po.put(bj, pack8(v0, v1)); }
;                 po.flush<false>(ai, m);
;                 asm volatile("" ::: "memory"); }
	v_lshlrev_b32_e32 v46, 16, v58
	v_and_b32_e32 v47, 0xffff0000, v58
	v_lshlrev_b32_e32 v50, 16, v60
	v_fma_f32 v46, v46, s89, v138
	v_fma_f32 v50, v50, s89, v134
	v_fma_f32 v47, v47, s89, v139
	v_med3_f32 v46, v46, s85, v226
	v_med3_f32 v50, v50, s85, v226
	v_med3_f32 v47, v47, s85, v226
	v_exp_f32_e32 v46, v46
	v_exp_f32_e32 v50, v50
	v_exp_f32_e32 v47, v47
	v_and_b32_e32 v51, 0xffff0000, v60
	v_add_f32_e32 v46, 1.0, v46
	v_add_f32_e32 v50, 1.0, v50
	v_add_f32_e32 v47, 1.0, v47
	v_fma_f32 v51, v51, s89, v135
	v_rcp_f32_e32 v46, v46
	v_rcp_f32_e32 v50, v50
	v_rcp_f32_e32 v47, v47
	v_med3_f32 v51, v51, s85, v226
	v_exp_f32_e32 v51, v51
	v_lshlrev_b32_e32 v48, 16, v59
	v_lshlrev_b32_e32 v52, 16, v61
	v_mul_f32_e32 v42, v42, v46
	v_mul_f32_e32 v46, v38, v50
	v_mul_f32_e32 v38, v43, v47
	v_fma_f32 v47, v48, s89, v140
	v_fma_f32 v48, v52, s89, v136
	v_add_f32_e32 v43, 1.0, v51
	v_med3_f32 v47, v47, s85, v226
	v_med3_f32 v48, v48, s85, v226
	v_rcp_f32_e32 v43, v43
	v_exp_f32_e32 v47, v47
	v_exp_f32_e32 v48, v48
	v_and_b32_e32 v49, 0xffff0000, v59
	v_and_b32_e32 v53, 0xffff0000, v61
	v_mul_f32_e32 v43, v39, v43
	v_add_f32_e32 v39, 1.0, v47
	v_add_f32_e32 v47, 1.0, v48
	v_fma_f32 v48, v49, s89, v141
	v_fma_f32 v49, v53, s89, v137
	v_med3_f32 v48, v48, s85, v226
	v_med3_f32 v49, v49, s85, v226
	v_exp_f32_e32 v48, v48
	v_exp_f32_e32 v49, v49
	v_rcp_f32_e32 v39, v39
	v_rcp_f32_e32 v47, v47
	v_add_f32_e32 v48, 1.0, v48
	v_add_f32_e32 v49, 1.0, v49
	v_rcp_f32_e32 v48, v48
	v_rcp_f32_e32 v49, v49
	v_mul_f32_e32 v39, v44, v39
	v_mul_f32_e32 v44, v40, v47
	v_mul_f32_e32 v40, v45, v48
	v_mul_f32_e32 v41, v41, v49
	v_cvt_pk_bf16_f32 v38, v42, v38
	v_cvt_pk_bf16_f32 v39, v39, v40
	v_cvt_pk_bf16_f32 v40, v46, v43
	v_cvt_pk_bf16_f32 v41, v44, v41
	ds_write_b128 v227, v[38:41] offset:64
	ds_read_b128 v[38:41], v3
	ds_read_b128 v[42:45], v3 offset:1152
	s_waitcnt lgkmcnt(1)
	global_store_dwordx4 v[62:63], v[38:41], off offset:2048
	s_waitcnt lgkmcnt(0)
	global_store_dwordx4 v[62:63], v[42:45], off offset:3072
	v_mov_b64_e32 v[38:39], v[158:159]
	v_mov_b64_e32 v[40:41], v[160:161]
	v_mov_b64_e32 v[42:43], v[162:163]
	v_mov_b64_e32 v[44:45], v[164:165]
	s_waitcnt lgkmcnt(0)
	v_lshlrev_b32_e32 v46, 16, v38
	v_and_b32_e32 v38, 0xffff0000, v38
	v_lshlrev_b32_e32 v48, 16, v40
	v_fma_f32 v46, v46, s89, v146
	v_fma_f32 v48, v48, s89, v142
	v_fma_f32 v38, v38, s89, v147
	v_med3_f32 v46, v46, s85, v226
	v_med3_f32 v48, v48, s85, v226
	v_med3_f32 v38, v38, s85, v226
	v_exp_f32_e32 v46, v46
	v_exp_f32_e32 v48, v48
	v_exp_f32_e32 v38, v38
	v_and_b32_e32 v40, 0xffff0000, v40
	v_fma_f32 v40, v40, s89, v143
	v_add_f32_e32 v46, 1.0, v46
	v_add_f32_e32 v48, 1.0, v48
	v_add_f32_e32 v38, 1.0, v38
	v_med3_f32 v40, v40, s85, v226
	v_rcp_f32_e32 v46, v46
	v_rcp_f32_e32 v48, v48
	v_rcp_f32_e32 v38, v38
	v_exp_f32_e32 v40, v40
	v_lshlrev_b32_e32 v47, 16, v39
	v_lshlrev_b32_e32 v49, 16, v41
	v_mul_f32_e32 v34, v34, v46
	v_mul_f32_e32 v46, v30, v48
	v_mul_f32_e32 v30, v35, v38
	v_add_f32_e32 v35, 1.0, v40
	v_fma_f32 v38, v47, s89, v148
	v_fma_f32 v40, v49, s89, v144
	v_med3_f32 v38, v38, s85, v226
	v_med3_f32 v40, v40, s85, v226
	v_rcp_f32_e32 v35, v35
	v_exp_f32_e32 v38, v38
	v_exp_f32_e32 v40, v40
	v_and_b32_e32 v39, 0xffff0000, v39
	v_and_b32_e32 v41, 0xffff0000, v41
	v_mul_f32_e32 v35, v31, v35
	v_add_f32_e32 v31, 1.0, v38
	v_add_f32_e32 v38, 1.0, v40
	v_fma_f32 v39, v39, s89, v149
	v_fma_f32 v40, v41, s89, v145
	v_med3_f32 v39, v39, s85, v226
	v_med3_f32 v40, v40, s85, v226
	v_exp_f32_e32 v39, v39
	v_exp_f32_e32 v40, v40
	v_rcp_f32_e32 v31, v31
	v_rcp_f32_e32 v38, v38
	v_add_f32_e32 v39, 1.0, v39
	v_add_f32_e32 v40, 1.0, v40
	v_rcp_f32_e32 v39, v39
	v_rcp_f32_e32 v40, v40
	v_mul_f32_e32 v31, v36, v31
	v_mul_f32_e32 v36, v32, v38
	v_mul_f32_e32 v32, v37, v39
	v_mul_f32_e32 v33, v33, v40
	v_cvt_pk_bf16_f32 v30, v34, v30
	v_cvt_pk_bf16_f32 v31, v31, v32
	v_cvt_pk_bf16_f32 v32, v46, v35
	v_cvt_pk_bf16_f32 v33, v36, v33
	ds_write_b128 v227, v[30:33]
	s_waitcnt lgkmcnt(1)
	v_lshlrev_b32_e32 v30, 16, v42
	v_and_b32_e32 v31, 0xffff0000, v42
	v_lshlrev_b32_e32 v34, 16, v44
	v_fma_f32 v30, v30, s89, v138
	v_fma_f32 v34, v34, s89, v134
	v_fma_f32 v31, v31, s89, v139
	v_med3_f32 v30, v30, s85, v226
	v_med3_f32 v34, v34, s85, v226
	v_med3_f32 v31, v31, s85, v226
	v_exp_f32_e32 v30, v30
	v_exp_f32_e32 v34, v34
	v_exp_f32_e32 v31, v31
	v_and_b32_e32 v35, 0xffff0000, v44
	v_add_f32_e32 v30, 1.0, v30
	v_add_f32_e32 v34, 1.0, v34
	v_add_f32_e32 v31, 1.0, v31
	v_fma_f32 v35, v35, s89, v135
	v_rcp_f32_e32 v30, v30
	v_rcp_f32_e32 v34, v34
	v_rcp_f32_e32 v31, v31
	v_med3_f32 v35, v35, s85, v226
	v_exp_f32_e32 v35, v35
	v_lshlrev_b32_e32 v32, 16, v43
	v_lshlrev_b32_e32 v36, 16, v45
	v_mul_f32_e32 v26, v26, v30
	v_mul_f32_e32 v30, v22, v34
	v_mul_f32_e32 v22, v27, v31
	v_fma_f32 v31, v32, s89, v140
	v_fma_f32 v32, v36, s89, v136
	v_add_f32_e32 v27, 1.0, v35
	v_med3_f32 v31, v31, s85, v226
	v_med3_f32 v32, v32, s85, v226
	v_rcp_f32_e32 v27, v27
	v_exp_f32_e32 v31, v31
	v_exp_f32_e32 v32, v32
	v_and_b32_e32 v33, 0xffff0000, v43
	v_and_b32_e32 v37, 0xffff0000, v45
	v_mul_f32_e32 v27, v23, v27
	v_add_f32_e32 v23, 1.0, v31
	v_add_f32_e32 v31, 1.0, v32
	v_fma_f32 v32, v33, s89, v141
	v_fma_f32 v33, v37, s89, v137
	v_med3_f32 v32, v32, s85, v226
	v_med3_f32 v33, v33, s85, v226
	v_exp_f32_e32 v32, v32
	v_exp_f32_e32 v33, v33
	v_rcp_f32_e32 v23, v23
	v_rcp_f32_e32 v31, v31
	v_add_f32_e32 v32, 1.0, v32
	v_add_f32_e32 v33, 1.0, v33
	v_rcp_f32_e32 v32, v32
	v_rcp_f32_e32 v33, v33
	v_mul_f32_e32 v23, v28, v23
	v_mul_f32_e32 v28, v24, v31
	v_mul_f32_e32 v24, v29, v32
	v_mul_f32_e32 v25, v25, v33
	v_cvt_pk_bf16_f32 v22, v26, v22
	v_cvt_pk_bf16_f32 v23, v23, v24
	v_cvt_pk_bf16_f32 v24, v30, v27
	v_cvt_pk_bf16_f32 v25, v28, v25
	ds_write_b128 v227, v[22:25] offset:64
	ds_read_b128 v[22:25], v3
	ds_read_b128 v[26:29], v3 offset:1152
	s_waitcnt lgkmcnt(1)
; __device__ __forceinline__ u32x4 pack8(const f32x4& v0, const f32x4& v1) { u32x4 w; w.x = cvt_pk_bf16(v0[0], v0[1]); w.y = cvt_pk_bf16(v0[2], v0[3]); w.z = cvt_pk_bf16(v1[0], v1[1]); w.w = cvt_pk_bf16(v1[2], v1[3]); return w; }
; #define UNPK0(q_) ((f32x4){bf_lo((q_).x), bf_hi((q_).x), bf_lo((q_).y), bf_hi((q_).y)})
; #define UNPK1(q_) ((f32x4){bf_lo((q_).z), bf_hi((q_).z), bf_lo((q_).w), bf_hi((q_).w)})
; #define PG8_BAR __builtin_amdgcn_s_barrier()
;     __device__ __forceinline__ void operator()(const f32x4 (&acc)[2][2][4][2], const Unit& u, int wr, int wc, int fr, int fq) const {
;     ...
; #pragma unroll
;         for (int ai = 0; ai < 2; ++ai)
; #pragma unroll
;             for (int m = 0; m < 4; ++m) {
;                 pb.stage(rb[ai][m][0], rb[ai][m][1]); const u32x4 gb0 = pb.get(0), gb1 = pb.get(1);
;                 asm volatile("" ::: "memory");
; #pragma unroll
;                 for (int bj = 0; bj < 2; ++bj) { const u32x4 gb = bj ? gb1 : gb0;
;                     const f32x4 b0 = UNPK0(gb) + bb[bj][0], b1 = UNPK1(gb) + bb[bj][1];
;                     f32x4 v0 = acc[ai][bj][m][0], v1 = acc[ai][bj][m][1];
; #pragma unroll
;                     for (int k = 0; k < 4; ++k) { v0[k] *= __builtin_amdgcn_rcpf(1.0f + eneg(b0[k])); v1[k] *= __builtin_amdgcn_rcpf(1.0f + eneg(b1[k])); }
;                     po.put(bj, pack8(v0, v1)); }
;                 po.flush<false>(ai, m);
;                 asm volatile("" ::: "memory"); }
; template <class Epi, class Sched, bool ALIGN_EPI = false, bool SP2 = false>
; __device__ __forceinline__ void gemm_phase(PG8_LAS unsigned char* lds, const Gemm g, const Sched& S, const Epi& E) {
;     ...
;         if constexpr (ALIGN_EPI) { if (wr == 0) PG8_BAR; }
;         if constexpr (!Epi::AFTER_DRAIN) { if constexpr (Epi::HAS_PRE) { E.post(acc, pre_st, cur, wr, wc, fr, fq); if (has_next) E.pre(pre_st, nxt, wr, wc, fr, fq); } else E(acc, cur, wr, wc, fr, fq); S.done(cur); }
;         if (!has_next) break;
; #pragma unroll
;         for (int a = 0; a < 2; ++a)
; #pragma unroll
;             for (int b = 0; b < 2; ++b)
; #pragma unroll
;                 for (int m = 0; m < 4; ++m)
; #pragma unroll
;                     for (int n = 0; n < 2; ++n) acc[a][b][m][n] = (f32x4){0.f, 0.f, 0.f, 0.f};
;         cur = nxt; cA = nA; cB = nB; ++ui;
;         if constexpr (ALIGN_EPI) { if (wr == 1) PG8_BAR; }
;     }
	global_store_dwordx4 v[4:5], v[22:25], off
	s_waitcnt lgkmcnt(0)
	global_store_dwordx4 v[4:5], v[26:29], off offset:1024
	v_mov_b64_e32 v[22:23], v[150:151]
	v_mov_b64_e32 v[24:25], v[152:153]
	v_mov_b64_e32 v[26:27], v[154:155]
	v_mov_b64_e32 v[28:29], v[156:157]
	s_waitcnt lgkmcnt(0)
	v_lshlrev_b32_e32 v30, 16, v22
	v_and_b32_e32 v22, 0xffff0000, v22
	v_lshlrev_b32_e32 v32, 16, v24
	v_fma_f32 v30, v30, s89, v146
	v_fma_f32 v32, v32, s89, v142
	v_fma_f32 v22, v22, s89, v147
	v_med3_f32 v30, v30, s85, v226
	v_med3_f32 v32, v32, s85, v226
	v_med3_f32 v22, v22, s85, v226
	v_exp_f32_e32 v30, v30
	v_exp_f32_e32 v32, v32
	v_exp_f32_e32 v22, v22
	v_and_b32_e32 v24, 0xffff0000, v24
	v_fma_f32 v24, v24, s89, v143
	v_add_f32_e32 v30, 1.0, v30
	v_add_f32_e32 v32, 1.0, v32
	v_add_f32_e32 v22, 1.0, v22
	v_med3_f32 v24, v24, s85, v226
	v_rcp_f32_e32 v30, v30
	v_rcp_f32_e32 v32, v32
	v_rcp_f32_e32 v22, v22
	v_exp_f32_e32 v24, v24
	v_lshlrev_b32_e32 v31, 16, v23
	v_lshlrev_b32_e32 v33, 16, v25
	v_mul_f32_e32 v18, v18, v30
	v_mul_f32_e32 v30, v14, v32
	v_mul_f32_e32 v14, v19, v22
	v_add_f32_e32 v19, 1.0, v24
	v_fma_f32 v22, v31, s89, v148
	v_fma_f32 v24, v33, s89, v144
	v_med3_f32 v22, v22, s85, v226
	v_med3_f32 v24, v24, s85, v226
	v_rcp_f32_e32 v19, v19
	v_exp_f32_e32 v22, v22
	v_exp_f32_e32 v24, v24
	v_and_b32_e32 v23, 0xffff0000, v23
	v_and_b32_e32 v25, 0xffff0000, v25
	v_mul_f32_e32 v19, v15, v19
	v_add_f32_e32 v15, 1.0, v22
	v_add_f32_e32 v22, 1.0, v24
	v_fma_f32 v23, v23, s89, v149
	v_fma_f32 v24, v25, s89, v145
	v_med3_f32 v23, v23, s85, v226
	v_med3_f32 v24, v24, s85, v226
	v_exp_f32_e32 v23, v23
	v_exp_f32_e32 v24, v24
	v_rcp_f32_e32 v15, v15
	v_rcp_f32_e32 v22, v22
	v_add_f32_e32 v23, 1.0, v23
	v_add_f32_e32 v24, 1.0, v24
	v_rcp_f32_e32 v23, v23
	v_rcp_f32_e32 v24, v24
	v_mul_f32_e32 v15, v20, v15
	v_mul_f32_e32 v20, v16, v22
	v_mul_f32_e32 v16, v21, v23
	v_mul_f32_e32 v17, v17, v24
	v_cvt_pk_bf16_f32 v14, v18, v14
	v_cvt_pk_bf16_f32 v15, v15, v16
	v_cvt_pk_bf16_f32 v16, v30, v19
	v_cvt_pk_bf16_f32 v17, v20, v17
	ds_write_b128 v227, v[14:17]
	s_waitcnt lgkmcnt(1)
	v_lshlrev_b32_e32 v14, 16, v26
	v_and_b32_e32 v15, 0xffff0000, v26
	v_lshlrev_b32_e32 v18, 16, v28
	v_fma_f32 v14, v14, s89, v138
	v_fma_f32 v18, v18, s89, v134
	v_fma_f32 v15, v15, s89, v139
	v_med3_f32 v14, v14, s85, v226
	v_med3_f32 v18, v18, s85, v226
	v_med3_f32 v15, v15, s85, v226
	v_exp_f32_e32 v14, v14
	v_exp_f32_e32 v18, v18
	v_exp_f32_e32 v15, v15
	v_and_b32_e32 v19, 0xffff0000, v28
	v_add_f32_e32 v14, 1.0, v14
	v_add_f32_e32 v18, 1.0, v18
	v_add_f32_e32 v15, 1.0, v15
	v_fma_f32 v19, v19, s89, v135
	v_rcp_f32_e32 v14, v14
	v_rcp_f32_e32 v18, v18
	v_rcp_f32_e32 v15, v15
	v_med3_f32 v19, v19, s85, v226
	v_exp_f32_e32 v19, v19
	v_lshlrev_b32_e32 v16, 16, v27
	v_lshlrev_b32_e32 v20, 16, v29
	v_mul_f32_e32 v10, v10, v14
	v_mul_f32_e32 v14, v6, v18
	v_mul_f32_e32 v6, v11, v15
	v_fma_f32 v15, v16, s89, v140
	v_fma_f32 v16, v20, s89, v136
	v_add_f32_e32 v11, 1.0, v19
	v_med3_f32 v15, v15, s85, v226
	v_med3_f32 v16, v16, s85, v226
	v_rcp_f32_e32 v11, v11
	v_exp_f32_e32 v15, v15
	v_exp_f32_e32 v16, v16
	v_and_b32_e32 v17, 0xffff0000, v27
	v_and_b32_e32 v21, 0xffff0000, v29
	v_mul_f32_e32 v11, v7, v11
	v_add_f32_e32 v7, 1.0, v15
	v_add_f32_e32 v15, 1.0, v16
	v_fma_f32 v16, v17, s89, v141
	v_fma_f32 v17, v21, s89, v137
	v_med3_f32 v16, v16, s85, v226
	v_med3_f32 v17, v17, s85, v226
	v_exp_f32_e32 v16, v16
	v_exp_f32_e32 v17, v17
	v_rcp_f32_e32 v7, v7
	v_rcp_f32_e32 v15, v15
	v_add_f32_e32 v16, 1.0, v16
	v_add_f32_e32 v17, 1.0, v17
	v_rcp_f32_e32 v16, v16
	v_rcp_f32_e32 v17, v17
	v_mul_f32_e32 v7, v12, v7
	v_mul_f32_e32 v12, v8, v15
	v_mul_f32_e32 v8, v13, v16
	v_mul_f32_e32 v9, v9, v17
	v_cvt_pk_bf16_f32 v6, v10, v6
	v_cvt_pk_bf16_f32 v7, v7, v8
	v_cvt_pk_bf16_f32 v8, v14, v11
	v_cvt_pk_bf16_f32 v9, v12, v9
	ds_write_b128 v227, v[6:9] offset:64
	ds_read_b128 v[6:9], v3
	ds_read_b128 v[10:13], v3 offset:1152
	s_waitcnt lgkmcnt(1)
	global_store_dwordx4 v[4:5], v[6:9], off offset:2048
	s_waitcnt lgkmcnt(0)
	global_store_dwordx4 v[4:5], v[10:13], off offset:3072
	s_cbranch_vccnz .LBB0_372
	s_andn2_b64 vcc, exec, s[10:11]
	s_cbranch_vccnz .LBB0_371
	s_barrier
	s_branch .LBB0_371

; __device__ __forceinline__ size_t tm_block(int pm, int ct, int nct) { return ((size_t)pm * nct + ct) * 32768; }
; __device__ __forceinline__ u32x4 pack8(const f32x4& v0, const f32x4& v1) { u32x4 w; w.x = cvt_pk_bf16(v0[0], v0[1]); w.y = cvt_pk_bf16(v0[2], v0[3]); w.z = cvt_pk_bf16(v1[0], v1[1]); w.w = cvt_pk_bf16(v1[2], v1[3]); return w; }
;     __device__ __forceinline__ void operator()(const f32x4 (&acc)[2][2][4][2], const Unit& u, int wr, int wc, int fr, int fq) const {
;         const int row0 = u.pm * BM + wr * 64 + fr, col0 = u.pn * BM + wc * 64 + 8 * fq;
;         const PieceOut po(scr, X1, tm_block(u.pm, u.pn * 4 + wc, 16), wr, wc, fr, fq);
; #pragma unroll
;         for (int ai = 0; ai < 2; ++ai) {
;             f32x4 xv[4][2][2];
; #pragma unroll
;             for (int m = 0; m < 4; ++m) { const float* xp = x + (size_t)(row0 + ai * HALF + m * 16) * 1024 + col0;
; #pragma unroll
;                 for (int bj = 0; bj < 2; ++bj) { xv[m][bj][0] = *(const f32x4*)(xp + bj * 32); xv[m][bj][1] = *(const f32x4*)(xp + bj * 32 + 4); } }
;             asm volatile("" ::: "memory");
; #pragma unroll
;             for (int m = 0; m < 4; ++m) { const int row = row0 + ai * HALF + m * 16; float sq = 0.f;
; #pragma unroll
;                 for (int bj = 0; bj < 2; ++bj) { const f32x4 o0 = xv[m][bj][0] + acc[ai][bj][m][0], o1 = xv[m][bj][1] + acc[ai][bj][m][1];
;                     sq += ((o0[0] * o0[0] + o0[1] * o0[1]) + (o0[2] * o0[2] + o0[3] * o0[3])) + ((o1[0] * o1[0] + o1[1] * o1[1]) + (o1[2] * o1[2] + o1[3] * o1[3]));
;                     po.put(bj, pack8(o0, o1)); }
;                 po.flush<false>(ai, m);
;                 sq += __shfl_xor(sq, 16); sq += __shfl_xor(sq, 32);
;                 if (fq == 0) atomicAdd(ss + row, sq); }
.LBB0_480:
	v_lshl_add_u32 v216, s46, 8, v198
	v_lshl_or_b32 v130, s48, 8, v200
	v_ashrrev_i32_e32 v131, 31, v130
	v_ashrrev_i32_e32 v217, 31, v216
	v_lshl_add_u64 v[130:131], v[130:131], 2, s[36:37]
	v_lshlrev_b64 v[132:133], 12, v[216:217]
	v_lshl_add_u64 v[196:197], v[130:131], 0, v[132:133]
	global_load_dwordx4 v[208:211], v[196:197], off nt
	global_load_dwordx4 v[212:215], v[196:197], off offset:16 nt
	global_load_dwordx4 v[220:223], v[196:197], off offset:128 nt
	global_load_dwordx4 v[224:227], v[196:197], off offset:144 nt
	v_or_b32_e32 v132, 16, v216
	v_or_b32_e32 v134, 32, v216
	v_or_b32_e32 v136, 48, v216
	v_ashrrev_i32_e32 v133, 31, v132
	v_ashrrev_i32_e32 v135, 31, v134
	v_ashrrev_i32_e32 v137, 31, v136
	v_lshlrev_b64 v[132:133], 12, v[132:133]
	v_lshlrev_b64 v[134:135], 12, v[134:135]
	v_lshlrev_b64 v[136:137], 12, v[136:137]
	v_lshl_add_u64 v[132:133], v[130:131], 0, v[132:133]
	v_lshl_add_u64 v[134:135], v[130:131], 0, v[134:135]
	v_lshl_add_u64 v[136:137], v[130:131], 0, v[136:137]
	global_load_dwordx4 v[170:173], v[132:133], off offset:16 nt
	global_load_dwordx4 v[174:177], v[132:133], off nt
	global_load_dwordx4 v[162:165], v[132:133], off offset:144 nt
	global_load_dwordx4 v[166:169], v[132:133], off offset:128 nt
	global_load_dwordx4 v[154:157], v[134:135], off offset:16 nt
	global_load_dwordx4 v[158:161], v[134:135], off nt
	global_load_dwordx4 v[146:149], v[134:135], off offset:144 nt
	global_load_dwordx4 v[150:153], v[134:135], off offset:128 nt
	global_load_dwordx4 v[138:141], v[136:137], off offset:16 nt
	global_load_dwordx4 v[142:145], v[136:137], off nt
	global_load_dwordx4 v[130:133], v[136:137], off offset:144 nt
	s_nop 0
	global_load_dwordx4 v[134:137], v[136:137], off offset:128 nt
	v_and_b32_e32 v219, 64, v204
	v_xor_b32_e32 v207, 16, v204
	v_add_u32_e32 v219, 64, v219
	v_cmp_lt_i32_e32 vcc, v207, v219
	s_lshl_b32 s27, s48, 2
	s_or_b32 s50, s27, s58
	s_ashr_i32 s47, s46, 31
	s_ashr_i32 s51, s50, 31
	s_lshl_b64 s[46:47], s[46:47], 19
	s_lshl_b64 s[50:51], s[50:51], 15
	s_add_u32 s27, s62, s46
	s_addc_u32 s29, s63, s47
	s_add_u32 s27, s27, s50
	s_addc_u32 s29, s29, s51
	s_add_u32 s46, s27, s16
	s_addc_u32 s47, s29, s17
	s_waitcnt vmcnt(0)
	v_pk_add_f32 v[128:129], v[128:129], v[210:211]
	v_pk_add_f32 v[126:127], v[126:127], v[208:209]
	v_pk_add_f32 v[124:125], v[124:125], v[214:215]
	v_pk_add_f32 v[122:123], v[122:123], v[212:213]
	v_pk_add_f32 v[120:121], v[120:121], v[222:223]
	v_pk_add_f32 v[118:119], v[118:119], v[220:221]
	v_pk_add_f32 v[208:209], v[116:117], v[226:227]
	v_pk_add_f32 v[210:211], v[114:115], v[224:225]
	v_mul_f32_e32 v212, v127, v127
	v_mul_f32_e32 v213, v129, v129
	v_mul_f32_e32 v214, v123, v123
	v_mul_f32_e32 v215, v125, v125
	v_cvt_pk_bf16_f32 v114, v126, v127
	v_cvt_pk_bf16_f32 v115, v128, v129
	v_cvt_pk_bf16_f32 v116, v122, v123
	v_cvt_pk_bf16_f32 v117, v124, v125
	v_mul_f32_e32 v123, v119, v119
	v_mul_f32_e32 v125, v121, v121
	v_mul_f32_e32 v127, v211, v211
	v_mul_f32_e32 v129, v209, v209
	v_fmac_f32_e32 v212, v126, v126
	v_fmac_f32_e32 v213, v128, v128
	v_fmac_f32_e32 v214, v122, v122
	v_fmac_f32_e32 v215, v124, v124
	v_fmac_f32_e32 v123, v118, v118
	v_fmac_f32_e32 v125, v120, v120
	v_fmac_f32_e32 v127, v210, v210
	v_fmac_f32_e32 v129, v208, v208
	ds_write_b128 v205, v[114:117]
	v_cvt_pk_bf16_f32 v114, v118, v119
	v_cvt_pk_bf16_f32 v115, v120, v121
	v_add_f32_e32 v117, v212, v213
	v_add_f32_e32 v118, v214, v215
	v_add_f32_e32 v119, v123, v125
	v_add_f32_e32 v120, v127, v129
	v_add_f32_e32 v117, v117, v118
	v_add_f32_e32 v118, v119, v120
	v_add_f32_e32 v119, v117, v118
	v_cndmask_b32_e32 v117, v204, v207, vcc
	v_lshlrev_b32_e32 v118, 2, v117
	ds_bpermute_b32 v120, v118, v119
	v_cvt_pk_bf16_f32 v116, v210, v211
	v_cvt_pk_bf16_f32 v117, v208, v209
	ds_write_b128 v205, v[114:117] offset:64
	v_xor_b32_e32 v114, 32, v204
	v_cmp_lt_i32_e32 vcc, v114, v219
	s_waitcnt lgkmcnt(1)
	v_add_f32_e32 v120, v119, v120
	ds_read_b128 v[122:125], v206
	ds_read_b128 v[126:129], v206 offset:1152
	v_cndmask_b32_e32 v114, v204, v114, vcc
	v_lshlrev_b32_e32 v119, 2, v114
	ds_bpermute_b32 v121, v119, v120
	v_lshl_add_u64 v[116:117], s[46:47], 0, v[186:187]
	v_lshl_add_u64 v[114:115], v[216:217], 2, s[30:31]
	s_waitcnt lgkmcnt(2)
	global_store_dwordx4 v[116:117], v[122:125], off
	s_waitcnt lgkmcnt(1)
	global_store_dwordx4 v[116:117], v[126:129], off offset:1024
	s_and_saveexec_b64 s[46:47], s[6:7]
	s_cbranch_execz .LBB0_482
	s_waitcnt lgkmcnt(0)
	v_add_f32_e32 v120, v120, v121
	global_atomic_add_f32 v[114:115], v120, off

; __device__ __forceinline__ u32x4 pack8(const f32x4& v0, const f32x4& v1) { u32x4 w; w.x = cvt_pk_bf16(v0[0], v0[1]); w.y = cvt_pk_bf16(v0[2], v0[3]); w.z = cvt_pk_bf16(v1[0], v1[1]); w.w = cvt_pk_bf16(v1[2], v1[3]); return w; }
;     __device__ __forceinline__ void operator()(const f32x4 (&acc)[2][2][4][2], const Unit& u, int wr, int wc, int fr, int fq) const {
;     ...
;         for (int ai = 0; ai < 2; ++ai) {
;             f32x4 xv[4][2][2];
; #pragma unroll
;             for (int m = 0; m < 4; ++m) { const float* xp = x + (size_t)(row0 + ai * HALF + m * 16) * 1024 + col0;
; #pragma unroll
;                 for (int bj = 0; bj < 2; ++bj) { xv[m][bj][0] = *(const f32x4*)(xp + bj * 32); xv[m][bj][1] = *(const f32x4*)(xp + bj * 32 + 4); } }
;             asm volatile("" ::: "memory");
; #pragma unroll
;             for (int m = 0; m < 4; ++m) { const int row = row0 + ai * HALF + m * 16; float sq = 0.f;
; #pragma unroll
;                 for (int bj = 0; bj < 2; ++bj) { const f32x4 o0 = xv[m][bj][0] + acc[ai][bj][m][0], o1 = xv[m][bj][1] + acc[ai][bj][m][1];
;                     sq += ((o0[0] * o0[0] + o0[1] * o0[1]) + (o0[2] * o0[2] + o0[3] * o0[3])) + ((o1[0] * o1[0] + o1[1] * o1[1]) + (o1[2] * o1[2] + o1[3] * o1[3]));
;                     po.put(bj, pack8(o0, o1)); }
;                 po.flush<false>(ai, m);
;                 sq += __shfl_xor(sq, 16); sq += __shfl_xor(sq, 32);
;                 if (fq == 0) atomicAdd(ss + row, sq); }
.LBB0_488:
	s_or_b64 exec, exec, s[46:47]
	v_add_co_u32_e32 v68, vcc, 0x80000, v196
	s_waitcnt lgkmcnt(0)
	v_lshl_add_u64 v[66:67], v[196:197], 0, s[18:19]
	v_addc_co_u32_e32 v69, vcc, 0, v197, vcc
	global_load_dwordx4 v[120:123], v[66:67], off offset:16 nt
	global_load_dwordx4 v[124:127], v[66:67], off offset:128 nt
	global_load_dwordx4 v[128:131], v[68:69], off nt
	global_load_dwordx4 v[132:135], v[66:67], off offset:144 nt
	v_add_co_u32_e32 v78, vcc, 0x90000, v196
	v_lshl_add_u64 v[70:71], v[196:197], 0, s[20:21]
	s_nop 0
	v_addc_co_u32_e32 v79, vcc, 0, v197, vcc
	v_lshl_add_u64 v[72:73], v[196:197], 0, s[22:23]
	v_lshl_add_u64 v[136:137], v[196:197], 0, s[24:25]
	global_load_dwordx4 v[106:109], v[70:71], off offset:16 nt
	global_load_dwordx4 v[98:101], v[70:71], off offset:128 nt
	global_load_dwordx4 v[90:93], v[72:73], off offset:16 nt
	global_load_dwordx4 v[82:85], v[72:73], off offset:128 nt
	global_load_dwordx4 v[74:77], v[136:137], off offset:16 nt
	global_load_dwordx4 v[66:69], v[136:137], off offset:128 nt
	v_add_co_u32_e32 v80, vcc, 0xa0000, v196
	global_load_dwordx4 v[110:113], v[78:79], off nt
	global_load_dwordx4 v[102:105], v[70:71], off offset:144 nt
	v_addc_co_u32_e32 v81, vcc, 0, v197, vcc
	v_add_co_u32_e32 v70, vcc, 0xb0000, v196
	global_load_dwordx4 v[94:97], v[80:81], off nt
	global_load_dwordx4 v[86:89], v[72:73], off offset:144 nt
	v_addc_co_u32_e32 v71, vcc, 0, v197, vcc
	global_load_dwordx4 v[78:81], v[70:71], off nt
	s_nop 0
	global_load_dwordx4 v[70:73], v[136:137], off offset:144 nt
	v_add_co_u32_e32 v136, vcc, 0x4000, v116
	s_waitcnt vmcnt(15)
	v_pk_add_f32 v[58:59], v[58:59], v[120:121]
	v_pk_add_f32 v[60:61], v[60:61], v[122:123]
	s_waitcnt vmcnt(14)
	v_pk_add_f32 v[56:57], v[56:57], v[126:127]
	v_pk_add_f32 v[54:55], v[54:55], v[124:125]
	s_waitcnt vmcnt(13)
	v_pk_add_f32 v[64:65], v[64:65], v[130:131]
	v_pk_add_f32 v[62:63], v[62:63], v[128:129]
	v_mul_f32_e32 v124, v59, v59
	s_waitcnt vmcnt(12)
	v_pk_add_f32 v[120:121], v[52:53], v[134:135]
	v_pk_add_f32 v[122:123], v[50:51], v[132:133]
	v_mul_f32_e32 v125, v61, v61
	v_mul_f32_e32 v126, v55, v55
	v_mul_f32_e32 v127, v57, v57
	v_mul_f32_e32 v128, v63, v63
	v_mul_f32_e32 v129, v65, v65
	v_fmac_f32_e32 v124, v58, v58
	v_cvt_pk_bf16_f32 v50, v62, v63
	v_cvt_pk_bf16_f32 v51, v64, v65
	v_cvt_pk_bf16_f32 v52, v58, v59
	v_mul_f32_e32 v58, v123, v123
	v_mul_f32_e32 v59, v121, v121
	v_fmac_f32_e32 v125, v60, v60
	v_cvt_pk_bf16_f32 v53, v60, v61
	v_fmac_f32_e32 v126, v54, v54
	v_fmac_f32_e32 v127, v56, v56
	v_fmac_f32_e32 v128, v62, v62
	v_fmac_f32_e32 v129, v64, v64
	v_fmac_f32_e32 v58, v122, v122
	v_fmac_f32_e32 v59, v120, v120
	v_add_f32_e32 v60, v124, v125
	ds_write_b128 v205, v[50:53]
	v_add_f32_e32 v53, v126, v127
	v_cvt_pk_bf16_f32 v50, v54, v55
	v_add_f32_e32 v54, v128, v129
	v_add_f32_e32 v55, v58, v59
	v_add_f32_e32 v54, v54, v60
	v_add_f32_e32 v53, v53, v55
	v_add_f32_e32 v60, v54, v53
	ds_bpermute_b32 v61, v118, v60
	v_cvt_pk_bf16_f32 v51, v56, v57
	v_cvt_pk_bf16_f32 v52, v122, v123
	v_cvt_pk_bf16_f32 v53, v120, v121
	ds_write_b128 v205, v[50:53] offset:64
	s_waitcnt lgkmcnt(1)
	v_add_f32_e32 v50, v60, v61
	ds_read_b128 v[52:55], v206
	ds_read_b128 v[56:59], v206 offset:1152
	ds_bpermute_b32 v51, v119, v50
	v_addc_co_u32_e32 v137, vcc, 0, v117, vcc
	s_waitcnt lgkmcnt(2)
	global_store_dwordx4 v[136:137], v[52:55], off
	s_waitcnt lgkmcnt(1)
	global_store_dwordx4 v[136:137], v[56:59], off offset:1024
	s_and_saveexec_b64 s[46:47], s[6:7]
	s_cbranch_execz .LBB0_490
	s_waitcnt lgkmcnt(0)
	v_add_f32_e32 v50, v50, v51
	global_atomic_add_f32 v[114:115], v50, off offset:512

; __device__ __forceinline__ size_t tm_block(int pm, int ct, int nct) { return ((size_t)pm * nct + ct) * 32768; }
; #define UNPK0(q_) ((f32x4){bf_lo((q_).x), bf_hi((q_).x), bf_lo((q_).y), bf_hi((q_).y)})
; #define UNPK1(q_) ((f32x4){bf_lo((q_).z), bf_hi((q_).z), bf_lo((q_).w), bf_hi((q_).w)})
;     __device__ __forceinline__ void operator()(f32x4 (&acc)[2][2][4][2], const Unit& u, int wr, int wc, int fr, int fq) const {
;         const int lane = fq * 16 + fr, row0 = u.pm * BM + wr * 64 + fr;
;         const PieceIn pi(scr, X1, tm_block(u.pm, u.pn * 4 + wc, 16), wr, wc, fr, fq);
;         u32x4 rx[2][4][2];
; #pragma unroll
;         for (int ai = 0; ai < 2; ++ai)
; #pragma unroll
;             for (int m = 0; m < 4; ++m) pi.fetch(ai, m, rx[ai][m][0], rx[ai][m][1]);
;         asm volatile("" ::: "memory");
; #pragma unroll
;         for (int ai = 0; ai < 2; ++ai)
; #pragma unroll
;             for (int m = 0; m < 4; ++m) { const int row = row0 + ai * HALF + m * 16; float sq = 0.f;
;                 pi.stage(rx[ai][m][0], rx[ai][m][1]); const u32x4 x0 = pi.get(0), x1 = pi.get(1);
;                 asm volatile("" ::: "memory");
; #pragma unroll
;                 for (int bj = 0; bj < 2; ++bj) { const u32x4 z4 = bj ? x1 : x0;
;                     const f32x4 o0 = UNPK0(z4) + acc[ai][bj][m][0], o1 = UNPK1(z4) + acc[ai][bj][m][1];
;                     acc[ai][bj][m][0] = o0; acc[ai][bj][m][1] = o1;
;                     sq += ((o0[0] * o0[0] + o0[1] * o0[1]) + (o0[2] * o0[2] + o0[3] * o0[3])) + ((o1[0] * o1[0] + o1[1] * o1[1]) + (o1[2] * o1[2] + o1[3] * o1[3])); }
;                 sq += __shfl_xor(sq, 16); sq += __shfl_xor(sq, 32);
;                 if (fq == 0) atomicAdd(ss + row, sq); }
.LBB0_729:
	s_lshl_b32 s29, s46, 2
	s_or_b32 s50, s29, s58
	s_lshl_b32 s27, s48, 8
	s_ashr_i32 s49, s48, 31
	s_ashr_i32 s51, s50, 31
	s_add_i32 s27, s27, s18
	s_lshl_b32 s40, s27, 2
	s_add_u32 s40, s12, s40
	s_addc_u32 s41, s13, 0
	s_sub_u32 s40, s40, 0x40000
	s_subb_u32 s41, s41, 0
	s_lshl_b64 s[52:53], s[48:49], 19
	s_lshl_b64 s[50:51], s[50:51], 15
	s_add_u32 s29, s62, s52
	s_addc_u32 s37, s63, s53
	s_add_u32 s29, s29, s50
	s_addc_u32 s37, s37, s51
	s_add_u32 s50, s29, s22
	s_addc_u32 s51, s37, s23
	v_lshl_add_u64 v[130:131], s[50:51], 0, v[196:197]
	global_load_dwordx4 v[224:227], v[130:131], off nt
	global_load_dwordx4 v[228:231], v[130:131], off offset:1024 nt
	v_add_co_u32_e32 v132, vcc, s76, v130
	s_movk_i32 s29, 0x4000
	s_nop 0
	v_addc_co_u32_e32 v133, vcc, 0, v131, vcc
	v_add_co_u32_e32 v134, vcc, s29, v130
	global_load_dwordx4 v[178:181], v[130:131], off offset:2048 nt
	global_load_dwordx4 v[182:185], v[130:131], off offset:3072 nt
	v_addc_co_u32_e32 v135, vcc, 0, v131, vcc
	v_add_co_u32_e32 v136, vcc, s77, v130
	v_add_u32_e32 v223, v216, v213
	s_nop 0
	v_addc_co_u32_e32 v137, vcc, 0, v131, vcc
	global_load_dwordx4 v[170:173], v[132:133], off nt
	global_load_dwordx4 v[174:177], v[132:133], off offset:1024 nt
	global_load_dwordx4 v[162:165], v[132:133], off offset:2048 nt
	global_load_dwordx4 v[166:169], v[132:133], off offset:3072 nt
	global_load_dwordx4 v[154:157], v[134:135], off offset:1024 nt
	global_load_dwordx4 v[146:149], v[134:135], off offset:2048 nt
	global_load_dwordx4 v[158:161], v[136:137], off offset:-4096 nt
	global_load_dwordx4 v[150:153], v[134:135], off offset:3072 nt
	global_load_dwordx4 v[138:141], v[136:137], off nt
	global_load_dwordx4 v[142:145], v[136:137], off offset:1024 nt
	global_load_dwordx4 v[130:133], v[136:137], off offset:2048 nt
	s_nop 0
	global_load_dwordx4 v[134:137], v[136:137], off offset:3072 nt
	v_and_b32_e32 v207, 64, v217
	v_xor_b32_e32 v206, 16, v217
	v_add_u32_e32 v240, 64, v207
	v_cmp_lt_i32_e32 vcc, v206, v240
	v_lshlrev_b32_e32 v241, 2, v208
	global_load_dword v241, v241, s[40:41] offset:0
	v_lshlrev_b32_e32 v242, 2, v208
	global_load_dword v242, v242, s[40:41] offset:64
	v_lshlrev_b32_e32 v243, 2, v208
	global_load_dword v243, v243, s[40:41] offset:128
	v_lshlrev_b32_e32 v244, 2, v208
	global_load_dword v244, v244, s[40:41] offset:192
	v_lshlrev_b32_e32 v245, 2, v208
	global_load_dword v245, v245, s[40:41] offset:512
	v_lshlrev_b32_e32 v247, 2, v208
	global_load_dword v247, v247, s[40:41] offset:576
	s_waitcnt vmcnt(0)
	v_fmamk_f32 v241, v241, 0x3a800000, v219
	v_rcp_f32_e32 v241, v241
	v_fmamk_f32 v242, v242, 0x3a800000, v219
	v_rcp_f32_e32 v242, v242
	v_fmamk_f32 v243, v243, 0x3a800000, v219
	v_rcp_f32_e32 v243, v243
	v_fmamk_f32 v244, v244, 0x3a800000, v219
	v_rcp_f32_e32 v244, v244
	v_fmamk_f32 v245, v245, 0x3a800000, v219
	v_rcp_f32_e32 v245, v245
	v_fmamk_f32 v247, v247, 0x3a800000, v219
	v_rcp_f32_e32 v247, v247
	ds_write_b128 v222, v[224:227]
	ds_write_b128 v222, v[228:231] offset:1152
	ds_read_b128 v[226:229], v223
	ds_read_b128 v[230:233], v223 offset:64
	v_cndmask_b32_e32 v206, v217, v206, vcc
	v_lshlrev_b32_e32 v224, 2, v206
	s_waitcnt lgkmcnt(1)
	v_lshlrev_b32_e32 v206, 16, v226
	v_and_b32_e32 v207, 0xffff0000, v226
	v_lshlrev_b32_e32 v226, 16, v227
	v_and_b32_e32 v227, 0xffff0000, v227
	v_lshlrev_b32_e32 v234, 16, v228
	v_and_b32_e32 v235, 0xffff0000, v228
	v_lshlrev_b32_e32 v228, 16, v229
	v_and_b32_e32 v229, 0xffff0000, v229
	s_waitcnt lgkmcnt(0)
	v_lshlrev_b32_e32 v236, 16, v230
	v_and_b32_e32 v237, 0xffff0000, v230
	v_lshlrev_b32_e32 v230, 16, v231
	v_and_b32_e32 v231, 0xffff0000, v231
	v_lshlrev_b32_e32 v238, 16, v232
	v_and_b32_e32 v239, 0xffff0000, v232
	v_lshlrev_b32_e32 v232, 16, v233
	v_and_b32_e32 v233, 0xffff0000, v233
	v_fma_f32 v128, v128, v241, v226
	v_fma_f32 v129, v129, v241, v227
	v_fma_f32 v126, v126, v241, v206
	v_fma_f32 v127, v127, v241, v207
	v_fma_f32 v124, v124, v241, v228
	v_fma_f32 v125, v125, v241, v229
	v_fma_f32 v122, v122, v241, v234
	v_fma_f32 v123, v123, v241, v235
	v_fma_f32 v120, v120, v241, v230
	v_fma_f32 v121, v121, v241, v231
	v_fma_f32 v118, v118, v241, v236
	v_fma_f32 v119, v119, v241, v237
	v_fma_f32 v116, v116, v241, v232
	v_fma_f32 v117, v117, v241, v233
	v_fma_f32 v114, v114, v241, v238
	v_fma_f32 v115, v115, v241, v239
	v_mul_f32_e32 v206, v127, v127
	v_mul_f32_e32 v207, v129, v129
	v_mul_f32_e32 v225, v123, v123
	v_mul_f32_e32 v226, v125, v125
	v_mul_f32_e32 v227, v119, v119
	v_mul_f32_e32 v228, v121, v121
	v_mul_f32_e32 v229, v115, v115
	v_mul_f32_e32 v230, v117, v117
	v_fmac_f32_e32 v206, v126, v126
	v_fmac_f32_e32 v207, v128, v128
	v_fmac_f32_e32 v225, v122, v122
	v_fmac_f32_e32 v226, v124, v124
	v_fmac_f32_e32 v227, v118, v118
	v_fmac_f32_e32 v228, v120, v120
	v_fmac_f32_e32 v229, v114, v114
	v_fmac_f32_e32 v230, v116, v116
	v_add_f32_e32 v206, v206, v207
	v_add_f32_e32 v207, v225, v226
	v_add_f32_e32 v225, v227, v228
	v_add_f32_e32 v226, v229, v230
	v_add_f32_e32 v206, v206, v207
	v_add_f32_e32 v207, v225, v226
	v_add_f32_e32 v207, v206, v207
	ds_bpermute_b32 v225, v224, v207
	v_xor_b32_e32 v226, 32, v217
	v_cmp_lt_i32_e32 vcc, v226, v240
	v_or_b32_e32 v206, s27, v208
	s_nop 0
	v_cndmask_b32_e32 v227, v217, v226, vcc
	s_waitcnt lgkmcnt(0)
	v_add_f32_e32 v226, v207, v225
	v_lshlrev_b32_e32 v225, 2, v227
	ds_bpermute_b32 v227, v225, v226
	v_ashrrev_i32_e32 v207, 31, v206
	s_and_saveexec_b64 s[50:51], s[8:9]
	s_cbranch_execz .LBB0_731
	v_lshl_add_u64 v[228:229], v[206:207], 2, s[12:13]
	s_waitcnt lgkmcnt(0)
	v_add_f32_e32 v226, v226, v227
	global_atomic_add_f32 v[228:229], v226, off
